# FFN2-out and gated-branch GEMM epilogues: residual / gate / partial-sum loads issued 6-8 loads ahead into a ring of free registers, counted vmcnt waits instead of drain-per-chunk
# baseline (speedup 1.0000x reference)
; __device__ __forceinline__ unsigned cvt_pk_bf16(float lo, float hi) { f32x2_cv v = {lo, hi}; bf16x2_cv b = __builtin_convertvector(v, bf16x2_cv); return __builtin_bit_cast(unsigned, b); }
; __device__ __forceinline__ float fast_sigmoid(float x) { return __builtin_amdgcn_rcpf(1.0f + __expf(-x)); }
; __device__ __forceinline__ float bf_lo(unsigned w) { return __uint_as_float(w << 16); }
; __device__ __forceinline__ float bf_hi(unsigned w) { return __uint_as_float(w & 0xffff0000u); }
;     __device__ __forceinline__ void operator()(const f32x4 (&acc)[2][2][4][2], const Unit& u, int wr, int wc, int fr, int fq) const {
;     ...
;                 int rowi = lrow0 + ai * HALF + m * 16; asm volatile("" : "+v"(rowi)); const size_t row = (size_t)rowi;
; #pragma unroll
;                 for (int bj = 0; bj < 2; ++bj) {
;                     const u32x4 gw = *(const u32x4*)(GG + row * 2048 + goff + col0 + bj * HALF);
;                     f32x4 v0, v1;
;                     v0[0] = fast_sigmoid(bf_lo(gw.x)) * acc[ai][bj][m][0][0]; v0[1] = fast_sigmoid(bf_hi(gw.x)) * acc[ai][bj][m][0][1];
;                     v0[2] = fast_sigmoid(bf_lo(gw.y)) * acc[ai][bj][m][0][2]; v0[3] = fast_sigmoid(bf_hi(gw.y)) * acc[ai][bj][m][0][3];
;                     v1[0] = fast_sigmoid(bf_lo(gw.z)) * acc[ai][bj][m][1][0]; v1[1] = fast_sigmoid(bf_hi(gw.z)) * acc[ai][bj][m][1][1];
;                     v1[2] = fast_sigmoid(bf_lo(gw.w)) * acc[ai][bj][m][1][2]; v1[3] = fast_sigmoid(bf_hi(gw.w)) * acc[ai][bj][m][1][3];
;                     bf16_t* tp = TMP + row * 1024 + col0 + bj * HALF;
;                     if (MODE == 1) { const u32x4 tw = *(const u32x4*)tp;
;                         v0 += (f32x4){bf_lo(tw.x), bf_hi(tw.x), bf_lo(tw.y), bf_hi(tw.y)}; v1 += (f32x4){bf_lo(tw.z), bf_hi(tw.z), bf_lo(tw.w), bf_hi(tw.w)}; }
;                     u32x4 w; w.x = cvt_pk_bf16(v0[0], v0[1]); w.y = cvt_pk_bf16(v0[2], v0[3]); w.z = cvt_pk_bf16(v1[0], v1[1]); w.w = cvt_pk_bf16(v1[2], v1[3]);
;                     *(u32x4*)((MODE == 0 ? tp : MIX + row * 1024 + col0 + bj * HALF)) = w;
.LBB0_767:
	v_lshl_add_u32 v156, s47, 8, v152
	v_mov_b32_e32 v150, v156
	v_lshl_or_b32 v148, s2, 8, v154
	v_ashrrev_i32_e32 v149, 31, v148
	v_ashrrev_i32_e32 v151, 31, v150
	v_lshlrev_b64 v[158:159], 12, v[150:151]
	v_lshlrev_b64 v[162:163], 11, v[150:151]
	v_lshl_add_u64 v[150:151], s[16:17], 0, v[158:159]
	v_lshlrev_b64 v[148:149], 1, v[148:149]
	v_lshl_add_u64 v[150:151], v[150:151], 0, v[148:149]
	global_load_dwordx4 v[210:213], v[150:151], off
	global_load_dwordx4 v[214:217], v[150:151], off offset:256
	v_or_b32_e32 v166, 16, v156
	v_ashrrev_i32_e32 v167, 31, v166
	v_lshlrev_b64 v[168:169], 12, v[166:167]
	v_lshl_add_u64 v[166:167], s[16:17], 0, v[168:169]
	v_lshl_add_u64 v[166:167], v[166:167], 0, v[148:149]
	global_load_dwordx4 v[218:221], v[166:167], off
	v_or_b32_e32 v166, 16, v156
	v_ashrrev_i32_e32 v167, 31, v166
	v_lshlrev_b64 v[168:169], 12, v[166:167]
	v_lshl_add_u64 v[166:167], s[16:17], 0, v[168:169]
	v_lshl_add_u64 v[166:167], v[166:167], 0, v[148:149]
	global_load_dwordx4 v[222:225], v[166:167], off offset:256
	v_or_b32_e32 v166, 32, v156
	v_ashrrev_i32_e32 v167, 31, v166
	v_lshlrev_b64 v[168:169], 12, v[166:167]
	v_lshl_add_u64 v[166:167], s[16:17], 0, v[168:169]
	v_lshl_add_u64 v[166:167], v[166:167], 0, v[148:149]
	global_load_dwordx4 v[226:229], v[166:167], off
	v_or_b32_e32 v166, 32, v156
	v_ashrrev_i32_e32 v167, 31, v166
	v_lshlrev_b64 v[168:169], 12, v[166:167]
	v_lshl_add_u64 v[166:167], s[16:17], 0, v[168:169]
	v_lshl_add_u64 v[166:167], v[166:167], 0, v[148:149]
	global_load_dwordx4 v[230:233], v[166:167], off offset:256
	v_or_b32_e32 v166, 48, v156
	v_ashrrev_i32_e32 v167, 31, v166
	v_lshlrev_b64 v[168:169], 12, v[166:167]
	v_lshl_add_u64 v[166:167], s[16:17], 0, v[168:169]
	v_lshl_add_u64 v[166:167], v[166:167], 0, v[148:149]
	global_load_dwordx4 v[182:185], v[166:167], off
	v_or_b32_e32 v166, 48, v156
	v_ashrrev_i32_e32 v167, 31, v166
	v_lshlrev_b64 v[168:169], 12, v[166:167]
	v_lshl_add_u64 v[166:167], s[16:17], 0, v[168:169]
	v_lshl_add_u64 v[166:167], v[166:167], 0, v[148:149]
	global_load_dwordx4 v[186:189], v[166:167], off offset:256
	s_mov_b64 s[4:5], -1
	s_andn2_b64 vcc, exec, s[10:11]
	s_waitcnt vmcnt(7)
	v_lshlrev_b32_e32 v157, 16, v210
	v_mul_f32_e32 v157, 0xbfb8aa3b, v157
	v_exp_f32_e32 v157, v157
	s_nop 0
	v_add_f32_e32 v157, 1.0, v157
	v_rcp_f32_e32 v164, v157
	v_and_b32_e32 v157, 0xffff0000, v210
	v_mul_f32_e32 v157, 0xbfb8aa3b, v157
	v_exp_f32_e32 v157, v157
	s_nop 0
	v_add_f32_e32 v157, 1.0, v157
	v_rcp_f32_e32 v165, v157
	v_lshlrev_b32_e32 v157, 16, v211
	v_mul_f32_e32 v157, 0xbfb8aa3b, v157
	v_exp_f32_e32 v157, v157
	v_pk_mul_f32 v[128:129], v[128:129], v[164:165]
	v_add_f32_e32 v157, 1.0, v157
	v_rcp_f32_e32 v158, v157
	v_and_b32_e32 v157, 0xffff0000, v211
	v_mul_f32_e32 v157, 0xbfb8aa3b, v157
	v_exp_f32_e32 v157, v157
	s_nop 0
	v_add_f32_e32 v157, 1.0, v157
	v_rcp_f32_e32 v159, v157
	v_lshlrev_b32_e32 v157, 16, v212
	v_mul_f32_e32 v157, 0xbfb8aa3b, v157
	v_exp_f32_e32 v157, v157
	v_pk_mul_f32 v[130:131], v[130:131], v[158:159]
	v_add_f32_e32 v157, 1.0, v157
	v_rcp_f32_e32 v158, v157
	v_and_b32_e32 v157, 0xffff0000, v212
	v_mul_f32_e32 v157, 0xbfb8aa3b, v157
	v_exp_f32_e32 v157, v157
	s_nop 0
	v_add_f32_e32 v157, 1.0, v157
	v_rcp_f32_e32 v159, v157
	s_nop 0
	v_pk_mul_f32 v[158:159], v[124:125], v[158:159]
	v_lshlrev_b32_e32 v124, 16, v213
	v_and_b32_e32 v125, 0xffff0000, v213
	v_add_u32_e32 v166, 0x80, v156
	v_ashrrev_i32_e32 v167, 31, v166
	v_lshlrev_b64 v[168:169], 12, v[166:167]
	v_lshl_add_u64 v[166:167], s[16:17], 0, v[168:169]
	v_lshl_add_u64 v[166:167], v[166:167], 0, v[148:149]
	global_load_dwordx4 v[210:213], v[166:167], off
	v_mul_f32_e32 v124, 0xbfb8aa3b, v124
	v_mul_f32_e32 v125, 0xbfb8aa3b, v125
	v_exp_f32_e32 v124, v124
	v_exp_f32_e32 v125, v125
	v_add_f32_e32 v124, 1.0, v124
	v_add_f32_e32 v125, 1.0, v125
	v_rcp_f32_e32 v124, v124
	v_rcp_f32_e32 v125, v125
	s_nop 0
	v_pk_mul_f32 v[160:161], v[126:127], v[124:125]
	v_lshl_add_u64 v[124:125], s[18:19], 0, v[162:163]
	v_lshl_add_u64 v[124:125], v[124:125], 0, v[148:149]
	v_cvt_pk_bf16_f32 v126, v128, v129
	v_cvt_pk_bf16_f32 v127, v130, v131
	v_cvt_pk_bf16_f32 v128, v158, v159
	v_cvt_pk_bf16_f32 v129, v160, v161
	global_store_dwordx4 v[124:125], v[126:129], off
	s_waitcnt vmcnt(8)
	v_lshlrev_b32_e32 v130, 16, v214
	v_and_b32_e32 v126, 0xffff0000, v214
	v_mul_f32_e32 v126, 0xbfb8aa3b, v126
	v_exp_f32_e32 v126, v126
	v_mul_f32_e32 v130, 0xbfb8aa3b, v130
	v_exp_f32_e32 v130, v130
	v_add_f32_e32 v126, 1.0, v126
	v_rcp_f32_e32 v131, v126
	v_lshlrev_b32_e32 v126, 16, v215
	v_and_b32_e32 v127, 0xffff0000, v215
	v_mul_f32_e32 v126, 0xbfb8aa3b, v126
	v_mul_f32_e32 v127, 0xbfb8aa3b, v127
	v_exp_f32_e32 v126, v126
	v_exp_f32_e32 v127, v127
	v_add_f32_e32 v130, 1.0, v130
	v_rcp_f32_e32 v130, v130
	v_add_f32_e32 v126, 1.0, v126
	v_add_f32_e32 v127, 1.0, v127
	v_rcp_f32_e32 v126, v126
	v_rcp_f32_e32 v127, v127
	v_pk_mul_f32 v[120:121], v[120:121], v[130:131]
	v_pk_mul_f32 v[122:123], v[122:123], v[126:127]
	v_lshlrev_b32_e32 v126, 16, v216
	v_and_b32_e32 v127, 0xffff0000, v216
	v_mul_f32_e32 v126, 0xbfb8aa3b, v126
	v_mul_f32_e32 v127, 0xbfb8aa3b, v127
	v_exp_f32_e32 v126, v126
	v_exp_f32_e32 v127, v127
	v_add_f32_e32 v126, 1.0, v126
	v_add_f32_e32 v127, 1.0, v127
	v_rcp_f32_e32 v126, v126
	v_rcp_f32_e32 v127, v127
	s_nop 0
	v_pk_mul_f32 v[116:117], v[116:117], v[126:127]
	v_lshlrev_b32_e32 v126, 16, v217
	v_and_b32_e32 v127, 0xffff0000, v217
	v_add_u32_e32 v166, 0x80, v156
	v_ashrrev_i32_e32 v167, 31, v166
	v_lshlrev_b64 v[168:169], 12, v[166:167]
	v_lshl_add_u64 v[166:167], s[16:17], 0, v[168:169]
	v_lshl_add_u64 v[166:167], v[166:167], 0, v[148:149]
	global_load_dwordx4 v[214:217], v[166:167], off offset:256
	v_mul_f32_e32 v126, 0xbfb8aa3b, v126
	v_mul_f32_e32 v127, 0xbfb8aa3b, v127
	v_exp_f32_e32 v126, v126
	v_exp_f32_e32 v127, v127
	v_add_f32_e32 v126, 1.0, v126
	v_add_f32_e32 v127, 1.0, v127
	v_rcp_f32_e32 v126, v126
	v_rcp_f32_e32 v127, v127
	s_nop 0
	v_pk_mul_f32 v[126:127], v[118:119], v[126:127]
	v_cvt_pk_bf16_f32 v118, v120, v121
	v_cvt_pk_bf16_f32 v119, v122, v123
	v_cvt_pk_bf16_f32 v120, v116, v117
	v_cvt_pk_bf16_f32 v121, v126, v127
	v_or_b32_e32 v116, 16, v156
	global_store_dwordx4 v[124:125], v[118:121], off offset:256
	s_nop 0
	v_ashrrev_i32_e32 v117, 31, v116
	v_lshlrev_b64 v[118:119], 12, v[116:117]
	v_lshlrev_b64 v[122:123], 11, v[116:117]
	v_lshl_add_u64 v[116:117], s[16:17], 0, v[118:119]
	v_lshl_add_u64 v[116:117], v[116:117], 0, v[148:149]
	s_waitcnt vmcnt(9)
; __device__ __forceinline__ unsigned cvt_pk_bf16(float lo, float hi) { f32x2_cv v = {lo, hi}; bf16x2_cv b = __builtin_convertvector(v, bf16x2_cv); return __builtin_bit_cast(unsigned, b); }
; __device__ __forceinline__ float fast_sigmoid(float x) { return __builtin_amdgcn_rcpf(1.0f + __expf(-x)); }
; __device__ __forceinline__ float bf_lo(unsigned w) { return __uint_as_float(w << 16); }
; __device__ __forceinline__ float bf_hi(unsigned w) { return __uint_as_float(w & 0xffff0000u); }
;     __device__ __forceinline__ void operator()(const f32x4 (&acc)[2][2][4][2], const Unit& u, int wr, int wc, int fr, int fq) const {
;     ...
;                 for (int bj = 0; bj < 2; ++bj) {
;                     const u32x4 gw = *(const u32x4*)(GG + row * 2048 + goff + col0 + bj * HALF);
;                     f32x4 v0, v1;
;                     v0[0] = fast_sigmoid(bf_lo(gw.x)) * acc[ai][bj][m][0][0]; v0[1] = fast_sigmoid(bf_hi(gw.x)) * acc[ai][bj][m][0][1];
;                     v0[2] = fast_sigmoid(bf_lo(gw.y)) * acc[ai][bj][m][0][2]; v0[3] = fast_sigmoid(bf_hi(gw.y)) * acc[ai][bj][m][0][3];
;                     v1[0] = fast_sigmoid(bf_lo(gw.z)) * acc[ai][bj][m][1][0]; v1[1] = fast_sigmoid(bf_hi(gw.z)) * acc[ai][bj][m][1][1];
;                     v1[2] = fast_sigmoid(bf_lo(gw.w)) * acc[ai][bj][m][1][2]; v1[3] = fast_sigmoid(bf_hi(gw.w)) * acc[ai][bj][m][1][3];
;                     bf16_t* tp = TMP + row * 1024 + col0 + bj * HALF;
;                     if (MODE == 1) { const u32x4 tw = *(const u32x4*)tp;
;                         v0 += (f32x4){bf_lo(tw.x), bf_hi(tw.x), bf_lo(tw.y), bf_hi(tw.y)}; v1 += (f32x4){bf_lo(tw.z), bf_hi(tw.z), bf_lo(tw.w), bf_hi(tw.w)}; }
;                     u32x4 w; w.x = cvt_pk_bf16(v0[0], v0[1]); w.y = cvt_pk_bf16(v0[2], v0[3]); w.z = cvt_pk_bf16(v1[0], v1[1]); w.w = cvt_pk_bf16(v1[2], v1[3]);
;                     *(u32x4*)((MODE == 0 ? tp : MIX + row * 1024 + col0 + bj * HALF)) = w;
	v_lshlrev_b32_e32 v124, 16, v218
	v_and_b32_e32 v118, 0xffff0000, v218
	v_mul_f32_e32 v124, 0xbfb8aa3b, v124
	v_mul_f32_e32 v118, 0xbfb8aa3b, v118
	v_exp_f32_e32 v124, v124
	v_exp_f32_e32 v118, v118
	v_add_f32_e32 v124, 1.0, v124
	v_add_f32_e32 v118, 1.0, v118
	v_rcp_f32_e32 v124, v124
	v_rcp_f32_e32 v125, v118
	s_nop 0
	v_pk_mul_f32 v[124:125], v[112:113], v[124:125]
	v_lshlrev_b32_e32 v112, 16, v219
	v_and_b32_e32 v113, 0xffff0000, v219
	v_mul_f32_e32 v112, 0xbfb8aa3b, v112
	v_mul_f32_e32 v113, 0xbfb8aa3b, v113
	v_exp_f32_e32 v112, v112
	v_exp_f32_e32 v113, v113
	v_add_f32_e32 v112, 1.0, v112
	v_add_f32_e32 v113, 1.0, v113
	v_rcp_f32_e32 v112, v112
	v_rcp_f32_e32 v113, v113
	s_nop 0
	v_pk_mul_f32 v[114:115], v[114:115], v[112:113]
	v_lshlrev_b32_e32 v112, 16, v220
	v_and_b32_e32 v113, 0xffff0000, v220
	v_mul_f32_e32 v112, 0xbfb8aa3b, v112
	v_mul_f32_e32 v113, 0xbfb8aa3b, v113
	v_exp_f32_e32 v112, v112
	v_exp_f32_e32 v113, v113
	v_add_f32_e32 v112, 1.0, v112
	v_add_f32_e32 v113, 1.0, v113
	v_rcp_f32_e32 v112, v112
	v_rcp_f32_e32 v113, v113
	s_nop 0
	v_pk_mul_f32 v[118:119], v[108:109], v[112:113]
	v_lshlrev_b32_e32 v108, 16, v221
	v_and_b32_e32 v109, 0xffff0000, v221
	v_add_u32_e32 v166, 0x90, v156
	v_ashrrev_i32_e32 v167, 31, v166
	v_lshlrev_b64 v[168:169], 12, v[166:167]
	v_lshl_add_u64 v[166:167], s[16:17], 0, v[168:169]
	v_lshl_add_u64 v[166:167], v[166:167], 0, v[148:149]
	global_load_dwordx4 v[218:221], v[166:167], off
	v_mul_f32_e32 v108, 0xbfb8aa3b, v108
	v_mul_f32_e32 v109, 0xbfb8aa3b, v109
	v_exp_f32_e32 v108, v108
	v_exp_f32_e32 v109, v109
	v_add_f32_e32 v108, 1.0, v108
	v_add_f32_e32 v109, 1.0, v109
	v_rcp_f32_e32 v108, v108
	v_rcp_f32_e32 v109, v109
	s_nop 0
	v_pk_mul_f32 v[120:121], v[110:111], v[108:109]
	v_lshl_add_u64 v[108:109], s[18:19], 0, v[122:123]
	v_lshl_add_u64 v[112:113], v[108:109], 0, v[148:149]
	v_cvt_pk_bf16_f32 v108, v124, v125
	v_cvt_pk_bf16_f32 v109, v114, v115
	v_cvt_pk_bf16_f32 v110, v118, v119
	v_cvt_pk_bf16_f32 v111, v120, v121
	global_store_dwordx4 v[112:113], v[108:111], off
	s_waitcnt vmcnt(10)
	v_lshlrev_b32_e32 v114, 16, v222
	v_and_b32_e32 v108, 0xffff0000, v222
	v_mul_f32_e32 v108, 0xbfb8aa3b, v108
	v_exp_f32_e32 v108, v108
	v_mul_f32_e32 v114, 0xbfb8aa3b, v114
	v_exp_f32_e32 v114, v114
	v_add_f32_e32 v108, 1.0, v108
	v_rcp_f32_e32 v115, v108
	v_lshlrev_b32_e32 v108, 16, v223
	v_and_b32_e32 v109, 0xffff0000, v223
	v_mul_f32_e32 v108, 0xbfb8aa3b, v108
	v_mul_f32_e32 v109, 0xbfb8aa3b, v109
	v_exp_f32_e32 v108, v108
	v_exp_f32_e32 v109, v109
	v_add_f32_e32 v114, 1.0, v114
	v_rcp_f32_e32 v114, v114
	v_add_f32_e32 v108, 1.0, v108
	v_add_f32_e32 v109, 1.0, v109
	v_rcp_f32_e32 v108, v108
	v_rcp_f32_e32 v109, v109
	v_pk_mul_f32 v[104:105], v[104:105], v[114:115]
	v_pk_mul_f32 v[106:107], v[106:107], v[108:109]
	v_lshlrev_b32_e32 v108, 16, v224
	v_and_b32_e32 v109, 0xffff0000, v224
	v_mul_f32_e32 v108, 0xbfb8aa3b, v108
	v_mul_f32_e32 v109, 0xbfb8aa3b, v109
	v_exp_f32_e32 v108, v108
	v_exp_f32_e32 v109, v109
	v_add_f32_e32 v108, 1.0, v108
	v_add_f32_e32 v109, 1.0, v109
	v_rcp_f32_e32 v108, v108
	v_rcp_f32_e32 v109, v109
	s_nop 0
	v_pk_mul_f32 v[108:109], v[100:101], v[108:109]
	v_lshlrev_b32_e32 v100, 16, v225
	v_and_b32_e32 v101, 0xffff0000, v225
	v_add_u32_e32 v166, 0x90, v156
	v_ashrrev_i32_e32 v167, 31, v166
	v_lshlrev_b64 v[168:169], 12, v[166:167]
	v_lshl_add_u64 v[166:167], s[16:17], 0, v[168:169]
	v_lshl_add_u64 v[166:167], v[166:167], 0, v[148:149]
	global_load_dwordx4 v[222:225], v[166:167], off offset:256
	v_mul_f32_e32 v100, 0xbfb8aa3b, v100
	v_mul_f32_e32 v101, 0xbfb8aa3b, v101
	v_exp_f32_e32 v100, v100
	v_exp_f32_e32 v101, v101
	v_add_f32_e32 v100, 1.0, v100
	v_add_f32_e32 v101, 1.0, v101
	v_rcp_f32_e32 v100, v100
	v_rcp_f32_e32 v101, v101
	s_nop 0
	v_pk_mul_f32 v[110:111], v[102:103], v[100:101]
	v_cvt_pk_bf16_f32 v100, v104, v105
	v_cvt_pk_bf16_f32 v101, v106, v107
	v_cvt_pk_bf16_f32 v102, v108, v109
	v_cvt_pk_bf16_f32 v103, v110, v111
	global_store_dwordx4 v[112:113], v[100:103], off offset:256
	s_nop 1
	v_or_b32_e32 v100, 32, v156
	s_nop 0
	v_ashrrev_i32_e32 v101, 31, v100
	v_lshlrev_b64 v[102:103], 12, v[100:101]
	v_lshlrev_b64 v[106:107], 11, v[100:101]
	v_lshl_add_u64 v[100:101], s[16:17], 0, v[102:103]
	v_lshl_add_u64 v[100:101], v[100:101], 0, v[148:149]
	s_waitcnt vmcnt(11)
	v_lshlrev_b32_e32 v108, 16, v226
	v_and_b32_e32 v102, 0xffff0000, v226
	v_mul_f32_e32 v108, 0xbfb8aa3b, v108
	v_mul_f32_e32 v102, 0xbfb8aa3b, v102
	v_exp_f32_e32 v108, v108
	v_exp_f32_e32 v102, v102
	v_add_f32_e32 v108, 1.0, v108
	v_add_f32_e32 v102, 1.0, v102
	v_rcp_f32_e32 v108, v108
	v_rcp_f32_e32 v109, v102
	s_nop 0
	v_pk_mul_f32 v[108:109], v[96:97], v[108:109]
	v_lshlrev_b32_e32 v96, 16, v227
	v_and_b32_e32 v97, 0xffff0000, v227
	v_mul_f32_e32 v96, 0xbfb8aa3b, v96
	v_mul_f32_e32 v97, 0xbfb8aa3b, v97
	v_exp_f32_e32 v96, v96
	v_exp_f32_e32 v97, v97
	v_add_f32_e32 v96, 1.0, v96
	v_add_f32_e32 v97, 1.0, v97
	v_rcp_f32_e32 v96, v96
	v_rcp_f32_e32 v97, v97
	s_nop 0
	v_pk_mul_f32 v[98:99], v[98:99], v[96:97]
	v_lshlrev_b32_e32 v96, 16, v228
	v_and_b32_e32 v97, 0xffff0000, v228
	v_mul_f32_e32 v96, 0xbfb8aa3b, v96
	v_mul_f32_e32 v97, 0xbfb8aa3b, v97
	v_exp_f32_e32 v96, v96
	v_exp_f32_e32 v97, v97
	v_add_f32_e32 v96, 1.0, v96
	v_add_f32_e32 v97, 1.0, v97
	v_rcp_f32_e32 v96, v96
	v_rcp_f32_e32 v97, v97
	s_nop 0
	v_pk_mul_f32 v[102:103], v[92:93], v[96:97]
	v_lshlrev_b32_e32 v92, 16, v229
	v_and_b32_e32 v93, 0xffff0000, v229
	v_add_u32_e32 v166, 0xa0, v156
	v_ashrrev_i32_e32 v167, 31, v166
	v_lshlrev_b64 v[168:169], 12, v[166:167]
	v_lshl_add_u64 v[166:167], s[16:17], 0, v[168:169]
	v_lshl_add_u64 v[166:167], v[166:167], 0, v[148:149]
	global_load_dwordx4 v[226:229], v[166:167], off
	v_mul_f32_e32 v92, 0xbfb8aa3b, v92
	v_mul_f32_e32 v93, 0xbfb8aa3b, v93
	v_exp_f32_e32 v92, v92
	v_exp_f32_e32 v93, v93
	v_add_f32_e32 v92, 1.0, v92
	v_add_f32_e32 v93, 1.0, v93
	v_rcp_f32_e32 v92, v92
	v_rcp_f32_e32 v93, v93
	s_nop 0
	v_pk_mul_f32 v[104:105], v[94:95], v[92:93]
	v_lshl_add_u64 v[92:93], s[18:19], 0, v[106:107]
	v_lshl_add_u64 v[96:97], v[92:93], 0, v[148:149]
	v_cvt_pk_bf16_f32 v92, v108, v109
	v_cvt_pk_bf16_f32 v93, v98, v99
	v_cvt_pk_bf16_f32 v94, v102, v103
	v_cvt_pk_bf16_f32 v95, v104, v105
	global_store_dwordx4 v[96:97], v[92:95], off
	s_waitcnt vmcnt(12)
; __device__ __forceinline__ unsigned cvt_pk_bf16(float lo, float hi) { f32x2_cv v = {lo, hi}; bf16x2_cv b = __builtin_convertvector(v, bf16x2_cv); return __builtin_bit_cast(unsigned, b); }
; __device__ __forceinline__ float fast_sigmoid(float x) { return __builtin_amdgcn_rcpf(1.0f + __expf(-x)); }
; __device__ __forceinline__ float bf_lo(unsigned w) { return __uint_as_float(w << 16); }
; __device__ __forceinline__ float bf_hi(unsigned w) { return __uint_as_float(w & 0xffff0000u); }
;     __device__ __forceinline__ void operator()(const f32x4 (&acc)[2][2][4][2], const Unit& u, int wr, int wc, int fr, int fq) const {
;     ...
;                 for (int bj = 0; bj < 2; ++bj) {
;                     const u32x4 gw = *(const u32x4*)(GG + row * 2048 + goff + col0 + bj * HALF);
;                     f32x4 v0, v1;
;                     v0[0] = fast_sigmoid(bf_lo(gw.x)) * acc[ai][bj][m][0][0]; v0[1] = fast_sigmoid(bf_hi(gw.x)) * acc[ai][bj][m][0][1];
;                     v0[2] = fast_sigmoid(bf_lo(gw.y)) * acc[ai][bj][m][0][2]; v0[3] = fast_sigmoid(bf_hi(gw.y)) * acc[ai][bj][m][0][3];
;                     v1[0] = fast_sigmoid(bf_lo(gw.z)) * acc[ai][bj][m][1][0]; v1[1] = fast_sigmoid(bf_hi(gw.z)) * acc[ai][bj][m][1][1];
;                     v1[2] = fast_sigmoid(bf_lo(gw.w)) * acc[ai][bj][m][1][2]; v1[3] = fast_sigmoid(bf_hi(gw.w)) * acc[ai][bj][m][1][3];
;                     bf16_t* tp = TMP + row * 1024 + col0 + bj * HALF;
;                     if (MODE == 1) { const u32x4 tw = *(const u32x4*)tp;
;                         v0 += (f32x4){bf_lo(tw.x), bf_hi(tw.x), bf_lo(tw.y), bf_hi(tw.y)}; v1 += (f32x4){bf_lo(tw.z), bf_hi(tw.z), bf_lo(tw.w), bf_hi(tw.w)}; }
;                     u32x4 w; w.x = cvt_pk_bf16(v0[0], v0[1]); w.y = cvt_pk_bf16(v0[2], v0[3]); w.z = cvt_pk_bf16(v1[0], v1[1]); w.w = cvt_pk_bf16(v1[2], v1[3]);
;                     *(u32x4*)((MODE == 0 ? tp : MIX + row * 1024 + col0 + bj * HALF)) = w;
	v_lshlrev_b32_e32 v98, 16, v230
	v_and_b32_e32 v92, 0xffff0000, v230
	v_mul_f32_e32 v92, 0xbfb8aa3b, v92
	v_exp_f32_e32 v92, v92
	v_mul_f32_e32 v98, 0xbfb8aa3b, v98
	v_exp_f32_e32 v98, v98
	v_add_f32_e32 v92, 1.0, v92
	v_rcp_f32_e32 v99, v92
	v_lshlrev_b32_e32 v92, 16, v231
	v_and_b32_e32 v93, 0xffff0000, v231
	v_mul_f32_e32 v92, 0xbfb8aa3b, v92
	v_mul_f32_e32 v93, 0xbfb8aa3b, v93
	v_exp_f32_e32 v92, v92
	v_exp_f32_e32 v93, v93
	v_add_f32_e32 v98, 1.0, v98
	v_rcp_f32_e32 v98, v98
	v_add_f32_e32 v92, 1.0, v92
	v_add_f32_e32 v93, 1.0, v93
	v_rcp_f32_e32 v92, v92
	v_rcp_f32_e32 v93, v93
	v_pk_mul_f32 v[88:89], v[88:89], v[98:99]
	v_pk_mul_f32 v[90:91], v[90:91], v[92:93]
	v_lshlrev_b32_e32 v92, 16, v232
	v_and_b32_e32 v93, 0xffff0000, v232
	v_mul_f32_e32 v92, 0xbfb8aa3b, v92
	v_mul_f32_e32 v93, 0xbfb8aa3b, v93
	v_exp_f32_e32 v92, v92
	v_exp_f32_e32 v93, v93
	v_add_f32_e32 v92, 1.0, v92
	v_add_f32_e32 v93, 1.0, v93
	v_rcp_f32_e32 v92, v92
	v_rcp_f32_e32 v93, v93
	s_nop 0
	v_pk_mul_f32 v[92:93], v[84:85], v[92:93]
	v_lshlrev_b32_e32 v84, 16, v233
	v_and_b32_e32 v85, 0xffff0000, v233
	v_add_u32_e32 v166, 0xa0, v156
	v_ashrrev_i32_e32 v167, 31, v166
	v_lshlrev_b64 v[168:169], 12, v[166:167]
	v_lshl_add_u64 v[166:167], s[16:17], 0, v[168:169]
	v_lshl_add_u64 v[166:167], v[166:167], 0, v[148:149]
	global_load_dwordx4 v[230:233], v[166:167], off offset:256
	v_mul_f32_e32 v84, 0xbfb8aa3b, v84
	v_mul_f32_e32 v85, 0xbfb8aa3b, v85
	v_exp_f32_e32 v84, v84
	v_exp_f32_e32 v85, v85
	v_add_f32_e32 v84, 1.0, v84
	v_add_f32_e32 v85, 1.0, v85
	v_rcp_f32_e32 v84, v84
	v_rcp_f32_e32 v85, v85
	s_nop 0
	v_pk_mul_f32 v[94:95], v[86:87], v[84:85]
	v_cvt_pk_bf16_f32 v84, v88, v89
	v_cvt_pk_bf16_f32 v85, v90, v91
	v_cvt_pk_bf16_f32 v86, v92, v93
	v_cvt_pk_bf16_f32 v87, v94, v95
	global_store_dwordx4 v[96:97], v[84:87], off offset:256
	s_nop 1
	v_or_b32_e32 v84, 48, v156
	s_nop 0
	v_ashrrev_i32_e32 v85, 31, v84
	v_lshlrev_b64 v[86:87], 12, v[84:85]
	v_lshlrev_b64 v[90:91], 11, v[84:85]
	v_lshl_add_u64 v[84:85], s[16:17], 0, v[86:87]
	v_lshl_add_u64 v[84:85], v[84:85], 0, v[148:149]
	s_waitcnt vmcnt(13)
	v_lshlrev_b32_e32 v92, 16, v182
	v_and_b32_e32 v86, 0xffff0000, v182
	v_mul_f32_e32 v92, 0xbfb8aa3b, v92
	v_mul_f32_e32 v86, 0xbfb8aa3b, v86
	v_exp_f32_e32 v92, v92
	v_exp_f32_e32 v86, v86
	v_add_f32_e32 v92, 1.0, v92
	v_add_f32_e32 v86, 1.0, v86
	v_rcp_f32_e32 v92, v92
	v_rcp_f32_e32 v93, v86
	s_nop 0
	v_pk_mul_f32 v[92:93], v[80:81], v[92:93]
	v_lshlrev_b32_e32 v80, 16, v183
	v_and_b32_e32 v81, 0xffff0000, v183
	v_mul_f32_e32 v80, 0xbfb8aa3b, v80
	v_mul_f32_e32 v81, 0xbfb8aa3b, v81
	v_exp_f32_e32 v80, v80
	v_exp_f32_e32 v81, v81
	v_add_f32_e32 v80, 1.0, v80
	v_add_f32_e32 v81, 1.0, v81
	v_rcp_f32_e32 v80, v80
	v_rcp_f32_e32 v81, v81
	s_nop 0
	v_pk_mul_f32 v[82:83], v[82:83], v[80:81]
	v_lshlrev_b32_e32 v80, 16, v184
	v_and_b32_e32 v81, 0xffff0000, v184
	v_mul_f32_e32 v80, 0xbfb8aa3b, v80
	v_mul_f32_e32 v81, 0xbfb8aa3b, v81
	v_exp_f32_e32 v80, v80
	v_exp_f32_e32 v81, v81
	v_add_f32_e32 v80, 1.0, v80
	v_add_f32_e32 v81, 1.0, v81
	v_rcp_f32_e32 v80, v80
	v_rcp_f32_e32 v81, v81
	s_nop 0
	v_pk_mul_f32 v[86:87], v[76:77], v[80:81]
	v_lshlrev_b32_e32 v76, 16, v185
	v_and_b32_e32 v77, 0xffff0000, v185
	v_add_u32_e32 v166, 0xb0, v156
	v_ashrrev_i32_e32 v167, 31, v166
	v_lshlrev_b64 v[168:169], 12, v[166:167]
	v_lshl_add_u64 v[166:167], s[16:17], 0, v[168:169]
	v_lshl_add_u64 v[166:167], v[166:167], 0, v[148:149]
	global_load_dwordx4 v[182:185], v[166:167], off
	v_mul_f32_e32 v76, 0xbfb8aa3b, v76
	v_mul_f32_e32 v77, 0xbfb8aa3b, v77
	v_exp_f32_e32 v76, v76
	v_exp_f32_e32 v77, v77
	v_add_f32_e32 v76, 1.0, v76
	v_add_f32_e32 v77, 1.0, v77
	v_rcp_f32_e32 v76, v76
	v_rcp_f32_e32 v77, v77
	s_nop 0
	v_pk_mul_f32 v[88:89], v[78:79], v[76:77]
	v_lshl_add_u64 v[76:77], s[18:19], 0, v[90:91]
	v_lshl_add_u64 v[80:81], v[76:77], 0, v[148:149]
	v_cvt_pk_bf16_f32 v76, v92, v93
	v_cvt_pk_bf16_f32 v77, v82, v83
	v_cvt_pk_bf16_f32 v78, v86, v87
	v_cvt_pk_bf16_f32 v79, v88, v89
	global_store_dwordx4 v[80:81], v[76:79], off
	s_waitcnt vmcnt(14)
	v_lshlrev_b32_e32 v82, 16, v186
	v_and_b32_e32 v76, 0xffff0000, v186
	v_mul_f32_e32 v76, 0xbfb8aa3b, v76
	v_exp_f32_e32 v76, v76
	v_mul_f32_e32 v82, 0xbfb8aa3b, v82
	v_exp_f32_e32 v82, v82
	v_add_f32_e32 v76, 1.0, v76
	v_rcp_f32_e32 v83, v76
	v_lshlrev_b32_e32 v76, 16, v187
	v_and_b32_e32 v77, 0xffff0000, v187
	v_mul_f32_e32 v76, 0xbfb8aa3b, v76
	v_mul_f32_e32 v77, 0xbfb8aa3b, v77
	v_exp_f32_e32 v76, v76
	v_exp_f32_e32 v77, v77
	v_add_f32_e32 v82, 1.0, v82
	v_rcp_f32_e32 v82, v82
	v_add_f32_e32 v76, 1.0, v76
	v_add_f32_e32 v77, 1.0, v77
	v_rcp_f32_e32 v76, v76
	v_rcp_f32_e32 v77, v77
	v_pk_mul_f32 v[72:73], v[72:73], v[82:83]
	v_pk_mul_f32 v[74:75], v[74:75], v[76:77]
	v_lshlrev_b32_e32 v76, 16, v188
	v_and_b32_e32 v77, 0xffff0000, v188
	v_mul_f32_e32 v76, 0xbfb8aa3b, v76
	v_mul_f32_e32 v77, 0xbfb8aa3b, v77
	v_exp_f32_e32 v76, v76
	v_exp_f32_e32 v77, v77
	v_add_f32_e32 v76, 1.0, v76
	v_add_f32_e32 v77, 1.0, v77
	v_rcp_f32_e32 v76, v76
	v_rcp_f32_e32 v77, v77
	s_nop 0
	v_pk_mul_f32 v[76:77], v[68:69], v[76:77]
	v_lshlrev_b32_e32 v68, 16, v189
	v_and_b32_e32 v69, 0xffff0000, v189
	v_add_u32_e32 v166, 0xb0, v156
	v_ashrrev_i32_e32 v167, 31, v166
	v_lshlrev_b64 v[168:169], 12, v[166:167]
	v_lshl_add_u64 v[166:167], s[16:17], 0, v[168:169]
	v_lshl_add_u64 v[166:167], v[166:167], 0, v[148:149]
	global_load_dwordx4 v[186:189], v[166:167], off offset:256
	v_mul_f32_e32 v68, 0xbfb8aa3b, v68
	v_mul_f32_e32 v69, 0xbfb8aa3b, v69
	v_exp_f32_e32 v68, v68
	v_exp_f32_e32 v69, v69
	v_add_f32_e32 v68, 1.0, v68
	v_add_f32_e32 v69, 1.0, v69
	v_rcp_f32_e32 v68, v68
	v_rcp_f32_e32 v69, v69
	s_nop 0
	v_pk_mul_f32 v[78:79], v[70:71], v[68:69]
	v_cvt_pk_bf16_f32 v68, v72, v73
	v_cvt_pk_bf16_f32 v69, v74, v75
	v_cvt_pk_bf16_f32 v70, v76, v77
	v_cvt_pk_bf16_f32 v71, v78, v79
	global_store_dwordx4 v[80:81], v[68:71], off offset:256
	s_nop 1
	v_add_u32_e32 v68, 0x80, v156
	s_nop 0
	v_ashrrev_i32_e32 v69, 31, v68
	v_lshlrev_b64 v[70:71], 12, v[68:69]
	v_lshlrev_b64 v[74:75], 11, v[68:69]
	v_lshl_add_u64 v[68:69], s[16:17], 0, v[70:71]
	v_lshl_add_u64 v[68:69], v[68:69], 0, v[148:149]
	s_waitcnt vmcnt(15)
; __device__ __forceinline__ unsigned cvt_pk_bf16(float lo, float hi) { f32x2_cv v = {lo, hi}; bf16x2_cv b = __builtin_convertvector(v, bf16x2_cv); return __builtin_bit_cast(unsigned, b); }
; __device__ __forceinline__ float fast_sigmoid(float x) { return __builtin_amdgcn_rcpf(1.0f + __expf(-x)); }
; __device__ __forceinline__ float bf_lo(unsigned w) { return __uint_as_float(w << 16); }
; __device__ __forceinline__ float bf_hi(unsigned w) { return __uint_as_float(w & 0xffff0000u); }
;     __device__ __forceinline__ void operator()(const f32x4 (&acc)[2][2][4][2], const Unit& u, int wr, int wc, int fr, int fq) const {
;     ...
;                 for (int bj = 0; bj < 2; ++bj) {
;                     const u32x4 gw = *(const u32x4*)(GG + row * 2048 + goff + col0 + bj * HALF);
;                     f32x4 v0, v1;
;                     v0[0] = fast_sigmoid(bf_lo(gw.x)) * acc[ai][bj][m][0][0]; v0[1] = fast_sigmoid(bf_hi(gw.x)) * acc[ai][bj][m][0][1];
;                     v0[2] = fast_sigmoid(bf_lo(gw.y)) * acc[ai][bj][m][0][2]; v0[3] = fast_sigmoid(bf_hi(gw.y)) * acc[ai][bj][m][0][3];
;                     v1[0] = fast_sigmoid(bf_lo(gw.z)) * acc[ai][bj][m][1][0]; v1[1] = fast_sigmoid(bf_hi(gw.z)) * acc[ai][bj][m][1][1];
;                     v1[2] = fast_sigmoid(bf_lo(gw.w)) * acc[ai][bj][m][1][2]; v1[3] = fast_sigmoid(bf_hi(gw.w)) * acc[ai][bj][m][1][3];
;                     bf16_t* tp = TMP + row * 1024 + col0 + bj * HALF;
;                     if (MODE == 1) { const u32x4 tw = *(const u32x4*)tp;
;                         v0 += (f32x4){bf_lo(tw.x), bf_hi(tw.x), bf_lo(tw.y), bf_hi(tw.y)}; v1 += (f32x4){bf_lo(tw.z), bf_hi(tw.z), bf_lo(tw.w), bf_hi(tw.w)}; }
;                     u32x4 w; w.x = cvt_pk_bf16(v0[0], v0[1]); w.y = cvt_pk_bf16(v0[2], v0[3]); w.z = cvt_pk_bf16(v1[0], v1[1]); w.w = cvt_pk_bf16(v1[2], v1[3]);
;                     *(u32x4*)((MODE == 0 ? tp : MIX + row * 1024 + col0 + bj * HALF)) = w;
	v_lshlrev_b32_e32 v76, 16, v210
	v_and_b32_e32 v70, 0xffff0000, v210
	v_mul_f32_e32 v76, 0xbfb8aa3b, v76
	v_mul_f32_e32 v70, 0xbfb8aa3b, v70
	v_exp_f32_e32 v76, v76
	v_exp_f32_e32 v70, v70
	v_add_f32_e32 v76, 1.0, v76
	v_add_f32_e32 v70, 1.0, v70
	v_rcp_f32_e32 v76, v76
	v_rcp_f32_e32 v77, v70
	s_nop 0
	v_pk_mul_f32 v[76:77], v[64:65], v[76:77]
	v_lshlrev_b32_e32 v64, 16, v211
	v_and_b32_e32 v65, 0xffff0000, v211
	v_mul_f32_e32 v64, 0xbfb8aa3b, v64
	v_mul_f32_e32 v65, 0xbfb8aa3b, v65
	v_exp_f32_e32 v64, v64
	v_exp_f32_e32 v65, v65
	v_add_f32_e32 v64, 1.0, v64
	v_add_f32_e32 v65, 1.0, v65
	v_rcp_f32_e32 v64, v64
	v_rcp_f32_e32 v65, v65
	s_nop 0
	v_pk_mul_f32 v[66:67], v[66:67], v[64:65]
	v_lshlrev_b32_e32 v64, 16, v212
	v_and_b32_e32 v65, 0xffff0000, v212
	v_mul_f32_e32 v64, 0xbfb8aa3b, v64
	v_mul_f32_e32 v65, 0xbfb8aa3b, v65
	v_exp_f32_e32 v64, v64
	v_exp_f32_e32 v65, v65
	v_add_f32_e32 v64, 1.0, v64
	v_add_f32_e32 v65, 1.0, v65
	v_rcp_f32_e32 v64, v64
	v_rcp_f32_e32 v65, v65
	s_nop 0
	v_pk_mul_f32 v[70:71], v[60:61], v[64:65]
	v_lshlrev_b32_e32 v60, 16, v213
	v_and_b32_e32 v61, 0xffff0000, v213
	v_mul_f32_e32 v60, 0xbfb8aa3b, v60
	v_mul_f32_e32 v61, 0xbfb8aa3b, v61
	v_exp_f32_e32 v60, v60
	v_exp_f32_e32 v61, v61
	v_add_f32_e32 v60, 1.0, v60
	v_add_f32_e32 v61, 1.0, v61
	v_rcp_f32_e32 v60, v60
	v_rcp_f32_e32 v61, v61
	s_nop 0
	v_pk_mul_f32 v[72:73], v[62:63], v[60:61]
	v_lshl_add_u64 v[60:61], s[18:19], 0, v[74:75]
	v_lshl_add_u64 v[64:65], v[60:61], 0, v[148:149]
	v_cvt_pk_bf16_f32 v60, v76, v77
	v_cvt_pk_bf16_f32 v61, v66, v67
	v_cvt_pk_bf16_f32 v62, v70, v71
	v_cvt_pk_bf16_f32 v63, v72, v73
	global_store_dwordx4 v[64:65], v[60:63], off
	s_waitcnt vmcnt(14)
	v_lshlrev_b32_e32 v66, 16, v214
	v_and_b32_e32 v60, 0xffff0000, v214
	v_mul_f32_e32 v60, 0xbfb8aa3b, v60
	v_exp_f32_e32 v60, v60
	v_mul_f32_e32 v66, 0xbfb8aa3b, v66
	v_exp_f32_e32 v66, v66
	v_add_f32_e32 v60, 1.0, v60
	v_rcp_f32_e32 v67, v60
	v_lshlrev_b32_e32 v60, 16, v215
	v_and_b32_e32 v61, 0xffff0000, v215
	v_mul_f32_e32 v60, 0xbfb8aa3b, v60
	v_mul_f32_e32 v61, 0xbfb8aa3b, v61
	v_exp_f32_e32 v60, v60
	v_exp_f32_e32 v61, v61
	v_add_f32_e32 v66, 1.0, v66
	v_rcp_f32_e32 v66, v66
	v_add_f32_e32 v60, 1.0, v60
	v_add_f32_e32 v61, 1.0, v61
	v_rcp_f32_e32 v60, v60
	v_rcp_f32_e32 v61, v61
	v_pk_mul_f32 v[56:57], v[56:57], v[66:67]
	v_pk_mul_f32 v[58:59], v[58:59], v[60:61]
	v_lshlrev_b32_e32 v60, 16, v216
	v_and_b32_e32 v61, 0xffff0000, v216
	v_mul_f32_e32 v60, 0xbfb8aa3b, v60
	v_mul_f32_e32 v61, 0xbfb8aa3b, v61
	v_exp_f32_e32 v60, v60
	v_exp_f32_e32 v61, v61
	v_add_f32_e32 v60, 1.0, v60
	v_add_f32_e32 v61, 1.0, v61
	v_rcp_f32_e32 v60, v60
	v_rcp_f32_e32 v61, v61
	s_nop 0
	v_pk_mul_f32 v[60:61], v[52:53], v[60:61]
	v_lshlrev_b32_e32 v52, 16, v217
	v_and_b32_e32 v53, 0xffff0000, v217
	v_mul_f32_e32 v52, 0xbfb8aa3b, v52
	v_mul_f32_e32 v53, 0xbfb8aa3b, v53
	v_exp_f32_e32 v52, v52
	v_exp_f32_e32 v53, v53
	v_add_f32_e32 v52, 1.0, v52
	v_add_f32_e32 v53, 1.0, v53
	v_rcp_f32_e32 v52, v52
	v_rcp_f32_e32 v53, v53
	s_nop 0
	v_pk_mul_f32 v[62:63], v[54:55], v[52:53]
	v_cvt_pk_bf16_f32 v52, v56, v57
	v_cvt_pk_bf16_f32 v53, v58, v59
	v_cvt_pk_bf16_f32 v54, v60, v61
	v_cvt_pk_bf16_f32 v55, v62, v63
	global_store_dwordx4 v[64:65], v[52:55], off offset:256
	s_nop 1
	v_add_u32_e32 v52, 0x90, v156
	s_nop 0
	v_ashrrev_i32_e32 v53, 31, v52
	v_lshlrev_b64 v[54:55], 12, v[52:53]
	v_lshlrev_b64 v[58:59], 11, v[52:53]
	v_lshl_add_u64 v[52:53], s[16:17], 0, v[54:55]
	v_lshl_add_u64 v[52:53], v[52:53], 0, v[148:149]
	s_waitcnt vmcnt(13)
	v_lshlrev_b32_e32 v60, 16, v218
	v_and_b32_e32 v54, 0xffff0000, v218
	v_mul_f32_e32 v60, 0xbfb8aa3b, v60
	v_mul_f32_e32 v54, 0xbfb8aa3b, v54
	v_exp_f32_e32 v60, v60
	v_exp_f32_e32 v54, v54
	v_add_f32_e32 v60, 1.0, v60
	v_add_f32_e32 v54, 1.0, v54
	v_rcp_f32_e32 v60, v60
	v_rcp_f32_e32 v61, v54
	s_nop 0
	v_pk_mul_f32 v[60:61], v[48:49], v[60:61]
	v_lshlrev_b32_e32 v48, 16, v219
	v_and_b32_e32 v49, 0xffff0000, v219
	v_mul_f32_e32 v48, 0xbfb8aa3b, v48
	v_mul_f32_e32 v49, 0xbfb8aa3b, v49
	v_exp_f32_e32 v48, v48
	v_exp_f32_e32 v49, v49
	v_add_f32_e32 v48, 1.0, v48
	v_add_f32_e32 v49, 1.0, v49
	v_rcp_f32_e32 v48, v48
	v_rcp_f32_e32 v49, v49
	s_nop 0
	v_pk_mul_f32 v[50:51], v[50:51], v[48:49]
	v_lshlrev_b32_e32 v48, 16, v220
	v_and_b32_e32 v49, 0xffff0000, v220
	v_mul_f32_e32 v48, 0xbfb8aa3b, v48
	v_mul_f32_e32 v49, 0xbfb8aa3b, v49
	v_exp_f32_e32 v48, v48
	v_exp_f32_e32 v49, v49
	v_add_f32_e32 v48, 1.0, v48
	v_add_f32_e32 v49, 1.0, v49
	v_rcp_f32_e32 v48, v48
	v_rcp_f32_e32 v49, v49
	s_nop 0
	v_pk_mul_f32 v[54:55], v[44:45], v[48:49]
	v_lshlrev_b32_e32 v44, 16, v221
	v_and_b32_e32 v45, 0xffff0000, v221
	v_mul_f32_e32 v44, 0xbfb8aa3b, v44
	v_mul_f32_e32 v45, 0xbfb8aa3b, v45
	v_exp_f32_e32 v44, v44
	v_exp_f32_e32 v45, v45
	v_add_f32_e32 v44, 1.0, v44
	v_add_f32_e32 v45, 1.0, v45
	v_rcp_f32_e32 v44, v44
	v_rcp_f32_e32 v45, v45
	s_nop 0
	v_pk_mul_f32 v[56:57], v[46:47], v[44:45]
	v_lshl_add_u64 v[44:45], s[18:19], 0, v[58:59]
	v_lshl_add_u64 v[48:49], v[44:45], 0, v[148:149]
	v_cvt_pk_bf16_f32 v44, v60, v61
	v_cvt_pk_bf16_f32 v45, v50, v51
	v_cvt_pk_bf16_f32 v46, v54, v55
	v_cvt_pk_bf16_f32 v47, v56, v57
	global_store_dwordx4 v[48:49], v[44:47], off
	s_waitcnt vmcnt(12)
; __device__ __forceinline__ unsigned cvt_pk_bf16(float lo, float hi) { f32x2_cv v = {lo, hi}; bf16x2_cv b = __builtin_convertvector(v, bf16x2_cv); return __builtin_bit_cast(unsigned, b); }
; __device__ __forceinline__ float fast_sigmoid(float x) { return __builtin_amdgcn_rcpf(1.0f + __expf(-x)); }
; __device__ __forceinline__ float bf_lo(unsigned w) { return __uint_as_float(w << 16); }
; __device__ __forceinline__ float bf_hi(unsigned w) { return __uint_as_float(w & 0xffff0000u); }
;     __device__ __forceinline__ void operator()(const f32x4 (&acc)[2][2][4][2], const Unit& u, int wr, int wc, int fr, int fq) const {
;     ...
;                 for (int bj = 0; bj < 2; ++bj) {
;                     const u32x4 gw = *(const u32x4*)(GG + row * 2048 + goff + col0 + bj * HALF);
;                     f32x4 v0, v1;
;                     v0[0] = fast_sigmoid(bf_lo(gw.x)) * acc[ai][bj][m][0][0]; v0[1] = fast_sigmoid(bf_hi(gw.x)) * acc[ai][bj][m][0][1];
;                     v0[2] = fast_sigmoid(bf_lo(gw.y)) * acc[ai][bj][m][0][2]; v0[3] = fast_sigmoid(bf_hi(gw.y)) * acc[ai][bj][m][0][3];
;                     v1[0] = fast_sigmoid(bf_lo(gw.z)) * acc[ai][bj][m][1][0]; v1[1] = fast_sigmoid(bf_hi(gw.z)) * acc[ai][bj][m][1][1];
;                     v1[2] = fast_sigmoid(bf_lo(gw.w)) * acc[ai][bj][m][1][2]; v1[3] = fast_sigmoid(bf_hi(gw.w)) * acc[ai][bj][m][1][3];
;                     bf16_t* tp = TMP + row * 1024 + col0 + bj * HALF;
;                     if (MODE == 1) { const u32x4 tw = *(const u32x4*)tp;
;                         v0 += (f32x4){bf_lo(tw.x), bf_hi(tw.x), bf_lo(tw.y), bf_hi(tw.y)}; v1 += (f32x4){bf_lo(tw.z), bf_hi(tw.z), bf_lo(tw.w), bf_hi(tw.w)}; }
;                     u32x4 w; w.x = cvt_pk_bf16(v0[0], v0[1]); w.y = cvt_pk_bf16(v0[2], v0[3]); w.z = cvt_pk_bf16(v1[0], v1[1]); w.w = cvt_pk_bf16(v1[2], v1[3]);
;                     *(u32x4*)((MODE == 0 ? tp : MIX + row * 1024 + col0 + bj * HALF)) = w;
	v_lshlrev_b32_e32 v50, 16, v222
	v_and_b32_e32 v44, 0xffff0000, v222
	v_mul_f32_e32 v44, 0xbfb8aa3b, v44
	v_exp_f32_e32 v44, v44
	v_mul_f32_e32 v50, 0xbfb8aa3b, v50
	v_exp_f32_e32 v50, v50
	v_add_f32_e32 v44, 1.0, v44
	v_rcp_f32_e32 v51, v44
	v_lshlrev_b32_e32 v44, 16, v223
	v_and_b32_e32 v45, 0xffff0000, v223
	v_mul_f32_e32 v44, 0xbfb8aa3b, v44
	v_mul_f32_e32 v45, 0xbfb8aa3b, v45
	v_exp_f32_e32 v44, v44
	v_exp_f32_e32 v45, v45
	v_add_f32_e32 v50, 1.0, v50
	v_rcp_f32_e32 v50, v50
	v_add_f32_e32 v44, 1.0, v44
	v_add_f32_e32 v45, 1.0, v45
	v_rcp_f32_e32 v44, v44
	v_rcp_f32_e32 v45, v45
	v_pk_mul_f32 v[40:41], v[40:41], v[50:51]
	v_pk_mul_f32 v[42:43], v[42:43], v[44:45]
	v_lshlrev_b32_e32 v44, 16, v224
	v_and_b32_e32 v45, 0xffff0000, v224
	v_mul_f32_e32 v44, 0xbfb8aa3b, v44
	v_mul_f32_e32 v45, 0xbfb8aa3b, v45
	v_exp_f32_e32 v44, v44
	v_exp_f32_e32 v45, v45
	v_add_f32_e32 v44, 1.0, v44
	v_add_f32_e32 v45, 1.0, v45
	v_rcp_f32_e32 v44, v44
	v_rcp_f32_e32 v45, v45
	s_nop 0
	v_pk_mul_f32 v[44:45], v[36:37], v[44:45]
	v_lshlrev_b32_e32 v36, 16, v225
	v_and_b32_e32 v37, 0xffff0000, v225
	v_mul_f32_e32 v36, 0xbfb8aa3b, v36
	v_mul_f32_e32 v37, 0xbfb8aa3b, v37
	v_exp_f32_e32 v36, v36
	v_exp_f32_e32 v37, v37
	v_add_f32_e32 v36, 1.0, v36
	v_add_f32_e32 v37, 1.0, v37
	v_rcp_f32_e32 v36, v36
	v_rcp_f32_e32 v37, v37
	s_nop 0
	v_pk_mul_f32 v[46:47], v[38:39], v[36:37]
	v_cvt_pk_bf16_f32 v36, v40, v41
	v_cvt_pk_bf16_f32 v37, v42, v43
	v_cvt_pk_bf16_f32 v38, v44, v45
	v_cvt_pk_bf16_f32 v39, v46, v47
	global_store_dwordx4 v[48:49], v[36:39], off offset:256
	s_nop 1
	v_add_u32_e32 v36, 0xa0, v156
	s_nop 0
	v_ashrrev_i32_e32 v37, 31, v36
	v_lshlrev_b64 v[38:39], 12, v[36:37]
	v_lshlrev_b64 v[42:43], 11, v[36:37]
	v_lshl_add_u64 v[36:37], s[16:17], 0, v[38:39]
	v_lshl_add_u64 v[36:37], v[36:37], 0, v[148:149]
	s_waitcnt vmcnt(11)
	v_lshlrev_b32_e32 v44, 16, v226
	v_and_b32_e32 v38, 0xffff0000, v226
	v_mul_f32_e32 v44, 0xbfb8aa3b, v44
	v_mul_f32_e32 v38, 0xbfb8aa3b, v38
	v_exp_f32_e32 v44, v44
	v_exp_f32_e32 v38, v38
	v_add_f32_e32 v44, 1.0, v44
	v_add_f32_e32 v38, 1.0, v38
	v_rcp_f32_e32 v44, v44
	v_rcp_f32_e32 v45, v38
	s_nop 0
	v_pk_mul_f32 v[44:45], v[32:33], v[44:45]
	v_lshlrev_b32_e32 v32, 16, v227
	v_and_b32_e32 v33, 0xffff0000, v227
	v_mul_f32_e32 v32, 0xbfb8aa3b, v32
	v_mul_f32_e32 v33, 0xbfb8aa3b, v33
	v_exp_f32_e32 v32, v32
	v_exp_f32_e32 v33, v33
	v_add_f32_e32 v32, 1.0, v32
	v_add_f32_e32 v33, 1.0, v33
	v_rcp_f32_e32 v32, v32
	v_rcp_f32_e32 v33, v33
	s_nop 0
	v_pk_mul_f32 v[34:35], v[34:35], v[32:33]
	v_lshlrev_b32_e32 v32, 16, v228
	v_and_b32_e32 v33, 0xffff0000, v228
	v_mul_f32_e32 v32, 0xbfb8aa3b, v32
	v_mul_f32_e32 v33, 0xbfb8aa3b, v33
	v_exp_f32_e32 v32, v32
	v_exp_f32_e32 v33, v33
	v_add_f32_e32 v32, 1.0, v32
	v_add_f32_e32 v33, 1.0, v33
	v_rcp_f32_e32 v32, v32
	v_rcp_f32_e32 v33, v33
	s_nop 0
	v_pk_mul_f32 v[38:39], v[28:29], v[32:33]
	v_lshlrev_b32_e32 v28, 16, v229
	v_and_b32_e32 v29, 0xffff0000, v229
	v_mul_f32_e32 v28, 0xbfb8aa3b, v28
	v_mul_f32_e32 v29, 0xbfb8aa3b, v29
	v_exp_f32_e32 v28, v28
	v_exp_f32_e32 v29, v29
	v_add_f32_e32 v28, 1.0, v28
	v_add_f32_e32 v29, 1.0, v29
	v_rcp_f32_e32 v28, v28
	v_rcp_f32_e32 v29, v29
	s_nop 0
	v_pk_mul_f32 v[40:41], v[30:31], v[28:29]
	v_lshl_add_u64 v[28:29], s[18:19], 0, v[42:43]
	v_lshl_add_u64 v[32:33], v[28:29], 0, v[148:149]
	v_cvt_pk_bf16_f32 v28, v44, v45
	v_cvt_pk_bf16_f32 v29, v34, v35
	v_cvt_pk_bf16_f32 v30, v38, v39
	v_cvt_pk_bf16_f32 v31, v40, v41
	global_store_dwordx4 v[32:33], v[28:31], off
	s_waitcnt vmcnt(10)
; __device__ __forceinline__ unsigned cvt_pk_bf16(float lo, float hi) { f32x2_cv v = {lo, hi}; bf16x2_cv b = __builtin_convertvector(v, bf16x2_cv); return __builtin_bit_cast(unsigned, b); }
; __device__ __forceinline__ float fast_sigmoid(float x) { return __builtin_amdgcn_rcpf(1.0f + __expf(-x)); }
; __device__ __forceinline__ float bf_lo(unsigned w) { return __uint_as_float(w << 16); }
; __device__ __forceinline__ float bf_hi(unsigned w) { return __uint_as_float(w & 0xffff0000u); }
;     __device__ __forceinline__ void operator()(const f32x4 (&acc)[2][2][4][2], const Unit& u, int wr, int wc, int fr, int fq) const {
;     ...
;                 for (int bj = 0; bj < 2; ++bj) {
;                     const u32x4 gw = *(const u32x4*)(GG + row * 2048 + goff + col0 + bj * HALF);
;                     f32x4 v0, v1;
;                     v0[0] = fast_sigmoid(bf_lo(gw.x)) * acc[ai][bj][m][0][0]; v0[1] = fast_sigmoid(bf_hi(gw.x)) * acc[ai][bj][m][0][1];
;                     v0[2] = fast_sigmoid(bf_lo(gw.y)) * acc[ai][bj][m][0][2]; v0[3] = fast_sigmoid(bf_hi(gw.y)) * acc[ai][bj][m][0][3];
;                     v1[0] = fast_sigmoid(bf_lo(gw.z)) * acc[ai][bj][m][1][0]; v1[1] = fast_sigmoid(bf_hi(gw.z)) * acc[ai][bj][m][1][1];
;                     v1[2] = fast_sigmoid(bf_lo(gw.w)) * acc[ai][bj][m][1][2]; v1[3] = fast_sigmoid(bf_hi(gw.w)) * acc[ai][bj][m][1][3];
;                     bf16_t* tp = TMP + row * 1024 + col0 + bj * HALF;
;                     if (MODE == 1) { const u32x4 tw = *(const u32x4*)tp;
;                         v0 += (f32x4){bf_lo(tw.x), bf_hi(tw.x), bf_lo(tw.y), bf_hi(tw.y)}; v1 += (f32x4){bf_lo(tw.z), bf_hi(tw.z), bf_lo(tw.w), bf_hi(tw.w)}; }
;                     u32x4 w; w.x = cvt_pk_bf16(v0[0], v0[1]); w.y = cvt_pk_bf16(v0[2], v0[3]); w.z = cvt_pk_bf16(v1[0], v1[1]); w.w = cvt_pk_bf16(v1[2], v1[3]);
;                     *(u32x4*)((MODE == 0 ? tp : MIX + row * 1024 + col0 + bj * HALF)) = w;
	v_lshlrev_b32_e32 v34, 16, v230
	v_and_b32_e32 v28, 0xffff0000, v230
	v_mul_f32_e32 v28, 0xbfb8aa3b, v28
	v_exp_f32_e32 v28, v28
	v_mul_f32_e32 v34, 0xbfb8aa3b, v34
	v_exp_f32_e32 v34, v34
	v_add_f32_e32 v28, 1.0, v28
	v_rcp_f32_e32 v35, v28
	v_lshlrev_b32_e32 v28, 16, v231
	v_and_b32_e32 v29, 0xffff0000, v231
	v_mul_f32_e32 v28, 0xbfb8aa3b, v28
	v_mul_f32_e32 v29, 0xbfb8aa3b, v29
	v_exp_f32_e32 v28, v28
	v_exp_f32_e32 v29, v29
	v_add_f32_e32 v34, 1.0, v34
	v_rcp_f32_e32 v34, v34
	v_add_f32_e32 v28, 1.0, v28
	v_add_f32_e32 v29, 1.0, v29
	v_rcp_f32_e32 v28, v28
	v_rcp_f32_e32 v29, v29
	v_pk_mul_f32 v[24:25], v[24:25], v[34:35]
	v_pk_mul_f32 v[26:27], v[26:27], v[28:29]
	v_lshlrev_b32_e32 v28, 16, v232
	v_and_b32_e32 v29, 0xffff0000, v232
	v_mul_f32_e32 v28, 0xbfb8aa3b, v28
	v_mul_f32_e32 v29, 0xbfb8aa3b, v29
	v_exp_f32_e32 v28, v28
	v_exp_f32_e32 v29, v29
	v_add_f32_e32 v28, 1.0, v28
	v_add_f32_e32 v29, 1.0, v29
	v_rcp_f32_e32 v28, v28
	v_rcp_f32_e32 v29, v29
	s_nop 0
	v_pk_mul_f32 v[28:29], v[20:21], v[28:29]
	v_lshlrev_b32_e32 v20, 16, v233
	v_and_b32_e32 v21, 0xffff0000, v233
	v_mul_f32_e32 v20, 0xbfb8aa3b, v20
	v_mul_f32_e32 v21, 0xbfb8aa3b, v21
	v_exp_f32_e32 v20, v20
	v_exp_f32_e32 v21, v21
	v_add_f32_e32 v20, 1.0, v20
	v_add_f32_e32 v21, 1.0, v21
	v_rcp_f32_e32 v20, v20
	v_rcp_f32_e32 v21, v21
	s_nop 0
	v_pk_mul_f32 v[30:31], v[22:23], v[20:21]
	v_cvt_pk_bf16_f32 v20, v24, v25
	v_cvt_pk_bf16_f32 v21, v26, v27
	v_cvt_pk_bf16_f32 v22, v28, v29
	v_cvt_pk_bf16_f32 v23, v30, v31
	global_store_dwordx4 v[32:33], v[20:23], off offset:256
	s_nop 1
	v_add_u32_e32 v20, 0xb0, v156
	s_nop 0
	v_ashrrev_i32_e32 v21, 31, v20
	v_lshlrev_b64 v[22:23], 12, v[20:21]
	v_lshlrev_b64 v[26:27], 11, v[20:21]
	v_lshl_add_u64 v[20:21], s[16:17], 0, v[22:23]
	v_lshl_add_u64 v[20:21], v[20:21], 0, v[148:149]
	s_waitcnt vmcnt(9)
	v_lshlrev_b32_e32 v28, 16, v182
	v_and_b32_e32 v22, 0xffff0000, v182
	v_mul_f32_e32 v28, 0xbfb8aa3b, v28
	v_mul_f32_e32 v22, 0xbfb8aa3b, v22
	v_exp_f32_e32 v28, v28
	v_exp_f32_e32 v22, v22
	v_add_f32_e32 v28, 1.0, v28
	v_add_f32_e32 v22, 1.0, v22
	v_rcp_f32_e32 v28, v28
	v_rcp_f32_e32 v29, v22
	s_nop 0
	v_pk_mul_f32 v[28:29], v[16:17], v[28:29]
	v_lshlrev_b32_e32 v16, 16, v183
	v_and_b32_e32 v17, 0xffff0000, v183
	v_mul_f32_e32 v16, 0xbfb8aa3b, v16
	v_mul_f32_e32 v17, 0xbfb8aa3b, v17
	v_exp_f32_e32 v16, v16
	v_exp_f32_e32 v17, v17
	v_add_f32_e32 v16, 1.0, v16
	v_add_f32_e32 v17, 1.0, v17
	v_rcp_f32_e32 v16, v16
	v_rcp_f32_e32 v17, v17
	s_nop 0
	v_pk_mul_f32 v[18:19], v[18:19], v[16:17]
	v_lshlrev_b32_e32 v16, 16, v184
	v_and_b32_e32 v17, 0xffff0000, v184
	v_mul_f32_e32 v16, 0xbfb8aa3b, v16
	v_mul_f32_e32 v17, 0xbfb8aa3b, v17
	v_exp_f32_e32 v16, v16
	v_exp_f32_e32 v17, v17
	v_add_f32_e32 v16, 1.0, v16
	v_add_f32_e32 v17, 1.0, v17
	v_rcp_f32_e32 v16, v16
	v_rcp_f32_e32 v17, v17
	s_nop 0
	v_pk_mul_f32 v[22:23], v[12:13], v[16:17]
	v_lshlrev_b32_e32 v12, 16, v185
	v_and_b32_e32 v13, 0xffff0000, v185
	v_mul_f32_e32 v12, 0xbfb8aa3b, v12
	v_mul_f32_e32 v13, 0xbfb8aa3b, v13
	v_exp_f32_e32 v12, v12
	v_exp_f32_e32 v13, v13
	v_add_f32_e32 v12, 1.0, v12
	v_add_f32_e32 v13, 1.0, v13
	v_rcp_f32_e32 v12, v12
	v_rcp_f32_e32 v13, v13
	s_nop 0
	v_pk_mul_f32 v[24:25], v[14:15], v[12:13]
	v_lshl_add_u64 v[12:13], s[18:19], 0, v[26:27]
	v_lshl_add_u64 v[16:17], v[12:13], 0, v[148:149]
	v_cvt_pk_bf16_f32 v12, v28, v29
	v_cvt_pk_bf16_f32 v13, v18, v19
	v_cvt_pk_bf16_f32 v14, v22, v23
	v_cvt_pk_bf16_f32 v15, v24, v25
	global_store_dwordx4 v[16:17], v[12:15], off
	s_waitcnt vmcnt(8)
	v_lshlrev_b32_e32 v18, 16, v186
	v_and_b32_e32 v12, 0xffff0000, v186
	v_mul_f32_e32 v12, 0xbfb8aa3b, v12
	v_exp_f32_e32 v12, v12
	v_mul_f32_e32 v18, 0xbfb8aa3b, v18
	v_exp_f32_e32 v18, v18
	v_add_f32_e32 v12, 1.0, v12
	v_rcp_f32_e32 v19, v12
	v_lshlrev_b32_e32 v12, 16, v187
	v_and_b32_e32 v13, 0xffff0000, v187
	v_mul_f32_e32 v12, 0xbfb8aa3b, v12
	v_mul_f32_e32 v13, 0xbfb8aa3b, v13
	v_exp_f32_e32 v12, v12
	v_exp_f32_e32 v13, v13
	v_add_f32_e32 v18, 1.0, v18
	v_rcp_f32_e32 v18, v18
	v_add_f32_e32 v12, 1.0, v12
	v_add_f32_e32 v13, 1.0, v13
	v_rcp_f32_e32 v12, v12
	v_rcp_f32_e32 v13, v13
	v_pk_mul_f32 v[8:9], v[8:9], v[18:19]
	v_pk_mul_f32 v[10:11], v[10:11], v[12:13]
	v_lshlrev_b32_e32 v12, 16, v188
	v_and_b32_e32 v13, 0xffff0000, v188
	v_mul_f32_e32 v12, 0xbfb8aa3b, v12
	v_mul_f32_e32 v13, 0xbfb8aa3b, v13
	v_exp_f32_e32 v12, v12
	v_exp_f32_e32 v13, v13
	v_add_f32_e32 v12, 1.0, v12
	v_add_f32_e32 v13, 1.0, v13
	v_rcp_f32_e32 v12, v12
	v_rcp_f32_e32 v13, v13
	s_nop 0
	v_pk_mul_f32 v[12:13], v[4:5], v[12:13]
	v_lshlrev_b32_e32 v4, 16, v189
	v_and_b32_e32 v5, 0xffff0000, v189
	v_mul_f32_e32 v4, 0xbfb8aa3b, v4
	v_mul_f32_e32 v5, 0xbfb8aa3b, v5
	v_exp_f32_e32 v4, v4
	v_exp_f32_e32 v5, v5
	v_add_f32_e32 v4, 1.0, v4
	v_add_f32_e32 v5, 1.0, v5
	v_rcp_f32_e32 v4, v4
	v_rcp_f32_e32 v5, v5
	s_nop 0
	v_pk_mul_f32 v[14:15], v[6:7], v[4:5]
	v_cvt_pk_bf16_f32 v4, v8, v9
	v_cvt_pk_bf16_f32 v5, v10, v11
	v_cvt_pk_bf16_f32 v6, v12, v13
	v_cvt_pk_bf16_f32 v7, v14, v15
	global_store_dwordx4 v[16:17], v[4:7], off offset:256
	s_cbranch_vccnz .LBB0_756
	s_andn2_b64 vcc, exec, s[20:21]
	s_cbranch_vccnz .LBB0_755
	s_barrier
	s_branch .LBB0_755

; __device__ __forceinline__ unsigned cvt_pk_bf16(float lo, float hi) { f32x2_cv v = {lo, hi}; bf16x2_cv b = __builtin_convertvector(v, bf16x2_cv); return __builtin_bit_cast(unsigned, b); }
; __device__ __forceinline__ float fast_sigmoid(float x) { return __builtin_amdgcn_rcpf(1.0f + __expf(-x)); }
; __device__ __forceinline__ float bf_lo(unsigned w) { return __uint_as_float(w << 16); }
; __device__ __forceinline__ float bf_hi(unsigned w) { return __uint_as_float(w & 0xffff0000u); }
;     __device__ __forceinline__ void operator()(const f32x4 (&acc)[2][2][4][2], const Unit& u, int wr, int wc, int fr, int fq) const {
;     ...
;                     const u32x4 gw = *(const u32x4*)(GG + row * 2048 + goff + col0 + bj * HALF);
;                     f32x4 v0, v1;
;                     v0[0] = fast_sigmoid(bf_lo(gw.x)) * acc[ai][bj][m][0][0]; v0[1] = fast_sigmoid(bf_hi(gw.x)) * acc[ai][bj][m][0][1];
;                     v0[2] = fast_sigmoid(bf_lo(gw.y)) * acc[ai][bj][m][0][2]; v0[3] = fast_sigmoid(bf_hi(gw.y)) * acc[ai][bj][m][0][3];
;                     v1[0] = fast_sigmoid(bf_lo(gw.z)) * acc[ai][bj][m][1][0]; v1[1] = fast_sigmoid(bf_hi(gw.z)) * acc[ai][bj][m][1][1];
;                     v1[2] = fast_sigmoid(bf_lo(gw.w)) * acc[ai][bj][m][1][2]; v1[3] = fast_sigmoid(bf_hi(gw.w)) * acc[ai][bj][m][1][3];
;                     bf16_t* tp = TMP + row * 1024 + col0 + bj * HALF;
;                     if (MODE == 1) { const u32x4 tw = *(const u32x4*)tp;
;                         v0 += (f32x4){bf_lo(tw.x), bf_hi(tw.x), bf_lo(tw.y), bf_hi(tw.y)}; v1 += (f32x4){bf_lo(tw.z), bf_hi(tw.z), bf_lo(tw.w), bf_hi(tw.w)}; }
;                     u32x4 w; w.x = cvt_pk_bf16(v0[0], v0[1]); w.y = cvt_pk_bf16(v0[2], v0[3]); w.z = cvt_pk_bf16(v1[0], v1[1]); w.w = cvt_pk_bf16(v1[2], v1[3]);
;                     *(u32x4*)((MODE == 0 ? tp : MIX + row * 1024 + col0 + bj * HALF)) = w;
.LBB0_793:
	v_lshl_add_u32 v154, s7, 8, v150
	v_mov_b32_e32 v160, v154
	v_lshl_or_b32 v148, s6, 8, v152
	v_ashrrev_i32_e32 v149, 31, v148
	v_ashrrev_i32_e32 v161, 31, v160
	v_lshlrev_b64 v[156:157], 12, v[160:161]
	v_lshl_add_u64 v[156:157], s[16:17], 0, v[156:157]
	v_lshlrev_b64 v[148:149], 1, v[148:149]
	v_lshl_add_u64 v[164:165], v[156:157], 0, v[148:149]
	global_load_dwordx4 v[210:213], v[164:165], off offset:2048
	v_lshlrev_b64 v[184:185], 11, v[160:161]
	v_lshl_add_u64 v[186:187], s[18:19], 0, v[184:185]
	v_lshl_add_u64 v[188:189], v[186:187], 0, v[148:149]
	global_load_dwordx4 v[214:217], v[188:189], off
	global_load_dwordx4 v[218:221], v[164:165], off offset:2304
	v_lshlrev_b64 v[184:185], 11, v[160:161]
	v_lshl_add_u64 v[186:187], s[18:19], 0, v[184:185]
	v_lshl_add_u64 v[188:189], v[186:187], 0, v[148:149]
	global_load_dwordx4 v[222:225], v[188:189], off offset:256
	v_or_b32_e32 v184, 16, v154
	v_ashrrev_i32_e32 v185, 31, v184
	v_lshlrev_b64 v[186:187], 12, v[184:185]
	v_lshl_add_u64 v[186:187], s[16:17], 0, v[186:187]
	v_lshl_add_u64 v[188:189], v[186:187], 0, v[148:149]
	global_load_dwordx4 v[226:229], v[188:189], off offset:2048
	v_or_b32_e32 v184, 16, v154
	v_ashrrev_i32_e32 v185, 31, v184
	v_lshlrev_b64 v[186:187], 11, v[184:185]
	v_lshl_add_u64 v[188:189], s[18:19], 0, v[186:187]
	v_lshl_add_u64 v[190:191], v[188:189], 0, v[148:149]
	global_load_dwordx4 v[230:233], v[190:191], off
	v_lshlrev_b64 v[166:167], 11, v[160:161]
	v_lshl_add_u64 v[160:161], s[18:19], 0, v[166:167]
	v_lshl_add_u64 v[168:169], v[160:161], 0, v[148:149]
	v_lshl_add_u64 v[166:167], s[20:21], 0, v[166:167]
	v_lshl_add_u64 v[166:167], v[166:167], 0, v[148:149]
	s_andn2_b64 vcc, exec, s[10:11]
	s_mov_b64 s[6:7], -1
	s_waitcnt vmcnt(4)
	v_lshlrev_b32_e32 v155, 16, v210
	v_and_b32_e32 v170, 0xffff0000, v210
	v_lshlrev_b32_e32 v171, 16, v211
	v_and_b32_e32 v172, 0xffff0000, v211
	v_lshlrev_b32_e32 v173, 16, v212
	v_and_b32_e32 v174, 0xffff0000, v212
	v_lshlrev_b32_e32 v175, 16, v213
	v_and_b32_e32 v176, 0xffff0000, v213
	v_or_b32_e32 v184, 16, v154
	v_ashrrev_i32_e32 v185, 31, v184
	v_lshlrev_b64 v[186:187], 12, v[184:185]
	v_lshl_add_u64 v[186:187], s[16:17], 0, v[186:187]
	v_lshl_add_u64 v[188:189], v[186:187], 0, v[148:149]
	global_load_dwordx4 v[210:213], v[188:189], off offset:2304
	v_mul_f32_e32 v155, 0xbfb8aa3b, v155
	v_mul_f32_e32 v170, 0xbfb8aa3b, v170
	v_mul_f32_e32 v171, 0xbfb8aa3b, v171
	v_mul_f32_e32 v172, 0xbfb8aa3b, v172
	v_mul_f32_e32 v173, 0xbfb8aa3b, v173
	v_mul_f32_e32 v174, 0xbfb8aa3b, v174
	v_mul_f32_e32 v175, 0xbfb8aa3b, v175
	v_mul_f32_e32 v176, 0xbfb8aa3b, v176
	v_exp_f32_e32 v155, v155
	v_exp_f32_e32 v170, v170
	v_exp_f32_e32 v171, v171
	v_exp_f32_e32 v172, v172
	v_exp_f32_e32 v173, v173
	v_exp_f32_e32 v174, v174
	v_exp_f32_e32 v175, v175
	v_exp_f32_e32 v176, v176
	v_add_f32_e32 v155, 1.0, v155
	v_add_f32_e32 v177, 1.0, v170
	v_add_f32_e32 v178, 1.0, v171
	v_add_f32_e32 v179, 1.0, v172
	v_add_f32_e32 v180, 1.0, v173
	v_add_f32_e32 v182, 1.0, v174
	v_add_f32_e32 v175, 1.0, v175
	v_add_f32_e32 v183, 1.0, v176
	v_rcp_f32_e32 v170, v155
	v_rcp_f32_e32 v171, v177
	v_rcp_f32_e32 v172, v178
	v_rcp_f32_e32 v173, v179
	v_rcp_f32_e32 v174, v180
	v_rcp_f32_e32 v176, v175
	v_rcp_f32_e32 v177, v183
	v_rcp_f32_e32 v175, v182
	v_lshlrev_b32_e32 v156, 16, v214
	v_and_b32_e32 v157, 0xffff0000, v214
	v_lshlrev_b32_e32 v158, 16, v215
	v_and_b32_e32 v159, 0xffff0000, v215
	v_lshlrev_b32_e32 v160, 16, v216
	v_and_b32_e32 v161, 0xffff0000, v216
	v_lshlrev_b32_e32 v162, 16, v217
	v_and_b32_e32 v163, 0xffff0000, v217
	v_or_b32_e32 v184, 16, v154
	v_ashrrev_i32_e32 v185, 31, v184
	v_lshlrev_b64 v[186:187], 11, v[184:185]
	v_lshl_add_u64 v[188:189], s[18:19], 0, v[186:187]
	v_lshl_add_u64 v[190:191], v[188:189], 0, v[148:149]
	global_load_dwordx4 v[214:217], v[190:191], off offset:256
	v_pk_fma_f32 v[130:131], v[130:131], v[172:173], v[158:159]
	v_pk_fma_f32 v[128:129], v[128:129], v[170:171], v[156:157]
	v_pk_fma_f32 v[156:157], v[126:127], v[176:177], v[162:163]
	v_pk_fma_f32 v[126:127], v[124:125], v[174:175], v[160:161]
	v_cvt_pk_bf16_f32 v124, v128, v129
	v_cvt_pk_bf16_f32 v125, v130, v131
	v_cvt_pk_bf16_f32 v126, v126, v127
	v_cvt_pk_bf16_f32 v127, v156, v157
	global_store_dwordx4 v[166:167], v[124:127], off
	s_nop 0
	v_or_b32_e32 v156, 16, v154
	s_waitcnt vmcnt(6)
	v_lshlrev_b32_e32 v155, 16, v218
	v_and_b32_e32 v157, 0xffff0000, v218
	v_lshlrev_b32_e32 v158, 16, v219
	v_and_b32_e32 v159, 0xffff0000, v219
	v_lshlrev_b32_e32 v160, 16, v220
	v_and_b32_e32 v161, 0xffff0000, v220
	v_lshlrev_b32_e32 v162, 16, v221
	v_and_b32_e32 v163, 0xffff0000, v221
	v_or_b32_e32 v184, 32, v154
	v_ashrrev_i32_e32 v185, 31, v184
	v_lshlrev_b64 v[186:187], 12, v[184:185]
	v_lshl_add_u64 v[186:187], s[16:17], 0, v[186:187]
	v_lshl_add_u64 v[188:189], v[186:187], 0, v[148:149]
	global_load_dwordx4 v[218:221], v[188:189], off offset:2048
	v_mul_f32_e32 v155, 0xbfb8aa3b, v155
	v_mul_f32_e32 v157, 0xbfb8aa3b, v157
	v_mul_f32_e32 v158, 0xbfb8aa3b, v158
	v_mul_f32_e32 v159, 0xbfb8aa3b, v159
	v_mul_f32_e32 v160, 0xbfb8aa3b, v160
	v_mul_f32_e32 v161, 0xbfb8aa3b, v161
	v_mul_f32_e32 v162, 0xbfb8aa3b, v162
	v_mul_f32_e32 v163, 0xbfb8aa3b, v163
	v_exp_f32_e32 v155, v155
	v_exp_f32_e32 v157, v157
	v_exp_f32_e32 v158, v158
	v_exp_f32_e32 v159, v159
	v_exp_f32_e32 v160, v160
	v_exp_f32_e32 v161, v161
	v_exp_f32_e32 v162, v162
	v_exp_f32_e32 v163, v163
	v_add_f32_e32 v155, 1.0, v155
	v_add_f32_e32 v157, 1.0, v157
	v_add_f32_e32 v164, 1.0, v158
	v_add_f32_e32 v165, 1.0, v159
	v_add_f32_e32 v168, 1.0, v160
	v_add_f32_e32 v169, 1.0, v161
	v_add_f32_e32 v170, 1.0, v162
	v_add_f32_e32 v163, 1.0, v163
	v_rcp_f32_e32 v158, v155
	v_rcp_f32_e32 v159, v157
	v_rcp_f32_e32 v160, v164
	v_rcp_f32_e32 v161, v165
	v_rcp_f32_e32 v162, v168
	v_rcp_f32_e32 v164, v170
	v_rcp_f32_e32 v165, v163
	v_rcp_f32_e32 v163, v169
	s_waitcnt vmcnt(6)
; __device__ __forceinline__ unsigned cvt_pk_bf16(float lo, float hi) { f32x2_cv v = {lo, hi}; bf16x2_cv b = __builtin_convertvector(v, bf16x2_cv); return __builtin_bit_cast(unsigned, b); }
; __device__ __forceinline__ float fast_sigmoid(float x) { return __builtin_amdgcn_rcpf(1.0f + __expf(-x)); }
; __device__ __forceinline__ float bf_lo(unsigned w) { return __uint_as_float(w << 16); }
; __device__ __forceinline__ float bf_hi(unsigned w) { return __uint_as_float(w & 0xffff0000u); }
;     __device__ __forceinline__ void operator()(const f32x4 (&acc)[2][2][4][2], const Unit& u, int wr, int wc, int fr, int fq) const {
;     ...
;                 int rowi = lrow0 + ai * HALF + m * 16; asm volatile("" : "+v"(rowi)); const size_t row = (size_t)rowi;
; #pragma unroll
;                 for (int bj = 0; bj < 2; ++bj) {
;                     const u32x4 gw = *(const u32x4*)(GG + row * 2048 + goff + col0 + bj * HALF);
;                     f32x4 v0, v1;
;                     v0[0] = fast_sigmoid(bf_lo(gw.x)) * acc[ai][bj][m][0][0]; v0[1] = fast_sigmoid(bf_hi(gw.x)) * acc[ai][bj][m][0][1];
;                     v0[2] = fast_sigmoid(bf_lo(gw.y)) * acc[ai][bj][m][0][2]; v0[3] = fast_sigmoid(bf_hi(gw.y)) * acc[ai][bj][m][0][3];
;                     v1[0] = fast_sigmoid(bf_lo(gw.z)) * acc[ai][bj][m][1][0]; v1[1] = fast_sigmoid(bf_hi(gw.z)) * acc[ai][bj][m][1][1];
;                     v1[2] = fast_sigmoid(bf_lo(gw.w)) * acc[ai][bj][m][1][2]; v1[3] = fast_sigmoid(bf_hi(gw.w)) * acc[ai][bj][m][1][3];
;                     bf16_t* tp = TMP + row * 1024 + col0 + bj * HALF;
;                     if (MODE == 1) { const u32x4 tw = *(const u32x4*)tp;
;                         v0 += (f32x4){bf_lo(tw.x), bf_hi(tw.x), bf_lo(tw.y), bf_hi(tw.y)}; v1 += (f32x4){bf_lo(tw.z), bf_hi(tw.z), bf_lo(tw.w), bf_hi(tw.w)}; }
;                     u32x4 w; w.x = cvt_pk_bf16(v0[0], v0[1]); w.y = cvt_pk_bf16(v0[2], v0[3]); w.z = cvt_pk_bf16(v1[0], v1[1]); w.w = cvt_pk_bf16(v1[2], v1[3]);
;                     *(u32x4*)((MODE == 0 ? tp : MIX + row * 1024 + col0 + bj * HALF)) = w;
	v_lshlrev_b32_e32 v124, 16, v222
	v_and_b32_e32 v125, 0xffff0000, v222
	v_lshlrev_b32_e32 v126, 16, v223
	v_and_b32_e32 v127, 0xffff0000, v223
	v_lshlrev_b32_e32 v128, 16, v224
	v_and_b32_e32 v129, 0xffff0000, v224
	v_lshlrev_b32_e32 v130, 16, v225
	v_and_b32_e32 v131, 0xffff0000, v225
	v_or_b32_e32 v184, 32, v154
	v_ashrrev_i32_e32 v185, 31, v184
	v_lshlrev_b64 v[186:187], 11, v[184:185]
	v_lshl_add_u64 v[188:189], s[18:19], 0, v[186:187]
	v_lshl_add_u64 v[190:191], v[188:189], 0, v[148:149]
	global_load_dwordx4 v[222:225], v[190:191], off
	v_pk_fma_f32 v[122:123], v[122:123], v[160:161], v[126:127]
	v_pk_fma_f32 v[120:121], v[120:121], v[158:159], v[124:125]
	v_pk_fma_f32 v[124:125], v[118:119], v[164:165], v[130:131]
	v_pk_fma_f32 v[118:119], v[116:117], v[162:163], v[128:129]
	v_cvt_pk_bf16_f32 v116, v120, v121
	v_cvt_pk_bf16_f32 v117, v122, v123
	v_cvt_pk_bf16_f32 v118, v118, v119
	v_cvt_pk_bf16_f32 v119, v124, v125
	global_store_dwordx4 v[166:167], v[116:119], off offset:256
	s_nop 0
	v_ashrrev_i32_e32 v157, 31, v156
	v_lshlrev_b64 v[116:117], 12, v[156:157]
	v_lshl_add_u64 v[116:117], s[16:17], 0, v[116:117]
	v_lshl_add_u64 v[124:125], v[116:117], 0, v[148:149]
	v_lshlrev_b64 v[126:127], 11, v[156:157]
	v_lshl_add_u64 v[120:121], s[18:19], 0, v[126:127]
	v_lshl_add_u64 v[128:129], v[120:121], 0, v[148:149]
	v_lshl_add_u64 v[126:127], s[20:21], 0, v[126:127]
	v_lshl_add_u64 v[126:127], v[126:127], 0, v[148:149]
	s_waitcnt vmcnt(7)
	v_lshlrev_b32_e32 v130, 16, v226
	v_and_b32_e32 v131, 0xffff0000, v226
	v_lshlrev_b32_e32 v155, 16, v227
	v_and_b32_e32 v156, 0xffff0000, v227
	v_lshlrev_b32_e32 v157, 16, v228
	v_and_b32_e32 v158, 0xffff0000, v228
	v_lshlrev_b32_e32 v159, 16, v229
	v_and_b32_e32 v160, 0xffff0000, v229
	v_or_b32_e32 v184, 32, v154
	v_ashrrev_i32_e32 v185, 31, v184
	v_lshlrev_b64 v[186:187], 12, v[184:185]
	v_lshl_add_u64 v[186:187], s[16:17], 0, v[186:187]
	v_lshl_add_u64 v[188:189], v[186:187], 0, v[148:149]
	global_load_dwordx4 v[226:229], v[188:189], off offset:2304
	v_mul_f32_e32 v130, 0xbfb8aa3b, v130
	v_mul_f32_e32 v131, 0xbfb8aa3b, v131
	v_mul_f32_e32 v155, 0xbfb8aa3b, v155
	v_mul_f32_e32 v156, 0xbfb8aa3b, v156
	v_mul_f32_e32 v157, 0xbfb8aa3b, v157
	v_mul_f32_e32 v158, 0xbfb8aa3b, v158
	v_mul_f32_e32 v159, 0xbfb8aa3b, v159
	v_mul_f32_e32 v160, 0xbfb8aa3b, v160
	v_exp_f32_e32 v130, v130
	v_exp_f32_e32 v131, v131
	v_exp_f32_e32 v155, v155
	v_exp_f32_e32 v156, v156
	v_exp_f32_e32 v157, v157
	v_exp_f32_e32 v158, v158
	v_exp_f32_e32 v159, v159
	v_exp_f32_e32 v160, v160
	v_add_f32_e32 v130, 1.0, v130
	v_add_f32_e32 v131, 1.0, v131
	v_add_f32_e32 v155, 1.0, v155
	v_add_f32_e32 v161, 1.0, v156
	v_add_f32_e32 v162, 1.0, v157
	v_add_f32_e32 v163, 1.0, v158
	v_add_f32_e32 v159, 1.0, v159
	v_add_f32_e32 v164, 1.0, v160
	v_rcp_f32_e32 v130, v130
	v_rcp_f32_e32 v131, v131
	v_rcp_f32_e32 v156, v155
	v_rcp_f32_e32 v157, v161
	v_rcp_f32_e32 v158, v162
	v_rcp_f32_e32 v160, v159
	v_rcp_f32_e32 v161, v164
	v_rcp_f32_e32 v159, v163
	s_waitcnt vmcnt(7)
	v_lshlrev_b32_e32 v116, 16, v230
	v_and_b32_e32 v117, 0xffff0000, v230
	v_lshlrev_b32_e32 v118, 16, v231
	v_and_b32_e32 v119, 0xffff0000, v231
	v_lshlrev_b32_e32 v120, 16, v232
	v_and_b32_e32 v121, 0xffff0000, v232
	v_lshlrev_b32_e32 v122, 16, v233
	v_and_b32_e32 v123, 0xffff0000, v233
	v_or_b32_e32 v184, 32, v154
	v_ashrrev_i32_e32 v185, 31, v184
	v_lshlrev_b64 v[186:187], 11, v[184:185]
	v_lshl_add_u64 v[188:189], s[18:19], 0, v[186:187]
	v_lshl_add_u64 v[190:191], v[188:189], 0, v[148:149]
	global_load_dwordx4 v[230:233], v[190:191], off offset:256
	v_pk_fma_f32 v[114:115], v[114:115], v[156:157], v[118:119]
	v_pk_fma_f32 v[112:113], v[112:113], v[130:131], v[116:117]
	v_pk_fma_f32 v[116:117], v[110:111], v[160:161], v[122:123]
	v_pk_fma_f32 v[110:111], v[108:109], v[158:159], v[120:121]
	v_cvt_pk_bf16_f32 v108, v112, v113
	v_cvt_pk_bf16_f32 v109, v114, v115
	v_cvt_pk_bf16_f32 v110, v110, v111
	v_cvt_pk_bf16_f32 v111, v116, v117
	global_store_dwordx4 v[126:127], v[108:111], off
	s_nop 0
	v_or_b32_e32 v116, 32, v154
	s_waitcnt vmcnt(8)
	v_lshlrev_b32_e32 v117, 16, v210
	v_and_b32_e32 v118, 0xffff0000, v210
	v_lshlrev_b32_e32 v119, 16, v211
	v_and_b32_e32 v120, 0xffff0000, v211
	v_lshlrev_b32_e32 v121, 16, v212
	v_and_b32_e32 v122, 0xffff0000, v212
	v_lshlrev_b32_e32 v123, 16, v213
	v_and_b32_e32 v124, 0xffff0000, v213
	v_or_b32_e32 v184, 48, v154
	v_ashrrev_i32_e32 v185, 31, v184
	v_lshlrev_b64 v[186:187], 12, v[184:185]
	v_lshl_add_u64 v[186:187], s[16:17], 0, v[186:187]
	v_lshl_add_u64 v[188:189], v[186:187], 0, v[148:149]
	global_load_dwordx4 v[210:213], v[188:189], off offset:2048
	v_mul_f32_e32 v117, 0xbfb8aa3b, v117
	v_mul_f32_e32 v118, 0xbfb8aa3b, v118
	v_mul_f32_e32 v119, 0xbfb8aa3b, v119
	v_mul_f32_e32 v120, 0xbfb8aa3b, v120
	v_mul_f32_e32 v121, 0xbfb8aa3b, v121
	v_mul_f32_e32 v122, 0xbfb8aa3b, v122
	v_mul_f32_e32 v123, 0xbfb8aa3b, v123
	v_mul_f32_e32 v124, 0xbfb8aa3b, v124
	v_exp_f32_e32 v117, v117
	v_exp_f32_e32 v118, v118
	v_exp_f32_e32 v119, v119
	v_exp_f32_e32 v120, v120
	v_exp_f32_e32 v121, v121
	v_exp_f32_e32 v122, v122
	v_exp_f32_e32 v123, v123
	v_exp_f32_e32 v124, v124
	v_add_f32_e32 v117, 1.0, v117
	v_add_f32_e32 v125, 1.0, v118
	v_add_f32_e32 v128, 1.0, v119
	v_add_f32_e32 v129, 1.0, v120
	v_add_f32_e32 v130, 1.0, v121
	v_add_f32_e32 v131, 1.0, v122
	v_add_f32_e32 v123, 1.0, v123
	v_add_f32_e32 v155, 1.0, v124
	v_rcp_f32_e32 v118, v117
	v_rcp_f32_e32 v119, v125
	v_rcp_f32_e32 v120, v128
	v_rcp_f32_e32 v121, v129
	v_rcp_f32_e32 v122, v130
	v_rcp_f32_e32 v124, v123
	v_rcp_f32_e32 v125, v155
	v_rcp_f32_e32 v123, v131
	s_waitcnt vmcnt(8)
; __device__ __forceinline__ unsigned cvt_pk_bf16(float lo, float hi) { f32x2_cv v = {lo, hi}; bf16x2_cv b = __builtin_convertvector(v, bf16x2_cv); return __builtin_bit_cast(unsigned, b); }
; __device__ __forceinline__ float fast_sigmoid(float x) { return __builtin_amdgcn_rcpf(1.0f + __expf(-x)); }
; __device__ __forceinline__ float bf_lo(unsigned w) { return __uint_as_float(w << 16); }
; __device__ __forceinline__ float bf_hi(unsigned w) { return __uint_as_float(w & 0xffff0000u); }
;     __device__ __forceinline__ void operator()(const f32x4 (&acc)[2][2][4][2], const Unit& u, int wr, int wc, int fr, int fq) const {
;     ...
;                 int rowi = lrow0 + ai * HALF + m * 16; asm volatile("" : "+v"(rowi)); const size_t row = (size_t)rowi;
; #pragma unroll
;                 for (int bj = 0; bj < 2; ++bj) {
;                     const u32x4 gw = *(const u32x4*)(GG + row * 2048 + goff + col0 + bj * HALF);
;                     f32x4 v0, v1;
;                     v0[0] = fast_sigmoid(bf_lo(gw.x)) * acc[ai][bj][m][0][0]; v0[1] = fast_sigmoid(bf_hi(gw.x)) * acc[ai][bj][m][0][1];
;                     v0[2] = fast_sigmoid(bf_lo(gw.y)) * acc[ai][bj][m][0][2]; v0[3] = fast_sigmoid(bf_hi(gw.y)) * acc[ai][bj][m][0][3];
;                     v1[0] = fast_sigmoid(bf_lo(gw.z)) * acc[ai][bj][m][1][0]; v1[1] = fast_sigmoid(bf_hi(gw.z)) * acc[ai][bj][m][1][1];
;                     v1[2] = fast_sigmoid(bf_lo(gw.w)) * acc[ai][bj][m][1][2]; v1[3] = fast_sigmoid(bf_hi(gw.w)) * acc[ai][bj][m][1][3];
;                     bf16_t* tp = TMP + row * 1024 + col0 + bj * HALF;
;                     if (MODE == 1) { const u32x4 tw = *(const u32x4*)tp;
;                         v0 += (f32x4){bf_lo(tw.x), bf_hi(tw.x), bf_lo(tw.y), bf_hi(tw.y)}; v1 += (f32x4){bf_lo(tw.z), bf_hi(tw.z), bf_lo(tw.w), bf_hi(tw.w)}; }
;                     u32x4 w; w.x = cvt_pk_bf16(v0[0], v0[1]); w.y = cvt_pk_bf16(v0[2], v0[3]); w.z = cvt_pk_bf16(v1[0], v1[1]); w.w = cvt_pk_bf16(v1[2], v1[3]);
;                     *(u32x4*)((MODE == 0 ? tp : MIX + row * 1024 + col0 + bj * HALF)) = w;
	v_lshlrev_b32_e32 v108, 16, v214
	v_and_b32_e32 v109, 0xffff0000, v214
	v_lshlrev_b32_e32 v110, 16, v215
	v_and_b32_e32 v111, 0xffff0000, v215
	v_lshlrev_b32_e32 v112, 16, v216
	v_and_b32_e32 v113, 0xffff0000, v216
	v_lshlrev_b32_e32 v114, 16, v217
	v_and_b32_e32 v115, 0xffff0000, v217
	v_or_b32_e32 v184, 48, v154
	v_ashrrev_i32_e32 v185, 31, v184
	v_lshlrev_b64 v[186:187], 11, v[184:185]
	v_lshl_add_u64 v[188:189], s[18:19], 0, v[186:187]
	v_lshl_add_u64 v[190:191], v[188:189], 0, v[148:149]
	global_load_dwordx4 v[214:217], v[190:191], off
	v_pk_fma_f32 v[106:107], v[106:107], v[120:121], v[110:111]
	v_pk_fma_f32 v[104:105], v[104:105], v[118:119], v[108:109]
	v_pk_fma_f32 v[108:109], v[102:103], v[124:125], v[114:115]
	v_pk_fma_f32 v[102:103], v[100:101], v[122:123], v[112:113]
	v_cvt_pk_bf16_f32 v100, v104, v105
	v_cvt_pk_bf16_f32 v101, v106, v107
	v_cvt_pk_bf16_f32 v102, v102, v103
	v_cvt_pk_bf16_f32 v103, v108, v109
	global_store_dwordx4 v[126:127], v[100:103], off offset:256
	s_nop 0
	v_ashrrev_i32_e32 v117, 31, v116
	v_lshlrev_b64 v[100:101], 12, v[116:117]
	v_lshl_add_u64 v[100:101], s[16:17], 0, v[100:101]
	v_lshl_add_u64 v[108:109], v[100:101], 0, v[148:149]
	v_lshlrev_b64 v[110:111], 11, v[116:117]
	v_lshl_add_u64 v[104:105], s[18:19], 0, v[110:111]
	v_lshl_add_u64 v[112:113], v[104:105], 0, v[148:149]
	v_lshl_add_u64 v[110:111], s[20:21], 0, v[110:111]
	v_lshl_add_u64 v[110:111], v[110:111], 0, v[148:149]
	s_waitcnt vmcnt(8)
	v_lshlrev_b32_e32 v114, 16, v218
	v_and_b32_e32 v115, 0xffff0000, v218
	v_lshlrev_b32_e32 v116, 16, v219
	v_and_b32_e32 v117, 0xffff0000, v219
	v_lshlrev_b32_e32 v118, 16, v220
	v_and_b32_e32 v119, 0xffff0000, v220
	v_lshlrev_b32_e32 v120, 16, v221
	v_and_b32_e32 v121, 0xffff0000, v221
	v_or_b32_e32 v184, 48, v154
	v_ashrrev_i32_e32 v185, 31, v184
	v_lshlrev_b64 v[186:187], 12, v[184:185]
	v_lshl_add_u64 v[186:187], s[16:17], 0, v[186:187]
	v_lshl_add_u64 v[188:189], v[186:187], 0, v[148:149]
	global_load_dwordx4 v[218:221], v[188:189], off offset:2304
	v_mul_f32_e32 v114, 0xbfb8aa3b, v114
	v_mul_f32_e32 v115, 0xbfb8aa3b, v115
	v_mul_f32_e32 v116, 0xbfb8aa3b, v116
	v_mul_f32_e32 v117, 0xbfb8aa3b, v117
	v_mul_f32_e32 v118, 0xbfb8aa3b, v118
	v_mul_f32_e32 v119, 0xbfb8aa3b, v119
	v_mul_f32_e32 v120, 0xbfb8aa3b, v120
	v_mul_f32_e32 v121, 0xbfb8aa3b, v121
	v_exp_f32_e32 v114, v114
	v_exp_f32_e32 v115, v115
	v_exp_f32_e32 v116, v116
	v_exp_f32_e32 v117, v117
	v_exp_f32_e32 v118, v118
	v_exp_f32_e32 v119, v119
	v_exp_f32_e32 v120, v120
	v_exp_f32_e32 v121, v121
	v_add_f32_e32 v114, 1.0, v114
	v_add_f32_e32 v115, 1.0, v115
	v_add_f32_e32 v116, 1.0, v116
	v_add_f32_e32 v117, 1.0, v117
	v_add_f32_e32 v118, 1.0, v118
	v_add_f32_e32 v119, 1.0, v119
	v_add_f32_e32 v120, 1.0, v120
	v_add_f32_e32 v121, 1.0, v121
	v_rcp_f32_e32 v114, v114
	v_rcp_f32_e32 v115, v115
	v_rcp_f32_e32 v116, v116
	v_rcp_f32_e32 v117, v117
	v_rcp_f32_e32 v118, v118
	v_rcp_f32_e32 v120, v120
	v_rcp_f32_e32 v121, v121
	v_rcp_f32_e32 v119, v119
	s_waitcnt vmcnt(8)
	v_lshlrev_b32_e32 v100, 16, v222
	v_and_b32_e32 v101, 0xffff0000, v222
	v_lshlrev_b32_e32 v102, 16, v223
	v_and_b32_e32 v103, 0xffff0000, v223
	v_lshlrev_b32_e32 v104, 16, v224
	v_and_b32_e32 v105, 0xffff0000, v224
	v_lshlrev_b32_e32 v106, 16, v225
	v_and_b32_e32 v107, 0xffff0000, v225
	v_or_b32_e32 v184, 48, v154
	v_ashrrev_i32_e32 v185, 31, v184
	v_lshlrev_b64 v[186:187], 11, v[184:185]
	v_lshl_add_u64 v[188:189], s[18:19], 0, v[186:187]
	v_lshl_add_u64 v[190:191], v[188:189], 0, v[148:149]
	global_load_dwordx4 v[222:225], v[190:191], off offset:256
	v_pk_fma_f32 v[98:99], v[98:99], v[116:117], v[102:103]
	v_pk_fma_f32 v[96:97], v[96:97], v[114:115], v[100:101]
	v_pk_fma_f32 v[100:101], v[94:95], v[120:121], v[106:107]
	v_pk_fma_f32 v[94:95], v[92:93], v[118:119], v[104:105]
	v_cvt_pk_bf16_f32 v92, v96, v97
	v_cvt_pk_bf16_f32 v93, v98, v99
	v_cvt_pk_bf16_f32 v94, v94, v95
	v_cvt_pk_bf16_f32 v95, v100, v101
	global_store_dwordx4 v[110:111], v[92:95], off
	s_nop 0
	v_or_b32_e32 v100, 48, v154
	s_waitcnt vmcnt(8)
	v_lshlrev_b32_e32 v101, 16, v226
	v_and_b32_e32 v102, 0xffff0000, v226
	v_lshlrev_b32_e32 v103, 16, v227
	v_and_b32_e32 v104, 0xffff0000, v227
	v_lshlrev_b32_e32 v105, 16, v228
	v_and_b32_e32 v106, 0xffff0000, v228
	v_lshlrev_b32_e32 v107, 16, v229
	v_and_b32_e32 v108, 0xffff0000, v229
	v_add_u32_e32 v184, 0x80, v154
	v_ashrrev_i32_e32 v185, 31, v184
	v_lshlrev_b64 v[186:187], 12, v[184:185]
	v_lshl_add_u64 v[186:187], s[16:17], 0, v[186:187]
	v_lshl_add_u64 v[188:189], v[186:187], 0, v[148:149]
	global_load_dwordx4 v[226:229], v[188:189], off offset:2048
	v_mul_f32_e32 v101, 0xbfb8aa3b, v101
	v_mul_f32_e32 v102, 0xbfb8aa3b, v102
	v_mul_f32_e32 v103, 0xbfb8aa3b, v103
	v_mul_f32_e32 v104, 0xbfb8aa3b, v104
	v_mul_f32_e32 v105, 0xbfb8aa3b, v105
	v_mul_f32_e32 v106, 0xbfb8aa3b, v106
	v_mul_f32_e32 v107, 0xbfb8aa3b, v107
	v_mul_f32_e32 v108, 0xbfb8aa3b, v108
	v_exp_f32_e32 v101, v101
	v_exp_f32_e32 v102, v102
	v_exp_f32_e32 v103, v103
	v_exp_f32_e32 v104, v104
	v_exp_f32_e32 v105, v105
	v_exp_f32_e32 v106, v106
	v_exp_f32_e32 v107, v107
	v_exp_f32_e32 v108, v108
	v_add_f32_e32 v101, 1.0, v101
	v_add_f32_e32 v109, 1.0, v102
	v_add_f32_e32 v112, 1.0, v103
	v_add_f32_e32 v113, 1.0, v104
	v_add_f32_e32 v114, 1.0, v105
	v_add_f32_e32 v115, 1.0, v106
	v_add_f32_e32 v107, 1.0, v107
	v_add_f32_e32 v116, 1.0, v108
	v_rcp_f32_e32 v102, v101
	v_rcp_f32_e32 v103, v109
	v_rcp_f32_e32 v104, v112
	v_rcp_f32_e32 v105, v113
	v_rcp_f32_e32 v106, v114
	v_rcp_f32_e32 v108, v107
	v_rcp_f32_e32 v109, v116
	v_rcp_f32_e32 v107, v115
	s_waitcnt vmcnt(8)
; __device__ __forceinline__ unsigned cvt_pk_bf16(float lo, float hi) { f32x2_cv v = {lo, hi}; bf16x2_cv b = __builtin_convertvector(v, bf16x2_cv); return __builtin_bit_cast(unsigned, b); }
; __device__ __forceinline__ float fast_sigmoid(float x) { return __builtin_amdgcn_rcpf(1.0f + __expf(-x)); }
; __device__ __forceinline__ float bf_lo(unsigned w) { return __uint_as_float(w << 16); }
; __device__ __forceinline__ float bf_hi(unsigned w) { return __uint_as_float(w & 0xffff0000u); }
;     __device__ __forceinline__ void operator()(const f32x4 (&acc)[2][2][4][2], const Unit& u, int wr, int wc, int fr, int fq) const {
;     ...
;                 int rowi = lrow0 + ai * HALF + m * 16; asm volatile("" : "+v"(rowi)); const size_t row = (size_t)rowi;
; #pragma unroll
;                 for (int bj = 0; bj < 2; ++bj) {
;                     const u32x4 gw = *(const u32x4*)(GG + row * 2048 + goff + col0 + bj * HALF);
;                     f32x4 v0, v1;
;                     v0[0] = fast_sigmoid(bf_lo(gw.x)) * acc[ai][bj][m][0][0]; v0[1] = fast_sigmoid(bf_hi(gw.x)) * acc[ai][bj][m][0][1];
;                     v0[2] = fast_sigmoid(bf_lo(gw.y)) * acc[ai][bj][m][0][2]; v0[3] = fast_sigmoid(bf_hi(gw.y)) * acc[ai][bj][m][0][3];
;                     v1[0] = fast_sigmoid(bf_lo(gw.z)) * acc[ai][bj][m][1][0]; v1[1] = fast_sigmoid(bf_hi(gw.z)) * acc[ai][bj][m][1][1];
;                     v1[2] = fast_sigmoid(bf_lo(gw.w)) * acc[ai][bj][m][1][2]; v1[3] = fast_sigmoid(bf_hi(gw.w)) * acc[ai][bj][m][1][3];
;                     bf16_t* tp = TMP + row * 1024 + col0 + bj * HALF;
;                     if (MODE == 1) { const u32x4 tw = *(const u32x4*)tp;
;                         v0 += (f32x4){bf_lo(tw.x), bf_hi(tw.x), bf_lo(tw.y), bf_hi(tw.y)}; v1 += (f32x4){bf_lo(tw.z), bf_hi(tw.z), bf_lo(tw.w), bf_hi(tw.w)}; }
;                     u32x4 w; w.x = cvt_pk_bf16(v0[0], v0[1]); w.y = cvt_pk_bf16(v0[2], v0[3]); w.z = cvt_pk_bf16(v1[0], v1[1]); w.w = cvt_pk_bf16(v1[2], v1[3]);
;                     *(u32x4*)((MODE == 0 ? tp : MIX + row * 1024 + col0 + bj * HALF)) = w;
	v_lshlrev_b32_e32 v92, 16, v230
	v_and_b32_e32 v93, 0xffff0000, v230
	v_lshlrev_b32_e32 v94, 16, v231
	v_and_b32_e32 v95, 0xffff0000, v231
	v_lshlrev_b32_e32 v96, 16, v232
	v_and_b32_e32 v97, 0xffff0000, v232
	v_lshlrev_b32_e32 v98, 16, v233
	v_and_b32_e32 v99, 0xffff0000, v233
	v_add_u32_e32 v184, 0x80, v154
	v_ashrrev_i32_e32 v185, 31, v184
	v_lshlrev_b64 v[186:187], 11, v[184:185]
	v_lshl_add_u64 v[188:189], s[18:19], 0, v[186:187]
	v_lshl_add_u64 v[190:191], v[188:189], 0, v[148:149]
	global_load_dwordx4 v[230:233], v[190:191], off
	v_pk_fma_f32 v[90:91], v[90:91], v[104:105], v[94:95]
	v_pk_fma_f32 v[88:89], v[88:89], v[102:103], v[92:93]
	v_pk_fma_f32 v[92:93], v[86:87], v[108:109], v[98:99]
	v_pk_fma_f32 v[86:87], v[84:85], v[106:107], v[96:97]
	v_cvt_pk_bf16_f32 v84, v88, v89
	v_cvt_pk_bf16_f32 v85, v90, v91
	v_cvt_pk_bf16_f32 v86, v86, v87
	v_cvt_pk_bf16_f32 v87, v92, v93
	global_store_dwordx4 v[110:111], v[84:87], off offset:256
	s_nop 0
	v_ashrrev_i32_e32 v101, 31, v100
	v_lshlrev_b64 v[84:85], 12, v[100:101]
	v_lshl_add_u64 v[84:85], s[16:17], 0, v[84:85]
	v_lshl_add_u64 v[92:93], v[84:85], 0, v[148:149]
	v_lshlrev_b64 v[94:95], 11, v[100:101]
	v_lshl_add_u64 v[88:89], s[18:19], 0, v[94:95]
	v_lshl_add_u64 v[96:97], v[88:89], 0, v[148:149]
	v_lshl_add_u64 v[94:95], s[20:21], 0, v[94:95]
	v_lshl_add_u64 v[94:95], v[94:95], 0, v[148:149]
	s_waitcnt vmcnt(8)
	v_lshlrev_b32_e32 v98, 16, v210
	v_and_b32_e32 v99, 0xffff0000, v210
	v_lshlrev_b32_e32 v100, 16, v211
	v_and_b32_e32 v101, 0xffff0000, v211
	v_lshlrev_b32_e32 v102, 16, v212
	v_and_b32_e32 v103, 0xffff0000, v212
	v_lshlrev_b32_e32 v104, 16, v213
	v_and_b32_e32 v105, 0xffff0000, v213
	v_add_u32_e32 v184, 0x80, v154
	v_ashrrev_i32_e32 v185, 31, v184
	v_lshlrev_b64 v[186:187], 12, v[184:185]
	v_lshl_add_u64 v[186:187], s[16:17], 0, v[186:187]
	v_lshl_add_u64 v[188:189], v[186:187], 0, v[148:149]
	global_load_dwordx4 v[210:213], v[188:189], off offset:2304
	v_mul_f32_e32 v98, 0xbfb8aa3b, v98
	v_mul_f32_e32 v99, 0xbfb8aa3b, v99
	v_mul_f32_e32 v100, 0xbfb8aa3b, v100
	v_mul_f32_e32 v101, 0xbfb8aa3b, v101
	v_mul_f32_e32 v102, 0xbfb8aa3b, v102
	v_mul_f32_e32 v103, 0xbfb8aa3b, v103
	v_mul_f32_e32 v104, 0xbfb8aa3b, v104
	v_mul_f32_e32 v105, 0xbfb8aa3b, v105
	v_exp_f32_e32 v98, v98
	v_exp_f32_e32 v99, v99
	v_exp_f32_e32 v100, v100
	v_exp_f32_e32 v101, v101
	v_exp_f32_e32 v102, v102
	v_exp_f32_e32 v103, v103
	v_exp_f32_e32 v104, v104
	v_exp_f32_e32 v105, v105
	v_add_f32_e32 v98, 1.0, v98
	v_add_f32_e32 v99, 1.0, v99
	v_add_f32_e32 v100, 1.0, v100
	v_add_f32_e32 v101, 1.0, v101
	v_add_f32_e32 v102, 1.0, v102
	v_add_f32_e32 v103, 1.0, v103
	v_add_f32_e32 v104, 1.0, v104
	v_add_f32_e32 v105, 1.0, v105
	v_rcp_f32_e32 v98, v98
	v_rcp_f32_e32 v99, v99
	v_rcp_f32_e32 v100, v100
	v_rcp_f32_e32 v101, v101
	v_rcp_f32_e32 v102, v102
	v_rcp_f32_e32 v104, v104
	v_rcp_f32_e32 v105, v105
	v_rcp_f32_e32 v103, v103
	s_waitcnt vmcnt(8)
	v_lshlrev_b32_e32 v84, 16, v214
	v_and_b32_e32 v85, 0xffff0000, v214
	v_lshlrev_b32_e32 v86, 16, v215
	v_and_b32_e32 v87, 0xffff0000, v215
	v_lshlrev_b32_e32 v88, 16, v216
	v_and_b32_e32 v89, 0xffff0000, v216
	v_lshlrev_b32_e32 v90, 16, v217
	v_and_b32_e32 v91, 0xffff0000, v217
	v_add_u32_e32 v184, 0x80, v154
	v_ashrrev_i32_e32 v185, 31, v184
	v_lshlrev_b64 v[186:187], 11, v[184:185]
	v_lshl_add_u64 v[188:189], s[18:19], 0, v[186:187]
	v_lshl_add_u64 v[190:191], v[188:189], 0, v[148:149]
	global_load_dwordx4 v[214:217], v[190:191], off offset:256
	v_pk_fma_f32 v[82:83], v[82:83], v[100:101], v[86:87]
	v_pk_fma_f32 v[80:81], v[80:81], v[98:99], v[84:85]
	v_pk_fma_f32 v[84:85], v[78:79], v[104:105], v[90:91]
	v_pk_fma_f32 v[78:79], v[76:77], v[102:103], v[88:89]
	v_cvt_pk_bf16_f32 v76, v80, v81
	v_cvt_pk_bf16_f32 v77, v82, v83
	v_cvt_pk_bf16_f32 v78, v78, v79
	v_cvt_pk_bf16_f32 v79, v84, v85
	global_store_dwordx4 v[94:95], v[76:79], off
	s_nop 0
	v_add_u32_e32 v84, 0x80, v154
	s_waitcnt vmcnt(8)
	v_lshlrev_b32_e32 v85, 16, v218
	v_and_b32_e32 v86, 0xffff0000, v218
	v_lshlrev_b32_e32 v87, 16, v219
	v_and_b32_e32 v88, 0xffff0000, v219
	v_lshlrev_b32_e32 v89, 16, v220
	v_and_b32_e32 v90, 0xffff0000, v220
	v_lshlrev_b32_e32 v91, 16, v221
	v_and_b32_e32 v92, 0xffff0000, v221
	v_add_u32_e32 v184, 0x90, v154
	v_ashrrev_i32_e32 v185, 31, v184
	v_lshlrev_b64 v[186:187], 12, v[184:185]
	v_lshl_add_u64 v[186:187], s[16:17], 0, v[186:187]
	v_lshl_add_u64 v[188:189], v[186:187], 0, v[148:149]
	global_load_dwordx4 v[218:221], v[188:189], off offset:2048
	v_mul_f32_e32 v85, 0xbfb8aa3b, v85
	v_mul_f32_e32 v86, 0xbfb8aa3b, v86
	v_mul_f32_e32 v87, 0xbfb8aa3b, v87
	v_mul_f32_e32 v88, 0xbfb8aa3b, v88
	v_mul_f32_e32 v89, 0xbfb8aa3b, v89
	v_mul_f32_e32 v90, 0xbfb8aa3b, v90
	v_mul_f32_e32 v91, 0xbfb8aa3b, v91
	v_mul_f32_e32 v92, 0xbfb8aa3b, v92
	v_exp_f32_e32 v85, v85
	v_exp_f32_e32 v86, v86
	v_exp_f32_e32 v87, v87
	v_exp_f32_e32 v88, v88
	v_exp_f32_e32 v89, v89
	v_exp_f32_e32 v90, v90
	v_exp_f32_e32 v91, v91
	v_exp_f32_e32 v92, v92
	v_add_f32_e32 v85, 1.0, v85
	v_add_f32_e32 v93, 1.0, v86
	v_add_f32_e32 v96, 1.0, v87
	v_add_f32_e32 v97, 1.0, v88
	v_add_f32_e32 v98, 1.0, v89
	v_add_f32_e32 v99, 1.0, v90
	v_add_f32_e32 v91, 1.0, v91
	v_add_f32_e32 v100, 1.0, v92
	v_rcp_f32_e32 v86, v85
	v_rcp_f32_e32 v87, v93
	v_rcp_f32_e32 v88, v96
	v_rcp_f32_e32 v89, v97
	v_rcp_f32_e32 v90, v98
	v_rcp_f32_e32 v92, v91
	v_rcp_f32_e32 v93, v100
	v_rcp_f32_e32 v91, v99
	s_waitcnt vmcnt(8)
; __device__ __forceinline__ unsigned cvt_pk_bf16(float lo, float hi) { f32x2_cv v = {lo, hi}; bf16x2_cv b = __builtin_convertvector(v, bf16x2_cv); return __builtin_bit_cast(unsigned, b); }
; __device__ __forceinline__ float fast_sigmoid(float x) { return __builtin_amdgcn_rcpf(1.0f + __expf(-x)); }
; __device__ __forceinline__ float bf_lo(unsigned w) { return __uint_as_float(w << 16); }
; __device__ __forceinline__ float bf_hi(unsigned w) { return __uint_as_float(w & 0xffff0000u); }
;     __device__ __forceinline__ void operator()(const f32x4 (&acc)[2][2][4][2], const Unit& u, int wr, int wc, int fr, int fq) const {
;     ...
;                 int rowi = lrow0 + ai * HALF + m * 16; asm volatile("" : "+v"(rowi)); const size_t row = (size_t)rowi;
; #pragma unroll
;                 for (int bj = 0; bj < 2; ++bj) {
;                     const u32x4 gw = *(const u32x4*)(GG + row * 2048 + goff + col0 + bj * HALF);
;                     f32x4 v0, v1;
;                     v0[0] = fast_sigmoid(bf_lo(gw.x)) * acc[ai][bj][m][0][0]; v0[1] = fast_sigmoid(bf_hi(gw.x)) * acc[ai][bj][m][0][1];
;                     v0[2] = fast_sigmoid(bf_lo(gw.y)) * acc[ai][bj][m][0][2]; v0[3] = fast_sigmoid(bf_hi(gw.y)) * acc[ai][bj][m][0][3];
;                     v1[0] = fast_sigmoid(bf_lo(gw.z)) * acc[ai][bj][m][1][0]; v1[1] = fast_sigmoid(bf_hi(gw.z)) * acc[ai][bj][m][1][1];
;                     v1[2] = fast_sigmoid(bf_lo(gw.w)) * acc[ai][bj][m][1][2]; v1[3] = fast_sigmoid(bf_hi(gw.w)) * acc[ai][bj][m][1][3];
;                     bf16_t* tp = TMP + row * 1024 + col0 + bj * HALF;
;                     if (MODE == 1) { const u32x4 tw = *(const u32x4*)tp;
;                         v0 += (f32x4){bf_lo(tw.x), bf_hi(tw.x), bf_lo(tw.y), bf_hi(tw.y)}; v1 += (f32x4){bf_lo(tw.z), bf_hi(tw.z), bf_lo(tw.w), bf_hi(tw.w)}; }
;                     u32x4 w; w.x = cvt_pk_bf16(v0[0], v0[1]); w.y = cvt_pk_bf16(v0[2], v0[3]); w.z = cvt_pk_bf16(v1[0], v1[1]); w.w = cvt_pk_bf16(v1[2], v1[3]);
;                     *(u32x4*)((MODE == 0 ? tp : MIX + row * 1024 + col0 + bj * HALF)) = w;
	v_lshlrev_b32_e32 v76, 16, v222
	v_and_b32_e32 v77, 0xffff0000, v222
	v_lshlrev_b32_e32 v78, 16, v223
	v_and_b32_e32 v79, 0xffff0000, v223
	v_lshlrev_b32_e32 v80, 16, v224
	v_and_b32_e32 v81, 0xffff0000, v224
	v_lshlrev_b32_e32 v82, 16, v225
	v_and_b32_e32 v83, 0xffff0000, v225
	v_add_u32_e32 v184, 0x90, v154
	v_ashrrev_i32_e32 v185, 31, v184
	v_lshlrev_b64 v[186:187], 11, v[184:185]
	v_lshl_add_u64 v[188:189], s[18:19], 0, v[186:187]
	v_lshl_add_u64 v[190:191], v[188:189], 0, v[148:149]
	global_load_dwordx4 v[222:225], v[190:191], off
	v_pk_fma_f32 v[74:75], v[74:75], v[88:89], v[78:79]
	v_pk_fma_f32 v[72:73], v[72:73], v[86:87], v[76:77]
	v_pk_fma_f32 v[76:77], v[70:71], v[92:93], v[82:83]
	v_pk_fma_f32 v[70:71], v[68:69], v[90:91], v[80:81]
	v_cvt_pk_bf16_f32 v68, v72, v73
	v_cvt_pk_bf16_f32 v69, v74, v75
	v_cvt_pk_bf16_f32 v70, v70, v71
	v_cvt_pk_bf16_f32 v71, v76, v77
	global_store_dwordx4 v[94:95], v[68:71], off offset:256
	s_nop 0
	v_ashrrev_i32_e32 v85, 31, v84
	v_lshlrev_b64 v[68:69], 12, v[84:85]
	v_lshl_add_u64 v[68:69], s[16:17], 0, v[68:69]
	v_lshl_add_u64 v[76:77], v[68:69], 0, v[148:149]
	v_lshlrev_b64 v[78:79], 11, v[84:85]
	v_lshl_add_u64 v[72:73], s[18:19], 0, v[78:79]
	v_lshl_add_u64 v[80:81], v[72:73], 0, v[148:149]
	v_lshl_add_u64 v[78:79], s[20:21], 0, v[78:79]
	v_lshl_add_u64 v[78:79], v[78:79], 0, v[148:149]
	s_waitcnt vmcnt(8)
	v_lshlrev_b32_e32 v82, 16, v226
	v_and_b32_e32 v83, 0xffff0000, v226
	v_lshlrev_b32_e32 v84, 16, v227
	v_and_b32_e32 v85, 0xffff0000, v227
	v_lshlrev_b32_e32 v86, 16, v228
	v_and_b32_e32 v87, 0xffff0000, v228
	v_lshlrev_b32_e32 v88, 16, v229
	v_and_b32_e32 v89, 0xffff0000, v229
	v_add_u32_e32 v184, 0x90, v154
	v_ashrrev_i32_e32 v185, 31, v184
	v_lshlrev_b64 v[186:187], 12, v[184:185]
	v_lshl_add_u64 v[186:187], s[16:17], 0, v[186:187]
	v_lshl_add_u64 v[188:189], v[186:187], 0, v[148:149]
	global_load_dwordx4 v[226:229], v[188:189], off offset:2304
	v_mul_f32_e32 v82, 0xbfb8aa3b, v82
	v_mul_f32_e32 v83, 0xbfb8aa3b, v83
	v_mul_f32_e32 v84, 0xbfb8aa3b, v84
	v_mul_f32_e32 v85, 0xbfb8aa3b, v85
	v_mul_f32_e32 v86, 0xbfb8aa3b, v86
	v_mul_f32_e32 v87, 0xbfb8aa3b, v87
	v_mul_f32_e32 v88, 0xbfb8aa3b, v88
	v_mul_f32_e32 v89, 0xbfb8aa3b, v89
	v_exp_f32_e32 v82, v82
	v_exp_f32_e32 v83, v83
	v_exp_f32_e32 v84, v84
	v_exp_f32_e32 v85, v85
	v_exp_f32_e32 v86, v86
	v_exp_f32_e32 v87, v87
	v_exp_f32_e32 v88, v88
	v_exp_f32_e32 v89, v89
	v_add_f32_e32 v82, 1.0, v82
	v_add_f32_e32 v83, 1.0, v83
	v_add_f32_e32 v84, 1.0, v84
	v_add_f32_e32 v85, 1.0, v85
	v_add_f32_e32 v86, 1.0, v86
	v_add_f32_e32 v87, 1.0, v87
	v_add_f32_e32 v88, 1.0, v88
	v_add_f32_e32 v89, 1.0, v89
	v_rcp_f32_e32 v82, v82
	v_rcp_f32_e32 v83, v83
	v_rcp_f32_e32 v84, v84
	v_rcp_f32_e32 v85, v85
	v_rcp_f32_e32 v86, v86
	v_rcp_f32_e32 v88, v88
	v_rcp_f32_e32 v89, v89
	v_rcp_f32_e32 v87, v87
	s_waitcnt vmcnt(8)
	v_lshlrev_b32_e32 v68, 16, v230
	v_and_b32_e32 v69, 0xffff0000, v230
	v_lshlrev_b32_e32 v70, 16, v231
	v_and_b32_e32 v71, 0xffff0000, v231
	v_lshlrev_b32_e32 v72, 16, v232
	v_and_b32_e32 v73, 0xffff0000, v232
	v_lshlrev_b32_e32 v74, 16, v233
	v_and_b32_e32 v75, 0xffff0000, v233
	v_add_u32_e32 v184, 0x90, v154
	v_ashrrev_i32_e32 v185, 31, v184
	v_lshlrev_b64 v[186:187], 11, v[184:185]
	v_lshl_add_u64 v[188:189], s[18:19], 0, v[186:187]
	v_lshl_add_u64 v[190:191], v[188:189], 0, v[148:149]
	global_load_dwordx4 v[230:233], v[190:191], off offset:256
	v_pk_fma_f32 v[66:67], v[66:67], v[84:85], v[70:71]
	v_pk_fma_f32 v[64:65], v[64:65], v[82:83], v[68:69]
	v_pk_fma_f32 v[68:69], v[62:63], v[88:89], v[74:75]
	v_pk_fma_f32 v[62:63], v[60:61], v[86:87], v[72:73]
	v_cvt_pk_bf16_f32 v60, v64, v65
	v_cvt_pk_bf16_f32 v61, v66, v67
	v_cvt_pk_bf16_f32 v62, v62, v63
	v_cvt_pk_bf16_f32 v63, v68, v69
	global_store_dwordx4 v[78:79], v[60:63], off
	s_nop 0
	v_add_u32_e32 v68, 0x90, v154
	s_waitcnt vmcnt(8)
	v_lshlrev_b32_e32 v69, 16, v210
	v_and_b32_e32 v70, 0xffff0000, v210
	v_lshlrev_b32_e32 v71, 16, v211
	v_and_b32_e32 v72, 0xffff0000, v211
	v_lshlrev_b32_e32 v73, 16, v212
	v_and_b32_e32 v74, 0xffff0000, v212
	v_lshlrev_b32_e32 v75, 16, v213
	v_and_b32_e32 v76, 0xffff0000, v213
	v_add_u32_e32 v184, 0xa0, v154
	v_ashrrev_i32_e32 v185, 31, v184
	v_lshlrev_b64 v[186:187], 12, v[184:185]
	v_lshl_add_u64 v[186:187], s[16:17], 0, v[186:187]
	v_lshl_add_u64 v[188:189], v[186:187], 0, v[148:149]
	global_load_dwordx4 v[210:213], v[188:189], off offset:2048
	v_mul_f32_e32 v69, 0xbfb8aa3b, v69
	v_mul_f32_e32 v70, 0xbfb8aa3b, v70
	v_mul_f32_e32 v71, 0xbfb8aa3b, v71
	v_mul_f32_e32 v72, 0xbfb8aa3b, v72
	v_mul_f32_e32 v73, 0xbfb8aa3b, v73
	v_mul_f32_e32 v74, 0xbfb8aa3b, v74
	v_mul_f32_e32 v75, 0xbfb8aa3b, v75
	v_mul_f32_e32 v76, 0xbfb8aa3b, v76
	v_exp_f32_e32 v69, v69
	v_exp_f32_e32 v70, v70
	v_exp_f32_e32 v71, v71
	v_exp_f32_e32 v72, v72
	v_exp_f32_e32 v73, v73
	v_exp_f32_e32 v74, v74
	v_exp_f32_e32 v75, v75
	v_exp_f32_e32 v76, v76
	v_add_f32_e32 v69, 1.0, v69
	v_add_f32_e32 v77, 1.0, v70
	v_add_f32_e32 v80, 1.0, v71
	v_add_f32_e32 v81, 1.0, v72
	v_add_f32_e32 v82, 1.0, v73
	v_add_f32_e32 v83, 1.0, v74
	v_add_f32_e32 v75, 1.0, v75
	v_add_f32_e32 v84, 1.0, v76
	v_rcp_f32_e32 v70, v69
	v_rcp_f32_e32 v71, v77
	v_rcp_f32_e32 v72, v80
	v_rcp_f32_e32 v73, v81
	v_rcp_f32_e32 v74, v82
	v_rcp_f32_e32 v76, v75
	v_rcp_f32_e32 v77, v84
	v_rcp_f32_e32 v75, v83
	s_waitcnt vmcnt(8)
; __device__ __forceinline__ unsigned cvt_pk_bf16(float lo, float hi) { f32x2_cv v = {lo, hi}; bf16x2_cv b = __builtin_convertvector(v, bf16x2_cv); return __builtin_bit_cast(unsigned, b); }
; __device__ __forceinline__ float fast_sigmoid(float x) { return __builtin_amdgcn_rcpf(1.0f + __expf(-x)); }
; __device__ __forceinline__ float bf_lo(unsigned w) { return __uint_as_float(w << 16); }
; __device__ __forceinline__ float bf_hi(unsigned w) { return __uint_as_float(w & 0xffff0000u); }
;     __device__ __forceinline__ void operator()(const f32x4 (&acc)[2][2][4][2], const Unit& u, int wr, int wc, int fr, int fq) const {
;     ...
;                 int rowi = lrow0 + ai * HALF + m * 16; asm volatile("" : "+v"(rowi)); const size_t row = (size_t)rowi;
; #pragma unroll
;                 for (int bj = 0; bj < 2; ++bj) {
;                     const u32x4 gw = *(const u32x4*)(GG + row * 2048 + goff + col0 + bj * HALF);
;                     f32x4 v0, v1;
;                     v0[0] = fast_sigmoid(bf_lo(gw.x)) * acc[ai][bj][m][0][0]; v0[1] = fast_sigmoid(bf_hi(gw.x)) * acc[ai][bj][m][0][1];
;                     v0[2] = fast_sigmoid(bf_lo(gw.y)) * acc[ai][bj][m][0][2]; v0[3] = fast_sigmoid(bf_hi(gw.y)) * acc[ai][bj][m][0][3];
;                     v1[0] = fast_sigmoid(bf_lo(gw.z)) * acc[ai][bj][m][1][0]; v1[1] = fast_sigmoid(bf_hi(gw.z)) * acc[ai][bj][m][1][1];
;                     v1[2] = fast_sigmoid(bf_lo(gw.w)) * acc[ai][bj][m][1][2]; v1[3] = fast_sigmoid(bf_hi(gw.w)) * acc[ai][bj][m][1][3];
;                     bf16_t* tp = TMP + row * 1024 + col0 + bj * HALF;
;                     if (MODE == 1) { const u32x4 tw = *(const u32x4*)tp;
;                         v0 += (f32x4){bf_lo(tw.x), bf_hi(tw.x), bf_lo(tw.y), bf_hi(tw.y)}; v1 += (f32x4){bf_lo(tw.z), bf_hi(tw.z), bf_lo(tw.w), bf_hi(tw.w)}; }
;                     u32x4 w; w.x = cvt_pk_bf16(v0[0], v0[1]); w.y = cvt_pk_bf16(v0[2], v0[3]); w.z = cvt_pk_bf16(v1[0], v1[1]); w.w = cvt_pk_bf16(v1[2], v1[3]);
;                     *(u32x4*)((MODE == 0 ? tp : MIX + row * 1024 + col0 + bj * HALF)) = w;
	v_lshlrev_b32_e32 v60, 16, v214
	v_and_b32_e32 v61, 0xffff0000, v214
	v_lshlrev_b32_e32 v62, 16, v215
	v_and_b32_e32 v63, 0xffff0000, v215
	v_lshlrev_b32_e32 v64, 16, v216
	v_and_b32_e32 v65, 0xffff0000, v216
	v_lshlrev_b32_e32 v66, 16, v217
	v_and_b32_e32 v67, 0xffff0000, v217
	v_add_u32_e32 v184, 0xa0, v154
	v_ashrrev_i32_e32 v185, 31, v184
	v_lshlrev_b64 v[186:187], 11, v[184:185]
	v_lshl_add_u64 v[188:189], s[18:19], 0, v[186:187]
	v_lshl_add_u64 v[190:191], v[188:189], 0, v[148:149]
	global_load_dwordx4 v[214:217], v[190:191], off
	v_pk_fma_f32 v[58:59], v[58:59], v[72:73], v[62:63]
	v_pk_fma_f32 v[56:57], v[56:57], v[70:71], v[60:61]
	v_pk_fma_f32 v[60:61], v[54:55], v[76:77], v[66:67]
	v_pk_fma_f32 v[54:55], v[52:53], v[74:75], v[64:65]
	v_cvt_pk_bf16_f32 v52, v56, v57
	v_cvt_pk_bf16_f32 v53, v58, v59
	v_cvt_pk_bf16_f32 v54, v54, v55
	v_cvt_pk_bf16_f32 v55, v60, v61
	global_store_dwordx4 v[78:79], v[52:55], off offset:256
	s_nop 0
	v_ashrrev_i32_e32 v69, 31, v68
	v_lshlrev_b64 v[52:53], 12, v[68:69]
	v_lshl_add_u64 v[52:53], s[16:17], 0, v[52:53]
	v_lshl_add_u64 v[60:61], v[52:53], 0, v[148:149]
	v_lshlrev_b64 v[62:63], 11, v[68:69]
	v_lshl_add_u64 v[56:57], s[18:19], 0, v[62:63]
	v_lshl_add_u64 v[64:65], v[56:57], 0, v[148:149]
	v_lshl_add_u64 v[62:63], s[20:21], 0, v[62:63]
	v_lshl_add_u64 v[62:63], v[62:63], 0, v[148:149]
	s_waitcnt vmcnt(8)
	v_lshlrev_b32_e32 v66, 16, v218
	v_and_b32_e32 v67, 0xffff0000, v218
	v_lshlrev_b32_e32 v68, 16, v219
	v_and_b32_e32 v69, 0xffff0000, v219
	v_lshlrev_b32_e32 v70, 16, v220
	v_and_b32_e32 v71, 0xffff0000, v220
	v_lshlrev_b32_e32 v72, 16, v221
	v_and_b32_e32 v73, 0xffff0000, v221
	v_add_u32_e32 v184, 0xa0, v154
	v_ashrrev_i32_e32 v185, 31, v184
	v_lshlrev_b64 v[186:187], 12, v[184:185]
	v_lshl_add_u64 v[186:187], s[16:17], 0, v[186:187]
	v_lshl_add_u64 v[188:189], v[186:187], 0, v[148:149]
	global_load_dwordx4 v[218:221], v[188:189], off offset:2304
	v_mul_f32_e32 v66, 0xbfb8aa3b, v66
	v_mul_f32_e32 v67, 0xbfb8aa3b, v67
	v_mul_f32_e32 v68, 0xbfb8aa3b, v68
	v_mul_f32_e32 v69, 0xbfb8aa3b, v69
	v_mul_f32_e32 v70, 0xbfb8aa3b, v70
	v_mul_f32_e32 v71, 0xbfb8aa3b, v71
	v_mul_f32_e32 v72, 0xbfb8aa3b, v72
	v_mul_f32_e32 v73, 0xbfb8aa3b, v73
	v_exp_f32_e32 v66, v66
	v_exp_f32_e32 v67, v67
	v_exp_f32_e32 v68, v68
	v_exp_f32_e32 v69, v69
	v_exp_f32_e32 v70, v70
	v_exp_f32_e32 v71, v71
	v_exp_f32_e32 v72, v72
	v_exp_f32_e32 v73, v73
	v_add_f32_e32 v66, 1.0, v66
	v_add_f32_e32 v67, 1.0, v67
	v_add_f32_e32 v68, 1.0, v68
	v_add_f32_e32 v69, 1.0, v69
	v_add_f32_e32 v70, 1.0, v70
	v_add_f32_e32 v71, 1.0, v71
	v_add_f32_e32 v72, 1.0, v72
	v_add_f32_e32 v73, 1.0, v73
	v_rcp_f32_e32 v66, v66
	v_rcp_f32_e32 v67, v67
	v_rcp_f32_e32 v68, v68
	v_rcp_f32_e32 v69, v69
	v_rcp_f32_e32 v70, v70
	v_rcp_f32_e32 v72, v72
	v_rcp_f32_e32 v73, v73
	v_rcp_f32_e32 v71, v71
	s_waitcnt vmcnt(8)
	v_lshlrev_b32_e32 v52, 16, v222
	v_and_b32_e32 v53, 0xffff0000, v222
	v_lshlrev_b32_e32 v54, 16, v223
	v_and_b32_e32 v55, 0xffff0000, v223
	v_lshlrev_b32_e32 v56, 16, v224
	v_and_b32_e32 v57, 0xffff0000, v224
	v_lshlrev_b32_e32 v58, 16, v225
	v_and_b32_e32 v59, 0xffff0000, v225
	v_add_u32_e32 v184, 0xa0, v154
	v_ashrrev_i32_e32 v185, 31, v184
	v_lshlrev_b64 v[186:187], 11, v[184:185]
	v_lshl_add_u64 v[188:189], s[18:19], 0, v[186:187]
	v_lshl_add_u64 v[190:191], v[188:189], 0, v[148:149]
	global_load_dwordx4 v[222:225], v[190:191], off offset:256
	v_pk_fma_f32 v[50:51], v[50:51], v[68:69], v[54:55]
	v_pk_fma_f32 v[48:49], v[48:49], v[66:67], v[52:53]
	v_pk_fma_f32 v[52:53], v[46:47], v[72:73], v[58:59]
	v_pk_fma_f32 v[46:47], v[44:45], v[70:71], v[56:57]
	v_cvt_pk_bf16_f32 v44, v48, v49
	v_cvt_pk_bf16_f32 v45, v50, v51
	v_cvt_pk_bf16_f32 v46, v46, v47
	v_cvt_pk_bf16_f32 v47, v52, v53
	global_store_dwordx4 v[62:63], v[44:47], off
	s_nop 0
	v_add_u32_e32 v52, 0xa0, v154
	s_waitcnt vmcnt(8)
	v_lshlrev_b32_e32 v53, 16, v226
	v_and_b32_e32 v54, 0xffff0000, v226
	v_lshlrev_b32_e32 v55, 16, v227
	v_and_b32_e32 v56, 0xffff0000, v227
	v_lshlrev_b32_e32 v57, 16, v228
	v_and_b32_e32 v58, 0xffff0000, v228
	v_lshlrev_b32_e32 v59, 16, v229
	v_and_b32_e32 v60, 0xffff0000, v229
	v_add_u32_e32 v184, 0xb0, v154
	v_ashrrev_i32_e32 v185, 31, v184
	v_lshlrev_b64 v[186:187], 12, v[184:185]
	v_lshl_add_u64 v[186:187], s[16:17], 0, v[186:187]
	v_lshl_add_u64 v[188:189], v[186:187], 0, v[148:149]
	global_load_dwordx4 v[226:229], v[188:189], off offset:2048
	v_mul_f32_e32 v53, 0xbfb8aa3b, v53
	v_mul_f32_e32 v54, 0xbfb8aa3b, v54
	v_mul_f32_e32 v55, 0xbfb8aa3b, v55
	v_mul_f32_e32 v56, 0xbfb8aa3b, v56
	v_mul_f32_e32 v57, 0xbfb8aa3b, v57
	v_mul_f32_e32 v58, 0xbfb8aa3b, v58
	v_mul_f32_e32 v59, 0xbfb8aa3b, v59
	v_mul_f32_e32 v60, 0xbfb8aa3b, v60
	v_exp_f32_e32 v53, v53
	v_exp_f32_e32 v54, v54
	v_exp_f32_e32 v55, v55
	v_exp_f32_e32 v56, v56
	v_exp_f32_e32 v57, v57
	v_exp_f32_e32 v58, v58
	v_exp_f32_e32 v59, v59
	v_exp_f32_e32 v60, v60
	v_add_f32_e32 v53, 1.0, v53
	v_add_f32_e32 v61, 1.0, v54
	v_add_f32_e32 v64, 1.0, v55
	v_add_f32_e32 v65, 1.0, v56
	v_add_f32_e32 v66, 1.0, v57
	v_add_f32_e32 v67, 1.0, v58
	v_add_f32_e32 v59, 1.0, v59
	v_add_f32_e32 v68, 1.0, v60
	v_rcp_f32_e32 v54, v53
	v_rcp_f32_e32 v55, v61
	v_rcp_f32_e32 v56, v64
	v_rcp_f32_e32 v57, v65
	v_rcp_f32_e32 v58, v66
	v_rcp_f32_e32 v60, v59
	v_rcp_f32_e32 v61, v68
	v_rcp_f32_e32 v59, v67
	s_waitcnt vmcnt(8)
; __device__ __forceinline__ unsigned cvt_pk_bf16(float lo, float hi) { f32x2_cv v = {lo, hi}; bf16x2_cv b = __builtin_convertvector(v, bf16x2_cv); return __builtin_bit_cast(unsigned, b); }
; __device__ __forceinline__ float fast_sigmoid(float x) { return __builtin_amdgcn_rcpf(1.0f + __expf(-x)); }
; __device__ __forceinline__ float bf_lo(unsigned w) { return __uint_as_float(w << 16); }
; __device__ __forceinline__ float bf_hi(unsigned w) { return __uint_as_float(w & 0xffff0000u); }
;     __device__ __forceinline__ void operator()(const f32x4 (&acc)[2][2][4][2], const Unit& u, int wr, int wc, int fr, int fq) const {
;     ...
;                 int rowi = lrow0 + ai * HALF + m * 16; asm volatile("" : "+v"(rowi)); const size_t row = (size_t)rowi;
; #pragma unroll
;                 for (int bj = 0; bj < 2; ++bj) {
;                     const u32x4 gw = *(const u32x4*)(GG + row * 2048 + goff + col0 + bj * HALF);
;                     f32x4 v0, v1;
;                     v0[0] = fast_sigmoid(bf_lo(gw.x)) * acc[ai][bj][m][0][0]; v0[1] = fast_sigmoid(bf_hi(gw.x)) * acc[ai][bj][m][0][1];
;                     v0[2] = fast_sigmoid(bf_lo(gw.y)) * acc[ai][bj][m][0][2]; v0[3] = fast_sigmoid(bf_hi(gw.y)) * acc[ai][bj][m][0][3];
;                     v1[0] = fast_sigmoid(bf_lo(gw.z)) * acc[ai][bj][m][1][0]; v1[1] = fast_sigmoid(bf_hi(gw.z)) * acc[ai][bj][m][1][1];
;                     v1[2] = fast_sigmoid(bf_lo(gw.w)) * acc[ai][bj][m][1][2]; v1[3] = fast_sigmoid(bf_hi(gw.w)) * acc[ai][bj][m][1][3];
;                     bf16_t* tp = TMP + row * 1024 + col0 + bj * HALF;
;                     if (MODE == 1) { const u32x4 tw = *(const u32x4*)tp;
;                         v0 += (f32x4){bf_lo(tw.x), bf_hi(tw.x), bf_lo(tw.y), bf_hi(tw.y)}; v1 += (f32x4){bf_lo(tw.z), bf_hi(tw.z), bf_lo(tw.w), bf_hi(tw.w)}; }
;                     u32x4 w; w.x = cvt_pk_bf16(v0[0], v0[1]); w.y = cvt_pk_bf16(v0[2], v0[3]); w.z = cvt_pk_bf16(v1[0], v1[1]); w.w = cvt_pk_bf16(v1[2], v1[3]);
;                     *(u32x4*)((MODE == 0 ? tp : MIX + row * 1024 + col0 + bj * HALF)) = w;
	v_lshlrev_b32_e32 v44, 16, v230
	v_and_b32_e32 v45, 0xffff0000, v230
	v_lshlrev_b32_e32 v46, 16, v231
	v_and_b32_e32 v47, 0xffff0000, v231
	v_lshlrev_b32_e32 v48, 16, v232
	v_and_b32_e32 v49, 0xffff0000, v232
	v_lshlrev_b32_e32 v50, 16, v233
	v_and_b32_e32 v51, 0xffff0000, v233
	v_add_u32_e32 v184, 0xb0, v154
	v_ashrrev_i32_e32 v185, 31, v184
	v_lshlrev_b64 v[186:187], 11, v[184:185]
	v_lshl_add_u64 v[188:189], s[18:19], 0, v[186:187]
	v_lshl_add_u64 v[190:191], v[188:189], 0, v[148:149]
	global_load_dwordx4 v[230:233], v[190:191], off
	v_pk_fma_f32 v[42:43], v[42:43], v[56:57], v[46:47]
	v_pk_fma_f32 v[40:41], v[40:41], v[54:55], v[44:45]
	v_pk_fma_f32 v[44:45], v[38:39], v[60:61], v[50:51]
	v_pk_fma_f32 v[38:39], v[36:37], v[58:59], v[48:49]
	v_cvt_pk_bf16_f32 v36, v40, v41
	v_cvt_pk_bf16_f32 v37, v42, v43
	v_cvt_pk_bf16_f32 v38, v38, v39
	v_cvt_pk_bf16_f32 v39, v44, v45
	global_store_dwordx4 v[62:63], v[36:39], off offset:256
	s_nop 0
	v_ashrrev_i32_e32 v53, 31, v52
	v_lshlrev_b64 v[36:37], 12, v[52:53]
	v_lshl_add_u64 v[36:37], s[16:17], 0, v[36:37]
	v_lshl_add_u64 v[44:45], v[36:37], 0, v[148:149]
	v_lshlrev_b64 v[46:47], 11, v[52:53]
	v_lshl_add_u64 v[40:41], s[18:19], 0, v[46:47]
	v_lshl_add_u64 v[48:49], v[40:41], 0, v[148:149]
	v_lshl_add_u64 v[46:47], s[20:21], 0, v[46:47]
	v_lshl_add_u64 v[46:47], v[46:47], 0, v[148:149]
	s_waitcnt vmcnt(8)
	v_lshlrev_b32_e32 v50, 16, v210
	v_and_b32_e32 v51, 0xffff0000, v210
	v_lshlrev_b32_e32 v52, 16, v211
	v_and_b32_e32 v53, 0xffff0000, v211
	v_lshlrev_b32_e32 v54, 16, v212
	v_and_b32_e32 v55, 0xffff0000, v212
	v_lshlrev_b32_e32 v56, 16, v213
	v_and_b32_e32 v57, 0xffff0000, v213
	v_add_u32_e32 v184, 0xb0, v154
	v_ashrrev_i32_e32 v185, 31, v184
	v_lshlrev_b64 v[186:187], 12, v[184:185]
	v_lshl_add_u64 v[186:187], s[16:17], 0, v[186:187]
	v_lshl_add_u64 v[188:189], v[186:187], 0, v[148:149]
	global_load_dwordx4 v[210:213], v[188:189], off offset:2304
	v_mul_f32_e32 v50, 0xbfb8aa3b, v50
	v_mul_f32_e32 v51, 0xbfb8aa3b, v51
	v_mul_f32_e32 v52, 0xbfb8aa3b, v52
	v_mul_f32_e32 v53, 0xbfb8aa3b, v53
	v_mul_f32_e32 v54, 0xbfb8aa3b, v54
	v_mul_f32_e32 v55, 0xbfb8aa3b, v55
	v_mul_f32_e32 v56, 0xbfb8aa3b, v56
	v_mul_f32_e32 v57, 0xbfb8aa3b, v57
	v_exp_f32_e32 v50, v50
	v_exp_f32_e32 v51, v51
	v_exp_f32_e32 v52, v52
	v_exp_f32_e32 v53, v53
	v_exp_f32_e32 v54, v54
	v_exp_f32_e32 v55, v55
	v_exp_f32_e32 v56, v56
	v_exp_f32_e32 v57, v57
	v_add_f32_e32 v50, 1.0, v50
	v_add_f32_e32 v51, 1.0, v51
	v_add_f32_e32 v52, 1.0, v52
	v_add_f32_e32 v53, 1.0, v53
	v_add_f32_e32 v54, 1.0, v54
	v_add_f32_e32 v55, 1.0, v55
	v_add_f32_e32 v56, 1.0, v56
	v_add_f32_e32 v57, 1.0, v57
	v_rcp_f32_e32 v50, v50
	v_rcp_f32_e32 v51, v51
	v_rcp_f32_e32 v52, v52
	v_rcp_f32_e32 v53, v53
	v_rcp_f32_e32 v54, v54
	v_rcp_f32_e32 v56, v56
	v_rcp_f32_e32 v57, v57
	v_rcp_f32_e32 v55, v55
	s_waitcnt vmcnt(8)
	v_lshlrev_b32_e32 v36, 16, v214
	v_and_b32_e32 v37, 0xffff0000, v214
	v_lshlrev_b32_e32 v38, 16, v215
	v_and_b32_e32 v39, 0xffff0000, v215
	v_lshlrev_b32_e32 v40, 16, v216
	v_and_b32_e32 v41, 0xffff0000, v216
	v_lshlrev_b32_e32 v42, 16, v217
	v_and_b32_e32 v43, 0xffff0000, v217
	v_add_u32_e32 v184, 0xb0, v154
	v_ashrrev_i32_e32 v185, 31, v184
	v_lshlrev_b64 v[186:187], 11, v[184:185]
	v_lshl_add_u64 v[188:189], s[18:19], 0, v[186:187]
	v_lshl_add_u64 v[190:191], v[188:189], 0, v[148:149]
	global_load_dwordx4 v[214:217], v[190:191], off offset:256
	v_pk_fma_f32 v[34:35], v[34:35], v[52:53], v[38:39]
	v_pk_fma_f32 v[32:33], v[32:33], v[50:51], v[36:37]
	v_pk_fma_f32 v[36:37], v[30:31], v[56:57], v[42:43]
	v_pk_fma_f32 v[30:31], v[28:29], v[54:55], v[40:41]
	v_cvt_pk_bf16_f32 v28, v32, v33
	v_cvt_pk_bf16_f32 v29, v34, v35
	v_cvt_pk_bf16_f32 v30, v30, v31
	v_cvt_pk_bf16_f32 v31, v36, v37
	global_store_dwordx4 v[46:47], v[28:31], off
	s_nop 0
	v_add_u32_e32 v36, 0xb0, v154
	s_waitcnt vmcnt(8)
	v_lshlrev_b32_e32 v37, 16, v218
	v_and_b32_e32 v38, 0xffff0000, v218
	v_lshlrev_b32_e32 v39, 16, v219
	v_and_b32_e32 v40, 0xffff0000, v219
	v_lshlrev_b32_e32 v41, 16, v220
	v_and_b32_e32 v42, 0xffff0000, v220
	v_lshlrev_b32_e32 v43, 16, v221
	v_and_b32_e32 v44, 0xffff0000, v221
	v_mul_f32_e32 v37, 0xbfb8aa3b, v37
	v_mul_f32_e32 v38, 0xbfb8aa3b, v38
	v_mul_f32_e32 v39, 0xbfb8aa3b, v39
	v_mul_f32_e32 v40, 0xbfb8aa3b, v40
	v_mul_f32_e32 v41, 0xbfb8aa3b, v41
	v_mul_f32_e32 v42, 0xbfb8aa3b, v42
	v_mul_f32_e32 v43, 0xbfb8aa3b, v43
	v_mul_f32_e32 v44, 0xbfb8aa3b, v44
	v_exp_f32_e32 v37, v37
	v_exp_f32_e32 v38, v38
	v_exp_f32_e32 v39, v39
	v_exp_f32_e32 v40, v40
	v_exp_f32_e32 v41, v41
	v_exp_f32_e32 v42, v42
	v_exp_f32_e32 v43, v43
	v_exp_f32_e32 v44, v44
	v_add_f32_e32 v37, 1.0, v37
	v_add_f32_e32 v45, 1.0, v38
	v_add_f32_e32 v48, 1.0, v39
	v_add_f32_e32 v49, 1.0, v40
	v_add_f32_e32 v50, 1.0, v41
	v_add_f32_e32 v51, 1.0, v42
	v_add_f32_e32 v43, 1.0, v43
	v_add_f32_e32 v52, 1.0, v44
	v_rcp_f32_e32 v38, v37
	v_rcp_f32_e32 v39, v45
	v_rcp_f32_e32 v40, v48
	v_rcp_f32_e32 v41, v49
	v_rcp_f32_e32 v42, v50
	v_rcp_f32_e32 v44, v43
	v_rcp_f32_e32 v45, v52
	v_rcp_f32_e32 v43, v51
	s_waitcnt vmcnt(7)
; __device__ __forceinline__ unsigned cvt_pk_bf16(float lo, float hi) { f32x2_cv v = {lo, hi}; bf16x2_cv b = __builtin_convertvector(v, bf16x2_cv); return __builtin_bit_cast(unsigned, b); }
; __device__ __forceinline__ float fast_sigmoid(float x) { return __builtin_amdgcn_rcpf(1.0f + __expf(-x)); }
; __device__ __forceinline__ float bf_lo(unsigned w) { return __uint_as_float(w << 16); }
; __device__ __forceinline__ float bf_hi(unsigned w) { return __uint_as_float(w & 0xffff0000u); }
;     __device__ __forceinline__ void operator()(const f32x4 (&acc)[2][2][4][2], const Unit& u, int wr, int wc, int fr, int fq) const {
;     ...
;                 int rowi = lrow0 + ai * HALF + m * 16; asm volatile("" : "+v"(rowi)); const size_t row = (size_t)rowi;
; #pragma unroll
;                 for (int bj = 0; bj < 2; ++bj) {
;                     const u32x4 gw = *(const u32x4*)(GG + row * 2048 + goff + col0 + bj * HALF);
;                     f32x4 v0, v1;
;                     v0[0] = fast_sigmoid(bf_lo(gw.x)) * acc[ai][bj][m][0][0]; v0[1] = fast_sigmoid(bf_hi(gw.x)) * acc[ai][bj][m][0][1];
;                     v0[2] = fast_sigmoid(bf_lo(gw.y)) * acc[ai][bj][m][0][2]; v0[3] = fast_sigmoid(bf_hi(gw.y)) * acc[ai][bj][m][0][3];
;                     v1[0] = fast_sigmoid(bf_lo(gw.z)) * acc[ai][bj][m][1][0]; v1[1] = fast_sigmoid(bf_hi(gw.z)) * acc[ai][bj][m][1][1];
;                     v1[2] = fast_sigmoid(bf_lo(gw.w)) * acc[ai][bj][m][1][2]; v1[3] = fast_sigmoid(bf_hi(gw.w)) * acc[ai][bj][m][1][3];
;                     bf16_t* tp = TMP + row * 1024 + col0 + bj * HALF;
;                     if (MODE == 1) { const u32x4 tw = *(const u32x4*)tp;
;                         v0 += (f32x4){bf_lo(tw.x), bf_hi(tw.x), bf_lo(tw.y), bf_hi(tw.y)}; v1 += (f32x4){bf_lo(tw.z), bf_hi(tw.z), bf_lo(tw.w), bf_hi(tw.w)}; }
;                     u32x4 w; w.x = cvt_pk_bf16(v0[0], v0[1]); w.y = cvt_pk_bf16(v0[2], v0[3]); w.z = cvt_pk_bf16(v1[0], v1[1]); w.w = cvt_pk_bf16(v1[2], v1[3]);
;                     *(u32x4*)((MODE == 0 ? tp : MIX + row * 1024 + col0 + bj * HALF)) = w;
	v_lshlrev_b32_e32 v28, 16, v222
	v_and_b32_e32 v29, 0xffff0000, v222
	v_lshlrev_b32_e32 v30, 16, v223
	v_and_b32_e32 v31, 0xffff0000, v223
	v_lshlrev_b32_e32 v32, 16, v224
	v_and_b32_e32 v33, 0xffff0000, v224
	v_lshlrev_b32_e32 v34, 16, v225
	v_and_b32_e32 v35, 0xffff0000, v225
	v_pk_fma_f32 v[26:27], v[26:27], v[40:41], v[30:31]
	v_pk_fma_f32 v[24:25], v[24:25], v[38:39], v[28:29]
	v_pk_fma_f32 v[28:29], v[22:23], v[44:45], v[34:35]
	v_pk_fma_f32 v[22:23], v[20:21], v[42:43], v[32:33]
	v_cvt_pk_bf16_f32 v20, v24, v25
	v_cvt_pk_bf16_f32 v21, v26, v27
	v_cvt_pk_bf16_f32 v22, v22, v23
	v_cvt_pk_bf16_f32 v23, v28, v29
	global_store_dwordx4 v[46:47], v[20:23], off offset:256
	s_nop 0
	v_ashrrev_i32_e32 v37, 31, v36
	v_lshlrev_b64 v[20:21], 12, v[36:37]
	v_lshl_add_u64 v[20:21], s[16:17], 0, v[20:21]
	v_lshl_add_u64 v[28:29], v[20:21], 0, v[148:149]
	v_lshlrev_b64 v[30:31], 11, v[36:37]
	v_lshl_add_u64 v[24:25], s[18:19], 0, v[30:31]
	v_lshl_add_u64 v[32:33], v[24:25], 0, v[148:149]
	v_lshl_add_u64 v[30:31], s[20:21], 0, v[30:31]
	v_lshl_add_u64 v[30:31], v[30:31], 0, v[148:149]
	s_waitcnt vmcnt(6)
	v_lshlrev_b32_e32 v34, 16, v226
	v_and_b32_e32 v35, 0xffff0000, v226
	v_lshlrev_b32_e32 v36, 16, v227
	v_and_b32_e32 v37, 0xffff0000, v227
	v_lshlrev_b32_e32 v38, 16, v228
	v_and_b32_e32 v39, 0xffff0000, v228
	v_lshlrev_b32_e32 v40, 16, v229
	v_and_b32_e32 v41, 0xffff0000, v229
	v_mul_f32_e32 v34, 0xbfb8aa3b, v34
	v_mul_f32_e32 v35, 0xbfb8aa3b, v35
	v_mul_f32_e32 v36, 0xbfb8aa3b, v36
	v_mul_f32_e32 v37, 0xbfb8aa3b, v37
	v_mul_f32_e32 v38, 0xbfb8aa3b, v38
	v_mul_f32_e32 v39, 0xbfb8aa3b, v39
	v_mul_f32_e32 v40, 0xbfb8aa3b, v40
	v_mul_f32_e32 v41, 0xbfb8aa3b, v41
	v_exp_f32_e32 v34, v34
	v_exp_f32_e32 v35, v35
	v_exp_f32_e32 v36, v36
	v_exp_f32_e32 v37, v37
	v_exp_f32_e32 v38, v38
	v_exp_f32_e32 v39, v39
	v_exp_f32_e32 v40, v40
	v_exp_f32_e32 v41, v41
	v_add_f32_e32 v34, 1.0, v34
	v_add_f32_e32 v35, 1.0, v35
	v_add_f32_e32 v36, 1.0, v36
	v_add_f32_e32 v37, 1.0, v37
	v_add_f32_e32 v38, 1.0, v38
	v_add_f32_e32 v39, 1.0, v39
	v_add_f32_e32 v40, 1.0, v40
	v_add_f32_e32 v41, 1.0, v41
	v_rcp_f32_e32 v34, v34
	v_rcp_f32_e32 v35, v35
	v_rcp_f32_e32 v36, v36
	v_rcp_f32_e32 v37, v37
	v_rcp_f32_e32 v38, v38
	v_rcp_f32_e32 v40, v40
	v_rcp_f32_e32 v41, v41
	v_rcp_f32_e32 v39, v39
	s_waitcnt vmcnt(5)
	v_lshlrev_b32_e32 v20, 16, v230
	v_and_b32_e32 v21, 0xffff0000, v230
	v_lshlrev_b32_e32 v22, 16, v231
	v_and_b32_e32 v23, 0xffff0000, v231
	v_lshlrev_b32_e32 v24, 16, v232
	v_and_b32_e32 v25, 0xffff0000, v232
	v_lshlrev_b32_e32 v26, 16, v233
	v_and_b32_e32 v27, 0xffff0000, v233
	v_pk_fma_f32 v[18:19], v[18:19], v[36:37], v[22:23]
	v_pk_fma_f32 v[16:17], v[16:17], v[34:35], v[20:21]
	v_pk_fma_f32 v[20:21], v[14:15], v[40:41], v[26:27]
	v_pk_fma_f32 v[14:15], v[12:13], v[38:39], v[24:25]
	v_cvt_pk_bf16_f32 v12, v16, v17
	v_cvt_pk_bf16_f32 v13, v18, v19
	v_cvt_pk_bf16_f32 v14, v14, v15
	v_cvt_pk_bf16_f32 v15, v20, v21
	global_store_dwordx4 v[30:31], v[12:15], off
	s_nop 0
	s_waitcnt vmcnt(4)
	v_lshlrev_b32_e32 v20, 16, v210
	v_and_b32_e32 v21, 0xffff0000, v210
	v_lshlrev_b32_e32 v22, 16, v211
	v_and_b32_e32 v23, 0xffff0000, v211
	v_lshlrev_b32_e32 v24, 16, v212
	v_and_b32_e32 v25, 0xffff0000, v212
	v_lshlrev_b32_e32 v26, 16, v213
	v_and_b32_e32 v27, 0xffff0000, v213
	v_mul_f32_e32 v20, 0xbfb8aa3b, v20
	v_mul_f32_e32 v21, 0xbfb8aa3b, v21
	v_mul_f32_e32 v22, 0xbfb8aa3b, v22
	v_mul_f32_e32 v23, 0xbfb8aa3b, v23
	v_mul_f32_e32 v24, 0xbfb8aa3b, v24
	v_mul_f32_e32 v25, 0xbfb8aa3b, v25
	v_mul_f32_e32 v26, 0xbfb8aa3b, v26
	v_mul_f32_e32 v27, 0xbfb8aa3b, v27
	v_exp_f32_e32 v20, v20
	v_exp_f32_e32 v21, v21
	v_exp_f32_e32 v22, v22
	v_exp_f32_e32 v23, v23
	v_exp_f32_e32 v24, v24
	v_exp_f32_e32 v25, v25
	v_exp_f32_e32 v26, v26
	v_exp_f32_e32 v27, v27
	v_add_f32_e32 v20, 1.0, v20
	v_add_f32_e32 v21, 1.0, v21
	v_add_f32_e32 v22, 1.0, v22
	v_add_f32_e32 v23, 1.0, v23
	v_add_f32_e32 v24, 1.0, v24
	v_add_f32_e32 v25, 1.0, v25
	v_add_f32_e32 v26, 1.0, v26
	v_add_f32_e32 v27, 1.0, v27
	v_rcp_f32_e32 v20, v20
	v_rcp_f32_e32 v21, v21
	v_rcp_f32_e32 v22, v22
	v_rcp_f32_e32 v23, v23
	v_rcp_f32_e32 v24, v24
	v_rcp_f32_e32 v26, v26
	v_rcp_f32_e32 v27, v27
	v_rcp_f32_e32 v25, v25
	s_waitcnt vmcnt(3)
	v_lshlrev_b32_e32 v12, 16, v214
	v_and_b32_e32 v13, 0xffff0000, v214
	v_lshlrev_b32_e32 v14, 16, v215
	v_and_b32_e32 v15, 0xffff0000, v215
	v_lshlrev_b32_e32 v16, 16, v216
	v_and_b32_e32 v17, 0xffff0000, v216
	v_lshlrev_b32_e32 v18, 16, v217
	v_and_b32_e32 v19, 0xffff0000, v217
	v_pk_fma_f32 v[10:11], v[10:11], v[22:23], v[14:15]
	v_pk_fma_f32 v[8:9], v[8:9], v[20:21], v[12:13]
	v_pk_fma_f32 v[12:13], v[6:7], v[26:27], v[18:19]
	v_pk_fma_f32 v[6:7], v[4:5], v[24:25], v[16:17]
	v_cvt_pk_bf16_f32 v4, v8, v9
	v_cvt_pk_bf16_f32 v5, v10, v11
	v_cvt_pk_bf16_f32 v6, v6, v7
	v_cvt_pk_bf16_f32 v7, v12, v13
	global_store_dwordx4 v[30:31], v[4:7], off offset:256
	s_cbranch_vccnz .LBB0_782
	s_andn2_b64 vcc, exec, s[4:5]
	s_cbranch_vccnz .LBB0_781
	s_barrier
	s_branch .LBB0_781

; __device__ __forceinline__ unsigned cvt_pk_bf16(float lo, float hi) { f32x2_cv v = {lo, hi}; bf16x2_cv b = __builtin_convertvector(v, bf16x2_cv); return __builtin_bit_cast(unsigned, b); }
; __device__ __forceinline__ float bf_lo(unsigned w) { return __uint_as_float(w << 16); }
; __device__ __forceinline__ float bf_hi(unsigned w) { return __uint_as_float(w & 0xffff0000u); }
;     __device__ __forceinline__ void operator()(const f32x4 (&acc)[2][2][4][2], const Unit& u, int wr, int wc, int fr, int fq) const {
;     ...
;                 int lrow = lrow0 + ai * HALF + m * 16; asm volatile("" : "+v"(lrow)); const size_t row = (size_t)u.pm * BM + lrow;
;                 float ss = 0.f;
; #pragma unroll
;                 for (int bj = 0; bj < 2; ++bj) {
;                     f32x4 b0, b1;
;                     if (baseb) { const u32x4 bw = *(const u32x4*)(baseb + row * 1024 + col0 + bj * HALF);
;                         b0 = (f32x4){bf_lo(bw.x), bf_hi(bw.x), bf_lo(bw.y), bf_hi(bw.y)}; b1 = (f32x4){bf_lo(bw.z), bf_hi(bw.z), bf_lo(bw.w), bf_hi(bw.w)}; }
;                     else { const float* bp = base + (size_t)lrow * 1024 + col0 + bj * HALF; b0 = *(const f32x4*)bp; b1 = *(const f32x4*)(bp + 4); }
;                     const f32x4 v0 = b0 + acc[ai][bj][m][0] * alpha, v1 = b1 + acc[ai][bj][m][1] * alpha;
;                     if (H) { float* hp = H + row * 1024 + col0 + bj * HALF; *(f32x4*)hp = v0; *(f32x4*)(hp + 4) = v1; }
;                     if (XN) { u32x4 w; w.x = cvt_pk_bf16(v0[0], v0[1]); w.y = cvt_pk_bf16(v0[2], v0[3]); w.z = cvt_pk_bf16(v1[0], v1[1]); w.w = cvt_pk_bf16(v1[2], v1[3]);
;                         *(u32x4*)(XN + row * 1024 + col0 + bj * HALF) = w; }
;                     ss += (v0[0] * v0[0] + v0[1] * v0[1]) + (v0[2] * v0[2] + v0[3] * v0[3]) + (v1[0] * v1[0] + v1[1] * v1[1]) + (v1[2] * v1[2] + v1[3] * v1[3]);
;                     asm volatile("" ::: "memory");
.LBB0_1173:
	s_ashr_i32 s23, s22, 31
	v_mov_b32_e32 v160, v146
	s_lshl_b64 s[22:23], s[22:23], 8
	v_lshl_or_b32 v144, s45, 8, v148
	v_ashrrev_i32_e32 v161, 31, v160
	v_lshl_add_u64 v[160:161], s[22:23], 0, v[160:161]
	v_ashrrev_i32_e32 v145, 31, v144
	v_lshlrev_b64 v[160:161], 11, v[160:161]
	v_lshl_add_u64 v[160:161], s[14:15], 0, v[160:161]
	v_lshlrev_b64 v[144:145], 1, v[144:145]
	v_lshl_add_u64 v[164:165], v[160:161], 0, v[144:145]
	global_load_dwordx4 v[202:205], v[164:165], off
	global_load_dwordx4 v[206:209], v[164:165], off offset:256
	v_mov_b32_e32 v170, v149
	v_ashrrev_i32_e32 v171, 31, v170
	v_lshl_add_u64 v[172:173], s[22:23], 0, v[170:171]
	v_lshlrev_b64 v[172:173], 11, v[172:173]
	v_lshl_add_u64 v[172:173], s[14:15], 0, v[172:173]
	v_lshl_add_u64 v[174:175], v[172:173], 0, v[144:145]
	global_load_dwordx4 v[210:213], v[174:175], off
	v_mov_b32_e32 v170, v149
	v_ashrrev_i32_e32 v171, 31, v170
	v_lshl_add_u64 v[172:173], s[22:23], 0, v[170:171]
	v_lshlrev_b64 v[172:173], 11, v[172:173]
	v_lshl_add_u64 v[172:173], s[14:15], 0, v[172:173]
	v_lshl_add_u64 v[174:175], v[172:173], 0, v[144:145]
	global_load_dwordx4 v[214:217], v[174:175], off offset:256
	v_mov_b32_e32 v170, v150
	v_ashrrev_i32_e32 v171, 31, v170
	v_lshl_add_u64 v[172:173], s[22:23], 0, v[170:171]
	v_lshlrev_b64 v[172:173], 11, v[172:173]
	v_lshl_add_u64 v[172:173], s[14:15], 0, v[172:173]
	v_lshl_add_u64 v[174:175], v[172:173], 0, v[144:145]
	global_load_dwordx4 v[218:221], v[174:175], off
	v_mov_b32_e32 v170, v150
	v_ashrrev_i32_e32 v171, 31, v170
	v_lshl_add_u64 v[172:173], s[22:23], 0, v[170:171]
	v_lshlrev_b64 v[172:173], 11, v[172:173]
	v_lshl_add_u64 v[172:173], s[14:15], 0, v[172:173]
	v_lshl_add_u64 v[174:175], v[172:173], 0, v[144:145]
	global_load_dwordx4 v[222:225], v[174:175], off offset:256
	v_mov_b32_e32 v170, v151
	v_ashrrev_i32_e32 v171, 31, v170
	v_lshl_add_u64 v[172:173], s[22:23], 0, v[170:171]
	v_lshlrev_b64 v[172:173], 11, v[172:173]
	v_lshl_add_u64 v[172:173], s[14:15], 0, v[172:173]
	v_lshl_add_u64 v[174:175], v[172:173], 0, v[144:145]
	global_load_dwordx4 v[226:229], v[174:175], off
	v_mov_b32_e32 v170, v151
	v_ashrrev_i32_e32 v171, 31, v170
	v_lshl_add_u64 v[172:173], s[22:23], 0, v[170:171]
	v_lshlrev_b64 v[172:173], 11, v[172:173]
	v_lshl_add_u64 v[172:173], s[14:15], 0, v[172:173]
	v_lshl_add_u64 v[174:175], v[172:173], 0, v[144:145]
	global_load_dwordx4 v[230:233], v[174:175], off offset:256
	s_and_b64 vcc, exec, s[6:7]
	s_mov_b64 s[6:7], -1
	s_waitcnt vmcnt(7)
	v_lshlrev_b32_e32 v166, 16, v202
	v_and_b32_e32 v167, 0xffff0000, v202
	v_lshlrev_b32_e32 v160, 16, v203
	v_and_b32_e32 v161, 0xffff0000, v203
	v_lshlrev_b32_e32 v168, 16, v204
	v_and_b32_e32 v169, 0xffff0000, v204
	v_lshlrev_b32_e32 v162, 16, v205
	v_and_b32_e32 v163, 0xffff0000, v205
	v_mov_b32_e32 v170, v152
	v_ashrrev_i32_e32 v171, 31, v170
	v_lshl_add_u64 v[172:173], s[22:23], 0, v[170:171]
	v_lshlrev_b64 v[172:173], 11, v[172:173]
	v_lshl_add_u64 v[172:173], s[14:15], 0, v[172:173]
	v_lshl_add_u64 v[174:175], v[172:173], 0, v[144:145]
	global_load_dwordx4 v[202:205], v[174:175], off
	v_pk_fma_f32 v[126:127], v[126:127], 0.5, v[160:161] op_sel_hi:[1,0,1]
	v_pk_fma_f32 v[124:125], v[124:125], 0.5, v[166:167] op_sel_hi:[1,0,1]
	v_pk_fma_f32 v[160:161], v[122:123], 0.5, v[162:163] op_sel_hi:[1,0,1]
	v_pk_fma_f32 v[122:123], v[120:121], 0.5, v[168:169] op_sel_hi:[1,0,1]
	v_cvt_pk_bf16_f32 v120, v124, v125
	v_cvt_pk_bf16_f32 v121, v126, v127
	v_cvt_pk_bf16_f32 v122, v122, v123
	v_cvt_pk_bf16_f32 v123, v160, v161
	global_store_dwordx4 v[164:165], v[120:123], off
	v_mov_b32_e32 v124, v149
	s_waitcnt vmcnt(8)
	v_lshlrev_b32_e32 v126, 16, v206
	v_and_b32_e32 v127, 0xffff0000, v206
	v_lshlrev_b32_e32 v120, 16, v207
	v_and_b32_e32 v121, 0xffff0000, v207
	v_lshlrev_b32_e32 v160, 16, v208
	v_and_b32_e32 v161, 0xffff0000, v208
	v_lshlrev_b32_e32 v122, 16, v209
	v_and_b32_e32 v123, 0xffff0000, v209
	v_mov_b32_e32 v170, v152
	v_ashrrev_i32_e32 v171, 31, v170
	v_lshl_add_u64 v[172:173], s[22:23], 0, v[170:171]
	v_lshlrev_b64 v[172:173], 11, v[172:173]
	v_lshl_add_u64 v[172:173], s[14:15], 0, v[172:173]
	v_lshl_add_u64 v[174:175], v[172:173], 0, v[144:145]
	global_load_dwordx4 v[206:209], v[174:175], off offset:256
	v_pk_fma_f32 v[118:119], v[118:119], 0.5, v[120:121] op_sel_hi:[1,0,1]
	v_pk_fma_f32 v[116:117], v[116:117], 0.5, v[126:127] op_sel_hi:[1,0,1]
	v_pk_fma_f32 v[120:121], v[114:115], 0.5, v[122:123] op_sel_hi:[1,0,1]
	v_pk_fma_f32 v[114:115], v[112:113], 0.5, v[160:161] op_sel_hi:[1,0,1]
	v_cvt_pk_bf16_f32 v112, v116, v117
	v_cvt_pk_bf16_f32 v113, v118, v119
	v_cvt_pk_bf16_f32 v114, v114, v115
	v_cvt_pk_bf16_f32 v115, v120, v121
	global_store_dwordx4 v[164:165], v[112:115], off offset:256
	s_nop 0
	v_ashrrev_i32_e32 v125, 31, v124
	v_lshl_add_u64 v[112:113], s[22:23], 0, v[124:125]
	v_lshlrev_b64 v[112:113], 11, v[112:113]
	v_lshl_add_u64 v[112:113], s[14:15], 0, v[112:113]
	v_lshl_add_u64 v[116:117], v[112:113], 0, v[144:145]
	s_waitcnt vmcnt(9)
	v_lshlrev_b32_e32 v118, 16, v210
	v_and_b32_e32 v119, 0xffff0000, v210
	v_lshlrev_b32_e32 v112, 16, v211
	v_and_b32_e32 v113, 0xffff0000, v211
	v_lshlrev_b32_e32 v120, 16, v212
	v_and_b32_e32 v121, 0xffff0000, v212
	v_lshlrev_b32_e32 v114, 16, v213
	v_and_b32_e32 v115, 0xffff0000, v213
	v_mov_b32_e32 v170, v153
	v_ashrrev_i32_e32 v171, 31, v170
	v_lshl_add_u64 v[172:173], s[22:23], 0, v[170:171]
	v_lshlrev_b64 v[172:173], 11, v[172:173]
	v_lshl_add_u64 v[172:173], s[14:15], 0, v[172:173]
	v_lshl_add_u64 v[174:175], v[172:173], 0, v[144:145]
	global_load_dwordx4 v[210:213], v[174:175], off
	v_pk_fma_f32 v[110:111], v[110:111], 0.5, v[112:113] op_sel_hi:[1,0,1]
	v_pk_fma_f32 v[108:109], v[108:109], 0.5, v[118:119] op_sel_hi:[1,0,1]
	v_pk_fma_f32 v[112:113], v[106:107], 0.5, v[114:115] op_sel_hi:[1,0,1]
	v_pk_fma_f32 v[106:107], v[104:105], 0.5, v[120:121] op_sel_hi:[1,0,1]
	v_cvt_pk_bf16_f32 v104, v108, v109
	v_cvt_pk_bf16_f32 v105, v110, v111
	v_cvt_pk_bf16_f32 v106, v106, v107
	v_cvt_pk_bf16_f32 v107, v112, v113
	global_store_dwordx4 v[116:117], v[104:107], off
	v_mov_b32_e32 v108, v150
	s_waitcnt vmcnt(10)
; __device__ __forceinline__ unsigned cvt_pk_bf16(float lo, float hi) { f32x2_cv v = {lo, hi}; bf16x2_cv b = __builtin_convertvector(v, bf16x2_cv); return __builtin_bit_cast(unsigned, b); }
; __device__ __forceinline__ float bf_lo(unsigned w) { return __uint_as_float(w << 16); }
; __device__ __forceinline__ float bf_hi(unsigned w) { return __uint_as_float(w & 0xffff0000u); }
;     __device__ __forceinline__ void operator()(const f32x4 (&acc)[2][2][4][2], const Unit& u, int wr, int wc, int fr, int fq) const {
;     ...
;                 int lrow = lrow0 + ai * HALF + m * 16; asm volatile("" : "+v"(lrow)); const size_t row = (size_t)u.pm * BM + lrow;
;                 float ss = 0.f;
; #pragma unroll
;                 for (int bj = 0; bj < 2; ++bj) {
;                     f32x4 b0, b1;
;                     if (baseb) { const u32x4 bw = *(const u32x4*)(baseb + row * 1024 + col0 + bj * HALF);
;                         b0 = (f32x4){bf_lo(bw.x), bf_hi(bw.x), bf_lo(bw.y), bf_hi(bw.y)}; b1 = (f32x4){bf_lo(bw.z), bf_hi(bw.z), bf_lo(bw.w), bf_hi(bw.w)}; }
;                     else { const float* bp = base + (size_t)lrow * 1024 + col0 + bj * HALF; b0 = *(const f32x4*)bp; b1 = *(const f32x4*)(bp + 4); }
;                     const f32x4 v0 = b0 + acc[ai][bj][m][0] * alpha, v1 = b1 + acc[ai][bj][m][1] * alpha;
;                     if (H) { float* hp = H + row * 1024 + col0 + bj * HALF; *(f32x4*)hp = v0; *(f32x4*)(hp + 4) = v1; }
;                     if (XN) { u32x4 w; w.x = cvt_pk_bf16(v0[0], v0[1]); w.y = cvt_pk_bf16(v0[2], v0[3]); w.z = cvt_pk_bf16(v1[0], v1[1]); w.w = cvt_pk_bf16(v1[2], v1[3]);
;                         *(u32x4*)(XN + row * 1024 + col0 + bj * HALF) = w; }
;                     ss += (v0[0] * v0[0] + v0[1] * v0[1]) + (v0[2] * v0[2] + v0[3] * v0[3]) + (v1[0] * v1[0] + v1[1] * v1[1]) + (v1[2] * v1[2] + v1[3] * v1[3]);
;                     asm volatile("" ::: "memory");
	v_lshlrev_b32_e32 v110, 16, v214
	v_and_b32_e32 v111, 0xffff0000, v214
	v_lshlrev_b32_e32 v104, 16, v215
	v_and_b32_e32 v105, 0xffff0000, v215
	v_lshlrev_b32_e32 v112, 16, v216
	v_and_b32_e32 v113, 0xffff0000, v216
	v_lshlrev_b32_e32 v106, 16, v217
	v_and_b32_e32 v107, 0xffff0000, v217
	v_mov_b32_e32 v170, v153
	v_ashrrev_i32_e32 v171, 31, v170
	v_lshl_add_u64 v[172:173], s[22:23], 0, v[170:171]
	v_lshlrev_b64 v[172:173], 11, v[172:173]
	v_lshl_add_u64 v[172:173], s[14:15], 0, v[172:173]
	v_lshl_add_u64 v[174:175], v[172:173], 0, v[144:145]
	global_load_dwordx4 v[214:217], v[174:175], off offset:256
	v_pk_fma_f32 v[102:103], v[102:103], 0.5, v[104:105] op_sel_hi:[1,0,1]
	v_pk_fma_f32 v[100:101], v[100:101], 0.5, v[110:111] op_sel_hi:[1,0,1]
	v_pk_fma_f32 v[104:105], v[98:99], 0.5, v[106:107] op_sel_hi:[1,0,1]
	v_pk_fma_f32 v[98:99], v[96:97], 0.5, v[112:113] op_sel_hi:[1,0,1]
	v_cvt_pk_bf16_f32 v96, v100, v101
	v_cvt_pk_bf16_f32 v97, v102, v103
	v_cvt_pk_bf16_f32 v98, v98, v99
	v_cvt_pk_bf16_f32 v99, v104, v105
	global_store_dwordx4 v[116:117], v[96:99], off offset:256
	s_nop 0
	v_ashrrev_i32_e32 v109, 31, v108
	v_lshl_add_u64 v[96:97], s[22:23], 0, v[108:109]
	v_lshlrev_b64 v[96:97], 11, v[96:97]
	v_lshl_add_u64 v[96:97], s[14:15], 0, v[96:97]
	v_lshl_add_u64 v[100:101], v[96:97], 0, v[144:145]
	s_waitcnt vmcnt(11)
	v_lshlrev_b32_e32 v102, 16, v218
	v_and_b32_e32 v103, 0xffff0000, v218
	v_lshlrev_b32_e32 v96, 16, v219
	v_and_b32_e32 v97, 0xffff0000, v219
	v_lshlrev_b32_e32 v104, 16, v220
	v_and_b32_e32 v105, 0xffff0000, v220
	v_lshlrev_b32_e32 v98, 16, v221
	v_and_b32_e32 v99, 0xffff0000, v221
	v_mov_b32_e32 v170, v154
	v_ashrrev_i32_e32 v171, 31, v170
	v_lshl_add_u64 v[172:173], s[22:23], 0, v[170:171]
	v_lshlrev_b64 v[172:173], 11, v[172:173]
	v_lshl_add_u64 v[172:173], s[14:15], 0, v[172:173]
	v_lshl_add_u64 v[174:175], v[172:173], 0, v[144:145]
	global_load_dwordx4 v[218:221], v[174:175], off
	v_pk_fma_f32 v[94:95], v[94:95], 0.5, v[96:97] op_sel_hi:[1,0,1]
	v_pk_fma_f32 v[92:93], v[92:93], 0.5, v[102:103] op_sel_hi:[1,0,1]
	v_pk_fma_f32 v[96:97], v[90:91], 0.5, v[98:99] op_sel_hi:[1,0,1]
	v_pk_fma_f32 v[90:91], v[88:89], 0.5, v[104:105] op_sel_hi:[1,0,1]
	v_cvt_pk_bf16_f32 v88, v92, v93
	v_cvt_pk_bf16_f32 v89, v94, v95
	v_cvt_pk_bf16_f32 v90, v90, v91
	v_cvt_pk_bf16_f32 v91, v96, v97
	global_store_dwordx4 v[100:101], v[88:91], off
	v_mov_b32_e32 v92, v151
	s_waitcnt vmcnt(12)
	v_lshlrev_b32_e32 v94, 16, v222
	v_and_b32_e32 v95, 0xffff0000, v222
	v_lshlrev_b32_e32 v88, 16, v223
	v_and_b32_e32 v89, 0xffff0000, v223
	v_lshlrev_b32_e32 v96, 16, v224
	v_and_b32_e32 v97, 0xffff0000, v224
	v_lshlrev_b32_e32 v90, 16, v225
	v_and_b32_e32 v91, 0xffff0000, v225
	v_mov_b32_e32 v170, v154
	v_ashrrev_i32_e32 v171, 31, v170
	v_lshl_add_u64 v[172:173], s[22:23], 0, v[170:171]
	v_lshlrev_b64 v[172:173], 11, v[172:173]
	v_lshl_add_u64 v[172:173], s[14:15], 0, v[172:173]
	v_lshl_add_u64 v[174:175], v[172:173], 0, v[144:145]
	global_load_dwordx4 v[222:225], v[174:175], off offset:256
	v_pk_fma_f32 v[86:87], v[86:87], 0.5, v[88:89] op_sel_hi:[1,0,1]
	v_pk_fma_f32 v[84:85], v[84:85], 0.5, v[94:95] op_sel_hi:[1,0,1]
	v_pk_fma_f32 v[88:89], v[82:83], 0.5, v[90:91] op_sel_hi:[1,0,1]
	v_pk_fma_f32 v[82:83], v[80:81], 0.5, v[96:97] op_sel_hi:[1,0,1]
	v_cvt_pk_bf16_f32 v80, v84, v85
	v_cvt_pk_bf16_f32 v81, v86, v87
	v_cvt_pk_bf16_f32 v82, v82, v83
	v_cvt_pk_bf16_f32 v83, v88, v89
	global_store_dwordx4 v[100:101], v[80:83], off offset:256
	s_nop 0
	v_ashrrev_i32_e32 v93, 31, v92
	v_lshl_add_u64 v[80:81], s[22:23], 0, v[92:93]
	v_lshlrev_b64 v[80:81], 11, v[80:81]
	v_lshl_add_u64 v[80:81], s[14:15], 0, v[80:81]
	v_lshl_add_u64 v[84:85], v[80:81], 0, v[144:145]
	s_waitcnt vmcnt(13)
	v_lshlrev_b32_e32 v86, 16, v226
	v_and_b32_e32 v87, 0xffff0000, v226
	v_lshlrev_b32_e32 v80, 16, v227
	v_and_b32_e32 v81, 0xffff0000, v227
	v_lshlrev_b32_e32 v88, 16, v228
	v_and_b32_e32 v89, 0xffff0000, v228
	v_lshlrev_b32_e32 v82, 16, v229
	v_and_b32_e32 v83, 0xffff0000, v229
	v_mov_b32_e32 v170, v155
	v_ashrrev_i32_e32 v171, 31, v170
	v_lshl_add_u64 v[172:173], s[22:23], 0, v[170:171]
	v_lshlrev_b64 v[172:173], 11, v[172:173]
	v_lshl_add_u64 v[172:173], s[14:15], 0, v[172:173]
	v_lshl_add_u64 v[174:175], v[172:173], 0, v[144:145]
	global_load_dwordx4 v[226:229], v[174:175], off
	v_pk_fma_f32 v[78:79], v[78:79], 0.5, v[80:81] op_sel_hi:[1,0,1]
	v_pk_fma_f32 v[76:77], v[76:77], 0.5, v[86:87] op_sel_hi:[1,0,1]
	v_pk_fma_f32 v[80:81], v[74:75], 0.5, v[82:83] op_sel_hi:[1,0,1]
	v_pk_fma_f32 v[74:75], v[72:73], 0.5, v[88:89] op_sel_hi:[1,0,1]
	v_cvt_pk_bf16_f32 v72, v76, v77
	v_cvt_pk_bf16_f32 v73, v78, v79
	v_cvt_pk_bf16_f32 v74, v74, v75
	v_cvt_pk_bf16_f32 v75, v80, v81
	global_store_dwordx4 v[84:85], v[72:75], off
	v_mov_b32_e32 v76, v152
	s_waitcnt vmcnt(14)
	v_lshlrev_b32_e32 v78, 16, v230
	v_and_b32_e32 v79, 0xffff0000, v230
	v_lshlrev_b32_e32 v72, 16, v231
	v_and_b32_e32 v73, 0xffff0000, v231
	v_lshlrev_b32_e32 v80, 16, v232
	v_and_b32_e32 v81, 0xffff0000, v232
	v_lshlrev_b32_e32 v74, 16, v233
	v_and_b32_e32 v75, 0xffff0000, v233
	v_mov_b32_e32 v170, v155
	v_ashrrev_i32_e32 v171, 31, v170
	v_lshl_add_u64 v[172:173], s[22:23], 0, v[170:171]
	v_lshlrev_b64 v[172:173], 11, v[172:173]
	v_lshl_add_u64 v[172:173], s[14:15], 0, v[172:173]
	v_lshl_add_u64 v[174:175], v[172:173], 0, v[144:145]
	global_load_dwordx4 v[230:233], v[174:175], off offset:256
	v_pk_fma_f32 v[70:71], v[70:71], 0.5, v[72:73] op_sel_hi:[1,0,1]
	v_pk_fma_f32 v[68:69], v[68:69], 0.5, v[78:79] op_sel_hi:[1,0,1]
	v_pk_fma_f32 v[72:73], v[66:67], 0.5, v[74:75] op_sel_hi:[1,0,1]
	v_pk_fma_f32 v[66:67], v[64:65], 0.5, v[80:81] op_sel_hi:[1,0,1]
	v_cvt_pk_bf16_f32 v64, v68, v69
	v_cvt_pk_bf16_f32 v65, v70, v71
	v_cvt_pk_bf16_f32 v66, v66, v67
	v_cvt_pk_bf16_f32 v67, v72, v73
	global_store_dwordx4 v[84:85], v[64:67], off offset:256
	s_nop 0
	v_ashrrev_i32_e32 v77, 31, v76
	v_lshl_add_u64 v[64:65], s[22:23], 0, v[76:77]
	v_lshlrev_b64 v[64:65], 11, v[64:65]
	v_lshl_add_u64 v[64:65], s[14:15], 0, v[64:65]
	v_lshl_add_u64 v[68:69], v[64:65], 0, v[144:145]
	s_waitcnt vmcnt(15)
; __device__ __forceinline__ unsigned cvt_pk_bf16(float lo, float hi) { f32x2_cv v = {lo, hi}; bf16x2_cv b = __builtin_convertvector(v, bf16x2_cv); return __builtin_bit_cast(unsigned, b); }
; __device__ __forceinline__ float bf_lo(unsigned w) { return __uint_as_float(w << 16); }
; __device__ __forceinline__ float bf_hi(unsigned w) { return __uint_as_float(w & 0xffff0000u); }
;     __device__ __forceinline__ void operator()(const f32x4 (&acc)[2][2][4][2], const Unit& u, int wr, int wc, int fr, int fq) const {
;     ...
;                 int lrow = lrow0 + ai * HALF + m * 16; asm volatile("" : "+v"(lrow)); const size_t row = (size_t)u.pm * BM + lrow;
;                 float ss = 0.f;
; #pragma unroll
;                 for (int bj = 0; bj < 2; ++bj) {
;                     f32x4 b0, b1;
;                     if (baseb) { const u32x4 bw = *(const u32x4*)(baseb + row * 1024 + col0 + bj * HALF);
;                         b0 = (f32x4){bf_lo(bw.x), bf_hi(bw.x), bf_lo(bw.y), bf_hi(bw.y)}; b1 = (f32x4){bf_lo(bw.z), bf_hi(bw.z), bf_lo(bw.w), bf_hi(bw.w)}; }
;                     else { const float* bp = base + (size_t)lrow * 1024 + col0 + bj * HALF; b0 = *(const f32x4*)bp; b1 = *(const f32x4*)(bp + 4); }
;                     const f32x4 v0 = b0 + acc[ai][bj][m][0] * alpha, v1 = b1 + acc[ai][bj][m][1] * alpha;
;                     if (H) { float* hp = H + row * 1024 + col0 + bj * HALF; *(f32x4*)hp = v0; *(f32x4*)(hp + 4) = v1; }
;                     if (XN) { u32x4 w; w.x = cvt_pk_bf16(v0[0], v0[1]); w.y = cvt_pk_bf16(v0[2], v0[3]); w.z = cvt_pk_bf16(v1[0], v1[1]); w.w = cvt_pk_bf16(v1[2], v1[3]);
;                         *(u32x4*)(XN + row * 1024 + col0 + bj * HALF) = w; }
;                     ss += (v0[0] * v0[0] + v0[1] * v0[1]) + (v0[2] * v0[2] + v0[3] * v0[3]) + (v1[0] * v1[0] + v1[1] * v1[1]) + (v1[2] * v1[2] + v1[3] * v1[3]);
;                     asm volatile("" ::: "memory");
	v_lshlrev_b32_e32 v70, 16, v202
	v_and_b32_e32 v71, 0xffff0000, v202
	v_lshlrev_b32_e32 v64, 16, v203
	v_and_b32_e32 v65, 0xffff0000, v203
	v_lshlrev_b32_e32 v72, 16, v204
	v_and_b32_e32 v73, 0xffff0000, v204
	v_lshlrev_b32_e32 v66, 16, v205
	v_and_b32_e32 v67, 0xffff0000, v205
	v_pk_fma_f32 v[62:63], v[62:63], 0.5, v[64:65] op_sel_hi:[1,0,1]
	v_pk_fma_f32 v[60:61], v[60:61], 0.5, v[70:71] op_sel_hi:[1,0,1]
	v_pk_fma_f32 v[64:65], v[58:59], 0.5, v[66:67] op_sel_hi:[1,0,1]
	v_pk_fma_f32 v[58:59], v[56:57], 0.5, v[72:73] op_sel_hi:[1,0,1]
	v_cvt_pk_bf16_f32 v56, v60, v61
	v_cvt_pk_bf16_f32 v57, v62, v63
	v_cvt_pk_bf16_f32 v58, v58, v59
	v_cvt_pk_bf16_f32 v59, v64, v65
	global_store_dwordx4 v[68:69], v[56:59], off
	v_mov_b32_e32 v60, v153
	s_waitcnt vmcnt(14)
	v_lshlrev_b32_e32 v62, 16, v206
	v_and_b32_e32 v63, 0xffff0000, v206
	v_lshlrev_b32_e32 v56, 16, v207
	v_and_b32_e32 v57, 0xffff0000, v207
	v_lshlrev_b32_e32 v64, 16, v208
	v_and_b32_e32 v65, 0xffff0000, v208
	v_lshlrev_b32_e32 v58, 16, v209
	v_and_b32_e32 v59, 0xffff0000, v209
	v_pk_fma_f32 v[54:55], v[54:55], 0.5, v[56:57] op_sel_hi:[1,0,1]
	v_pk_fma_f32 v[52:53], v[52:53], 0.5, v[62:63] op_sel_hi:[1,0,1]
	v_pk_fma_f32 v[56:57], v[50:51], 0.5, v[58:59] op_sel_hi:[1,0,1]
	v_pk_fma_f32 v[50:51], v[48:49], 0.5, v[64:65] op_sel_hi:[1,0,1]
	v_cvt_pk_bf16_f32 v48, v52, v53
	v_cvt_pk_bf16_f32 v49, v54, v55
	v_cvt_pk_bf16_f32 v50, v50, v51
	v_cvt_pk_bf16_f32 v51, v56, v57
	global_store_dwordx4 v[68:69], v[48:51], off offset:256
	s_nop 0
	v_ashrrev_i32_e32 v61, 31, v60
	v_lshl_add_u64 v[48:49], s[22:23], 0, v[60:61]
	v_lshlrev_b64 v[48:49], 11, v[48:49]
	v_lshl_add_u64 v[48:49], s[14:15], 0, v[48:49]
	v_lshl_add_u64 v[52:53], v[48:49], 0, v[144:145]
	s_waitcnt vmcnt(13)
	v_lshlrev_b32_e32 v54, 16, v210
	v_and_b32_e32 v55, 0xffff0000, v210
	v_lshlrev_b32_e32 v48, 16, v211
	v_and_b32_e32 v49, 0xffff0000, v211
	v_lshlrev_b32_e32 v56, 16, v212
	v_and_b32_e32 v57, 0xffff0000, v212
	v_lshlrev_b32_e32 v50, 16, v213
	v_and_b32_e32 v51, 0xffff0000, v213
	v_pk_fma_f32 v[46:47], v[46:47], 0.5, v[48:49] op_sel_hi:[1,0,1]
	v_pk_fma_f32 v[44:45], v[44:45], 0.5, v[54:55] op_sel_hi:[1,0,1]
	v_pk_fma_f32 v[48:49], v[42:43], 0.5, v[50:51] op_sel_hi:[1,0,1]
	v_pk_fma_f32 v[42:43], v[40:41], 0.5, v[56:57] op_sel_hi:[1,0,1]
	v_cvt_pk_bf16_f32 v40, v44, v45
	v_cvt_pk_bf16_f32 v41, v46, v47
	v_cvt_pk_bf16_f32 v42, v42, v43
	v_cvt_pk_bf16_f32 v43, v48, v49
	global_store_dwordx4 v[52:53], v[40:43], off
	v_mov_b32_e32 v44, v154
	s_waitcnt vmcnt(12)
	v_lshlrev_b32_e32 v46, 16, v214
	v_and_b32_e32 v47, 0xffff0000, v214
	v_lshlrev_b32_e32 v40, 16, v215
	v_and_b32_e32 v41, 0xffff0000, v215
	v_lshlrev_b32_e32 v48, 16, v216
	v_and_b32_e32 v49, 0xffff0000, v216
	v_lshlrev_b32_e32 v42, 16, v217
	v_and_b32_e32 v43, 0xffff0000, v217
	v_pk_fma_f32 v[38:39], v[38:39], 0.5, v[40:41] op_sel_hi:[1,0,1]
	v_pk_fma_f32 v[36:37], v[36:37], 0.5, v[46:47] op_sel_hi:[1,0,1]
	v_pk_fma_f32 v[40:41], v[34:35], 0.5, v[42:43] op_sel_hi:[1,0,1]
	v_pk_fma_f32 v[34:35], v[32:33], 0.5, v[48:49] op_sel_hi:[1,0,1]
	v_cvt_pk_bf16_f32 v32, v36, v37
	v_cvt_pk_bf16_f32 v33, v38, v39
	v_cvt_pk_bf16_f32 v34, v34, v35
	v_cvt_pk_bf16_f32 v35, v40, v41
	global_store_dwordx4 v[52:53], v[32:35], off offset:256
	s_nop 0
	v_ashrrev_i32_e32 v45, 31, v44
	v_lshl_add_u64 v[32:33], s[22:23], 0, v[44:45]
	v_lshlrev_b64 v[32:33], 11, v[32:33]
	v_lshl_add_u64 v[32:33], s[14:15], 0, v[32:33]
	v_lshl_add_u64 v[36:37], v[32:33], 0, v[144:145]
	s_waitcnt vmcnt(11)
	v_lshlrev_b32_e32 v38, 16, v218
	v_and_b32_e32 v39, 0xffff0000, v218
	v_lshlrev_b32_e32 v32, 16, v219
	v_and_b32_e32 v33, 0xffff0000, v219
	v_lshlrev_b32_e32 v40, 16, v220
	v_and_b32_e32 v41, 0xffff0000, v220
	v_lshlrev_b32_e32 v34, 16, v221
	v_and_b32_e32 v35, 0xffff0000, v221
	v_pk_fma_f32 v[30:31], v[30:31], 0.5, v[32:33] op_sel_hi:[1,0,1]
	v_pk_fma_f32 v[28:29], v[28:29], 0.5, v[38:39] op_sel_hi:[1,0,1]
	v_pk_fma_f32 v[32:33], v[26:27], 0.5, v[34:35] op_sel_hi:[1,0,1]
	v_pk_fma_f32 v[26:27], v[24:25], 0.5, v[40:41] op_sel_hi:[1,0,1]
	v_cvt_pk_bf16_f32 v24, v28, v29
	v_cvt_pk_bf16_f32 v25, v30, v31
	v_cvt_pk_bf16_f32 v26, v26, v27
	v_cvt_pk_bf16_f32 v27, v32, v33
	global_store_dwordx4 v[36:37], v[24:27], off
	v_mov_b32_e32 v28, v155
	s_waitcnt vmcnt(10)
	v_lshlrev_b32_e32 v30, 16, v222
	v_and_b32_e32 v31, 0xffff0000, v222
	v_lshlrev_b32_e32 v24, 16, v223
	v_and_b32_e32 v25, 0xffff0000, v223
	v_lshlrev_b32_e32 v32, 16, v224
	v_and_b32_e32 v33, 0xffff0000, v224
	v_lshlrev_b32_e32 v26, 16, v225
	v_and_b32_e32 v27, 0xffff0000, v225
	v_pk_fma_f32 v[22:23], v[22:23], 0.5, v[24:25] op_sel_hi:[1,0,1]
	v_pk_fma_f32 v[20:21], v[20:21], 0.5, v[30:31] op_sel_hi:[1,0,1]
	v_pk_fma_f32 v[24:25], v[18:19], 0.5, v[26:27] op_sel_hi:[1,0,1]
	v_pk_fma_f32 v[18:19], v[16:17], 0.5, v[32:33] op_sel_hi:[1,0,1]
	v_cvt_pk_bf16_f32 v16, v20, v21
	v_cvt_pk_bf16_f32 v17, v22, v23
	v_cvt_pk_bf16_f32 v18, v18, v19
	v_cvt_pk_bf16_f32 v19, v24, v25
	global_store_dwordx4 v[36:37], v[16:19], off offset:256
	s_nop 0
	v_ashrrev_i32_e32 v29, 31, v28
	v_lshl_add_u64 v[16:17], s[22:23], 0, v[28:29]
	v_lshlrev_b64 v[16:17], 11, v[16:17]
	v_lshl_add_u64 v[16:17], s[14:15], 0, v[16:17]
	v_lshl_add_u64 v[20:21], v[16:17], 0, v[144:145]
	s_waitcnt vmcnt(9)
	v_lshlrev_b32_e32 v22, 16, v226
	v_and_b32_e32 v23, 0xffff0000, v226
	v_lshlrev_b32_e32 v16, 16, v227
	v_and_b32_e32 v17, 0xffff0000, v227
	v_lshlrev_b32_e32 v24, 16, v228
	v_and_b32_e32 v25, 0xffff0000, v228
	v_lshlrev_b32_e32 v18, 16, v229
	v_and_b32_e32 v19, 0xffff0000, v229
	v_pk_fma_f32 v[14:15], v[14:15], 0.5, v[16:17] op_sel_hi:[1,0,1]
	v_pk_fma_f32 v[12:13], v[12:13], 0.5, v[22:23] op_sel_hi:[1,0,1]
	v_pk_fma_f32 v[16:17], v[10:11], 0.5, v[18:19] op_sel_hi:[1,0,1]
	v_pk_fma_f32 v[10:11], v[8:9], 0.5, v[24:25] op_sel_hi:[1,0,1]
	v_cvt_pk_bf16_f32 v8, v12, v13
	v_cvt_pk_bf16_f32 v9, v14, v15
	v_cvt_pk_bf16_f32 v10, v10, v11
	v_cvt_pk_bf16_f32 v11, v16, v17
	global_store_dwordx4 v[20:21], v[8:11], off
	s_waitcnt vmcnt(8)
	v_lshlrev_b32_e32 v12, 16, v230
	v_and_b32_e32 v13, 0xffff0000, v230
	v_lshlrev_b32_e32 v8, 16, v231
	v_and_b32_e32 v9, 0xffff0000, v231
	v_lshlrev_b32_e32 v14, 16, v232
	v_and_b32_e32 v15, 0xffff0000, v232
	v_lshlrev_b32_e32 v10, 16, v233
	v_and_b32_e32 v11, 0xffff0000, v233
	v_pk_fma_f32 v[6:7], v[6:7], 0.5, v[8:9] op_sel_hi:[1,0,1]
	v_pk_fma_f32 v[4:5], v[4:5], 0.5, v[12:13] op_sel_hi:[1,0,1]
	v_pk_fma_f32 v[8:9], v[2:3], 0.5, v[10:11] op_sel_hi:[1,0,1]
	v_pk_fma_f32 v[2:3], v[0:1], 0.5, v[14:15] op_sel_hi:[1,0,1]
	v_cvt_pk_bf16_f32 v0, v4, v5
	v_cvt_pk_bf16_f32 v1, v6, v7
	v_cvt_pk_bf16_f32 v2, v2, v3
	v_cvt_pk_bf16_f32 v3, v8, v9
	global_store_dwordx4 v[20:21], v[0:3], off offset:256
	s_cbranch_vccnz .LBB0_1158
	s_andn2_b64 vcc, exec, s[12:13]
	s_cbranch_vccnz .LBB0_1157
	s_barrier
	s_branch .LBB0_1157
